# K-loops 8-barrier form: four 32-MFMA bursts per K iteration (phase 2/6 reads hoisted into load segments 1/5, their DMA moved to segments 3/7, phases 4/8 folded), vmcnt(8)+lgkmcnt(0) at every close; ph
# speedup vs baseline: 1.0135x; 1.0135x over previous
.LBB0_120:
	s_mov_b32 s100, -1
	v_readlane_b32 s30, v254, 52
	v_readlane_b32 s40, v252, 4
	s_mul_i32 s25, s30, 0x8400
	v_readlane_b32 s44, v252, 8
	s_mul_hi_i32 s1, s30, 0x8400
	v_readlane_b32 s45, v252, 9
	s_add_u32 s68, s44, s25
	v_readlane_b32 s46, v252, 10
	s_addc_u32 s69, s45, s1
	s_mul_i32 s25, s30, 0x2c00
	v_readlane_b32 s47, v252, 11
	s_mul_hi_i32 s1, s30, 0x2c00
	s_add_u32 s70, s46, s25
	s_addc_u32 s71, s47, s1
	s_mul_i32 s25, s38, 0x1c00000
	v_readlane_b32 s20, v252, 32
	s_mul_hi_i32 s1, s38, 0x1c00000
	s_add_u32 s27, s20, s25
	v_readlane_b32 s20, v252, 33
	v_readlane_b32 s31, v254, 53
	s_addc_u32 s30, s20, s1
	s_mul_i32 s33, s38, 0xfea00000
	s_mul_hi_i32 s31, s38, 0xfea00000
	s_add_u32 s94, s27, s33
	s_addc_u32 s95, s30, s31
	s_add_u32 s25, s54, s25
	s_addc_u32 s1, s55, s1
	s_mul_i32 s30, s38, 0xffea0000
	s_mul_hi_i32 s27, s38, 0xffea0000
	s_add_u32 s25, s25, s30
	s_addc_u32 s1, s1, s27
	s_add_u32 s52, s25, 0x5600000
	s_addc_u32 s53, s1, 0
	s_add_u32 s50, s25, 0x5780000
	s_addc_u32 s51, s1, 0
	v_lshrrev_b32_e32 v15, 1, v14
	s_add_u32 s92, s25, 0x5900000
	v_and_b32_e32 v15, 24, v15
	s_addc_u32 s93, s1, 0
	v_and_b32_e32 v216, 15, v14
	s_lshl_b32 s1, s10, 6
	v_lshlrev_b32_e32 v16, 1, v15
	v_lshlrev_b32_e32 v14, 2, v14
	v_writelane_b32 v254, s1, 61
	v_lshl_or_b32 v16, v216, 6, v16
	s_lshl_b32 s1, s10, 13
	v_and_b32_e32 v14, 32, v14
	v_bitop3_b32 v17, v16, s1, v14 bitop3:0xde
	s_lshl_b32 s1, s11, 5
	s_and_b32 s1, s1, 0x60
	s_add_i32 m0, s75, 0x18000
	v_lshl_add_u64 v[6:7], v[6:7], 0, s[18:19]
	s_lshl_b32 s10, s1, 7
	s_waitcnt vmcnt(2)
	s_barrier
	global_load_lds_dwordx4 v[6:7], off
	v_lshl_add_u64 v[4:5], v[4:5], 0, s[18:19]
	s_add_i32 m0, s75, 0x1a000
	s_add_i32 s31, s75, 0x8000
	s_add_i32 s34, s75, 0xa000
	v_bitop3_b32 v217, v16, s10, v14 bitop3:0xde
	v_add_u32_e32 v217, 0x10000, v217
	global_load_lds_dwordx4 v[4:5], off
	v_lshl_add_u64 v[2:3], v[2:3], 0, s[18:19]
	s_mov_b32 m0, s31
	s_add_u32 s10, s82, 0x40080
	global_load_lds_dwordx4 v[2:3], off
	v_lshl_add_u64 v[0:1], v[0:1], 0, s[18:19]
	s_mov_b32 m0, s34
	s_addc_u32 s11, s83, 0
	global_load_lds_dwordx4 v[0:1], off
	s_add_i32 m0, s75, 0x1c000
	v_lshl_add_u64 v[0:1], s[10:11], 0, v[144:145]
	global_load_lds_dwordx4 v[0:1], off
	v_lshl_add_u64 v[0:1], s[10:11], 0, v[162:163]
	s_add_i32 m0, s75, 0x1e000
	s_ashr_i32 s30, s8, 31
	global_load_lds_dwordx4 v[0:1], off
	v_lshlrev_b32_e32 v0, 14, v8
	v_and_b32_e32 v0, 0xffff8000, v0
	v_lshl_add_u32 v0, v9, 11, v0
	v_and_b32_e32 v1, 1, v8
	v_lshl_or_b32 v0, v1, 6, v0
	v_lshl_add_u32 v164, v10, 1, v0
	v_lshlrev_b32_e32 v0, 14, v11
	s_add_u32 s60, s68, 0x2c00
	v_and_b32_e32 v0, 0xffff8000, v0
	s_waitcnt vmcnt(6)
	s_addc_u32 s61, s69, 0
	v_lshl_add_u32 v0, v12, 11, v0
	v_and_b32_e32 v1, 1, v11
	v_readlane_b32 s41, v252, 5
	v_readlane_b32 s42, v252, 6
	v_readlane_b32 s43, v252, 7
	s_add_u32 s64, s68, 0x5800
	v_lshl_or_b32 v0, v1, 6, v0
	v_readlane_b32 s48, v252, 38
	s_mov_b32 s35, 0
	v_cmp_eq_u32_e64 s[38:39], 0, v216
	v_cmp_lt_u32_e64 s[40:41], 1, v216
	v_cmp_gt_u32_e64 s[42:43], 2, v216
	v_cmp_lt_u32_e64 s[44:45], 13, v216
	v_add_u32_e32 v218, -14, v216
	s_addc_u32 s65, s69, 0
	v_or_b32_e32 v219, s1, v15
	v_mov_b32_e32 v165, v145
	v_lshl_add_u32 v166, v13, 1, v0
	v_mov_b32_e32 v167, v145
	v_add_u32_e32 v220, 0, v17
	v_readlane_b32 s49, v252, 39
	s_barrier
	v_readfirstlane_b32 s101, v208
	s_nop 3
	s_lshr_b32 s101, s101, 8
	s_cmp_eq_u32 s101, 0
	s_cbranch_scc1 .Lprio_d_done
	s_setprio 1

.LBB0_124:
	s_nop 0
	s_ashr_i32 s79, s78, 31
	s_lshl_b64 s[10:11], s[78:79], 19
	s_add_u32 s80, s54, s10
	v_cmp_lt_i64_e32 vcc, s[72:73], v[178:179]
	s_addc_u32 s81, s55, s11
	s_and_b64 s[10:11], vcc, exec
	s_cselect_b32 s1, s81, s87
	s_cselect_b32 s10, s80, s86
	s_ashr_i32 s77, s76, 31
	s_lshl_b64 s[36:37], s[76:77], 19
	s_add_u32 s72, s66, s36
	s_addc_u32 s73, s59, s37
	s_and_b64 s[36:37], vcc, exec
	s_cselect_b32 s11, s73, s83
	s_cselect_b32 s25, s72, s82
	s_add_u32 s86, s86, 0x40080
	s_addc_u32 s87, s87, 0
	s_add_u32 s33, s82, 0x100
	s_addc_u32 s36, s83, 0
	s_mov_b32 s37, -2
	s_add_u32 s27, s86, 0xfffc0080
	s_addc_u32 s56, s87, -1
	s_add_i32 s57, 0, 0x10000
	ds_read_b128 v[64:67], v217
	ds_read_b128 v[68:71], v217 offset:1024
	ds_read_b128 v[72:75], v217 offset:2048
	ds_read_b128 v[76:79], v217 offset:3072
	s_cmp_eq_u32 s37, 12
	s_cselect_b32 vcc_hi, s1, s56
	s_cselect_b32 vcc_lo, s10, s27
	s_cselect_b32 s83, s11, s36
	s_cselect_b32 s82, s25, s33
	s_add_i32 m0, s75, 0xc000
	ds_read_b128 v[80:83], v220
	ds_read_b128 v[84:87], v220 offset:1024
	ds_read_b128 v[88:91], v220 offset:2048
	ds_read_b128 v[92:95], v220 offset:3072
	ds_read_b128 v[188:191], v220 offset:4096
	ds_read_b128 v[192:195], v220 offset:5120
	ds_read_b128 v[196:199], v220 offset:6144
	ds_read_b128 v[200:203], v220 offset:7168
	s_waitcnt lgkmcnt(8)
	ds_read_b128 v[204:207], v217 offset:16384
	ds_read_b128 v[222:225], v217 offset:17408
	ds_read_b128 v[228:231], v217 offset:18432
	ds_read_b128 v[232:235], v217 offset:19456
	global_load_lds_dwordx4 v164, s[86:87]
	s_add_i32 m0, s75, 0xe000
	s_nop 0
	global_load_lds_dwordx4 v166, s[86:87]
	s_waitcnt lgkmcnt(0)
	s_waitcnt vmcnt(8)
	s_barrier
	v_mfma_f32_16x16x32_bf16 v[146:149], v[64:67], v[80:83], 0
	v_mfma_f32_16x16x32_bf16 v[116:119], v[72:75], v[80:83], 0
	v_mfma_f32_16x16x32_bf16 v[158:161], v[64:67], v[88:91], 0
	v_mfma_f32_16x16x32_bf16 v[124:127], v[72:75], v[88:91], 0
	v_mfma_f32_16x16x32_bf16 v[154:157], v[64:67], v[188:191], 0
	v_mfma_f32_16x16x32_bf16 v[112:115], v[72:75], v[188:191], 0
	v_mfma_f32_16x16x32_bf16 v[150:153], v[64:67], v[196:199], 0
	v_mfma_f32_16x16x32_bf16 v[120:123], v[72:75], v[196:199], 0
	v_mfma_f32_16x16x32_bf16 v[146:149], v[68:71], v[84:87], v[146:149]
	v_mfma_f32_16x16x32_bf16 v[116:119], v[76:79], v[84:87], v[116:119]
	v_mfma_f32_16x16x32_bf16 v[158:161], v[68:71], v[92:95], v[158:161]
	v_mfma_f32_16x16x32_bf16 v[124:127], v[76:79], v[92:95], v[124:127]
	v_mfma_f32_16x16x32_bf16 v[154:157], v[68:71], v[192:195], v[154:157]
	v_mfma_f32_16x16x32_bf16 v[112:115], v[76:79], v[192:195], v[112:115]
	v_mfma_f32_16x16x32_bf16 v[150:153], v[68:71], v[200:203], v[150:153]
	v_mfma_f32_16x16x32_bf16 v[120:123], v[76:79], v[200:203], v[120:123]
	v_mfma_f32_16x16x32_bf16 v[140:143], v[204:207], v[80:83], 0
	v_mfma_f32_16x16x32_bf16 v[80:83], v[228:231], v[80:83], 0
	v_mfma_f32_16x16x32_bf16 v[140:143], v[222:225], v[84:87], v[140:143]
	v_mfma_f32_16x16x32_bf16 v[80:83], v[232:235], v[84:87], v[80:83]
	v_mfma_f32_16x16x32_bf16 v[84:87], v[204:207], v[88:91], 0
	v_mfma_f32_16x16x32_bf16 v[88:91], v[228:231], v[88:91], 0
	v_mfma_f32_16x16x32_bf16 v[100:103], v[228:231], v[188:191], 0
	v_mfma_f32_16x16x32_bf16 v[104:107], v[204:207], v[196:199], 0
	v_mfma_f32_16x16x32_bf16 v[96:99], v[228:231], v[196:199], 0
	v_mfma_f32_16x16x32_bf16 v[84:87], v[222:225], v[92:95], v[84:87]
	v_mfma_f32_16x16x32_bf16 v[88:91], v[232:235], v[92:95], v[88:91]
	v_mfma_f32_16x16x32_bf16 v[92:95], v[204:207], v[188:191], 0
	v_mfma_f32_16x16x32_bf16 v[100:103], v[232:235], v[192:195], v[100:103]
	v_mfma_f32_16x16x32_bf16 v[128:131], v[222:225], v[200:203], v[104:107]
	v_mfma_f32_16x16x32_bf16 v[96:99], v[232:235], v[200:203], v[96:99]
	v_mfma_f32_16x16x32_bf16 v[92:95], v[222:225], v[192:195], v[92:95]
	s_barrier
	s_add_i32 s27, 0, 0x14000
	s_add_i32 s56, s57, s74
	s_mov_b32 m0, s56
	s_nop 0
	global_load_lds_dwordx4 v144, s[82:83]
	s_add_i32 m0, s56, 0x2000
	s_nop 0
	global_load_lds_dwordx4 v162, s[82:83]
	s_mov_b32 m0, s75
	ds_read_b128 v[104:107], v220 offset:16384
	ds_read_b128 v[108:111], v220 offset:17408
	ds_read_b128 v[132:135], v220 offset:18432
	ds_read_b128 v[136:139], v220 offset:19456
	ds_read_b128 v[188:191], v220 offset:20480
	ds_read_b128 v[192:195], v220 offset:21504
	ds_read_b128 v[196:199], v220 offset:22528
	ds_read_b128 v[200:203], v220 offset:23552
	global_load_lds_dwordx4 v144, vcc
	s_mov_b32 m0, s85
	s_nop 0
	global_load_lds_dwordx4 v162, vcc
	s_add_u32 s56, s82, 0x40000
	s_addc_u32 s57, s83, 0
	s_add_i32 s27, s27, s74
	s_mov_b32 m0, s27
	s_nop 0
	global_load_lds_dwordx4 v144, s[56:57]
	s_add_i32 m0, s27, 0x2000
	s_nop 0
	global_load_lds_dwordx4 v162, s[56:57]
	s_waitcnt lgkmcnt(0)
	s_waitcnt vmcnt(8)
	s_barrier
	v_mfma_f32_16x16x32_bf16 v[48:51], v[64:67], v[104:107], 0
	v_mfma_f32_16x16x32_bf16 v[20:23], v[72:75], v[104:107], 0
	v_mfma_f32_16x16x32_bf16 v[60:63], v[64:67], v[132:135], 0
	v_mfma_f32_16x16x32_bf16 v[28:31], v[72:75], v[132:135], 0
	v_mfma_f32_16x16x32_bf16 v[56:59], v[64:67], v[188:191], 0
	v_mfma_f32_16x16x32_bf16 v[16:19], v[72:75], v[188:191], 0
	v_mfma_f32_16x16x32_bf16 v[52:55], v[64:67], v[196:199], 0
	v_mfma_f32_16x16x32_bf16 v[24:27], v[72:75], v[196:199], 0
	v_mfma_f32_16x16x32_bf16 v[48:51], v[68:71], v[108:111], v[48:51]
	v_mfma_f32_16x16x32_bf16 v[20:23], v[76:79], v[108:111], v[20:23]
	v_mfma_f32_16x16x32_bf16 v[60:63], v[68:71], v[136:139], v[60:63]
	v_mfma_f32_16x16x32_bf16 v[28:31], v[76:79], v[136:139], v[28:31]
	v_mfma_f32_16x16x32_bf16 v[56:59], v[68:71], v[192:195], v[56:59]
	v_mfma_f32_16x16x32_bf16 v[16:19], v[76:79], v[192:195], v[16:19]
	v_mfma_f32_16x16x32_bf16 v[52:55], v[68:71], v[200:203], v[52:55]
	v_mfma_f32_16x16x32_bf16 v[24:27], v[76:79], v[200:203], v[24:27]
	v_mfma_f32_16x16x32_bf16 v[44:47], v[204:207], v[104:107], 0
	v_mfma_f32_16x16x32_bf16 v[12:15], v[228:231], v[104:107], 0
	v_mfma_f32_16x16x32_bf16 v[40:43], v[204:207], v[132:135], 0
	v_mfma_f32_16x16x32_bf16 v[8:11], v[228:231], v[132:135], 0
	v_mfma_f32_16x16x32_bf16 v[36:39], v[204:207], v[188:191], 0
	v_mfma_f32_16x16x32_bf16 v[4:7], v[228:231], v[188:191], 0
	v_mfma_f32_16x16x32_bf16 v[32:35], v[204:207], v[196:199], 0
	v_mfma_f32_16x16x32_bf16 v[0:3], v[228:231], v[196:199], 0
	v_mfma_f32_16x16x32_bf16 v[44:47], v[222:225], v[108:111], v[44:47]
	v_mfma_f32_16x16x32_bf16 v[12:15], v[232:235], v[108:111], v[12:15]
	v_mfma_f32_16x16x32_bf16 v[40:43], v[222:225], v[136:139], v[40:43]
	v_mfma_f32_16x16x32_bf16 v[8:11], v[232:235], v[136:139], v[8:11]
	v_mfma_f32_16x16x32_bf16 v[36:39], v[222:225], v[192:195], v[36:39]
	v_mfma_f32_16x16x32_bf16 v[4:7], v[232:235], v[192:195], v[4:7]
	v_mfma_f32_16x16x32_bf16 v[32:35], v[222:225], v[200:203], v[32:35]
	v_mfma_f32_16x16x32_bf16 v[0:3], v[232:235], v[200:203], v[0:3]
	s_barrier
	s_add_i32 s27, 0, 0x18000
	ds_read_b128 v[64:67], v217 offset:32768
	ds_read_b128 v[68:71], v217 offset:33792
	ds_read_b128 v[72:75], v217 offset:34816
	ds_read_b128 v[76:79], v217 offset:35840
	s_add_u32 s56, vcc_lo, 0x40000
	s_addc_u32 s57, vcc_hi, 0
	s_mov_b32 m0, s98
	ds_read_b128 v[104:107], v220 offset:32768
	ds_read_b128 v[108:111], v220 offset:33792
	ds_read_b128 v[132:135], v220 offset:34816
	ds_read_b128 v[188:191], v220 offset:35840
	ds_read_b128 v[192:195], v220 offset:36864
	ds_read_b128 v[196:199], v220 offset:37888
	ds_read_b128 v[200:203], v220 offset:38912
	ds_read_b128 v[204:207], v220 offset:39936
	s_waitcnt lgkmcnt(8)
	ds_read_b128 v[222:225], v217 offset:49152
	ds_read_b128 v[228:231], v217 offset:50176
	ds_read_b128 v[232:235], v217 offset:51200
	ds_read_b128 v[236:239], v217 offset:52224
	global_load_lds_dwordx4 v144, s[56:57]
	s_mov_b32 m0, s29
	s_nop 0
	global_load_lds_dwordx4 v162, s[56:57]
	s_waitcnt lgkmcnt(0)
	s_waitcnt vmcnt(8)
	s_barrier
	v_mfma_f32_16x16x32_bf16 v[136:139], v[64:67], v[104:107], v[146:149]
	v_mfma_f32_16x16x32_bf16 v[146:149], v[68:71], v[108:111], v[136:139]
	v_mfma_f32_16x16x32_bf16 v[136:139], v[64:67], v[132:135], v[158:161]
	v_mfma_f32_16x16x32_bf16 v[158:161], v[68:71], v[188:191], v[136:139]
	v_mfma_f32_16x16x32_bf16 v[136:139], v[64:67], v[192:195], v[154:157]
	v_mfma_f32_16x16x32_bf16 v[116:119], v[72:75], v[104:107], v[116:119]
	v_mfma_f32_16x16x32_bf16 v[124:127], v[72:75], v[132:135], v[124:127]
	v_mfma_f32_16x16x32_bf16 v[154:157], v[68:71], v[196:199], v[136:139]
	v_mfma_f32_16x16x32_bf16 v[112:115], v[72:75], v[192:195], v[112:115]
	v_mfma_f32_16x16x32_bf16 v[136:139], v[64:67], v[200:203], v[150:153]
	v_mfma_f32_16x16x32_bf16 v[120:123], v[72:75], v[200:203], v[120:123]
	v_mfma_f32_16x16x32_bf16 v[116:119], v[76:79], v[108:111], v[116:119]
	v_mfma_f32_16x16x32_bf16 v[124:127], v[76:79], v[188:191], v[124:127]
	v_mfma_f32_16x16x32_bf16 v[112:115], v[76:79], v[196:199], v[112:115]
	v_mfma_f32_16x16x32_bf16 v[150:153], v[68:71], v[204:207], v[136:139]
	v_mfma_f32_16x16x32_bf16 v[120:123], v[76:79], v[204:207], v[120:123]
	v_mfma_f32_16x16x32_bf16 v[136:139], v[222:225], v[104:107], v[140:143]
	v_mfma_f32_16x16x32_bf16 v[80:83], v[232:235], v[104:107], v[80:83]
	v_mfma_f32_16x16x32_bf16 v[140:143], v[228:231], v[108:111], v[136:139]
	v_mfma_f32_16x16x32_bf16 v[108:111], v[236:239], v[108:111], v[80:83]
	v_mfma_f32_16x16x32_bf16 v[80:83], v[222:225], v[132:135], v[84:87]
	v_mfma_f32_16x16x32_bf16 v[136:139], v[228:231], v[188:191], v[80:83]
	v_mfma_f32_16x16x32_bf16 v[80:83], v[232:235], v[132:135], v[88:91]
	v_mfma_f32_16x16x32_bf16 v[104:107], v[236:239], v[188:191], v[80:83]
	v_mfma_f32_16x16x32_bf16 v[80:83], v[222:225], v[192:195], v[92:95]
	v_mfma_f32_16x16x32_bf16 v[132:135], v[228:231], v[196:199], v[80:83]
	v_mfma_f32_16x16x32_bf16 v[80:83], v[232:235], v[192:195], v[100:103]
	v_mfma_f32_16x16x32_bf16 v[100:103], v[236:239], v[196:199], v[80:83]
	v_mfma_f32_16x16x32_bf16 v[80:83], v[222:225], v[200:203], v[128:131]
	v_mfma_f32_16x16x32_bf16 v[128:131], v[228:231], v[204:207], v[80:83]
	v_mfma_f32_16x16x32_bf16 v[80:83], v[232:235], v[200:203], v[96:99]
	v_mfma_f32_16x16x32_bf16 v[96:99], v[236:239], v[204:207], v[80:83]
	s_barrier
	s_nop 0
	s_add_i32 s58, 0, 0x1c000
	s_add_i32 s27, s27, s74
	s_add_u32 s56, s82, s18
	s_addc_u32 s57, s83, s19
	s_mov_b32 m0, s27
	s_nop 0
	global_load_lds_dwordx4 v144, s[56:57]
	s_add_u32 s56, s82, s18
	s_addc_u32 s57, s83, s19
	s_add_i32 m0, s27, 0x2000
	s_nop 0
	global_load_lds_dwordx4 v162, s[56:57]
	s_nop 0
	s_mov_b32 m0, s31
	s_add_u32 s56, vcc_lo, s18
	s_addc_u32 s57, vcc_hi, s19
	s_nop 2
	ds_read_b128 v[80:83], v220 offset:49152
	ds_read_b128 v[84:87], v220 offset:50176
	ds_read_b128 v[88:91], v220 offset:51200
	ds_read_b128 v[92:95], v220 offset:52224
	ds_read_b128 v[188:191], v220 offset:53248
	ds_read_b128 v[192:195], v220 offset:54272
	ds_read_b128 v[196:199], v220 offset:55296
	ds_read_b128 v[200:203], v220 offset:56320
	global_load_lds_dwordx4 v144, s[56:57]
	s_add_u32 s56, vcc_lo, s18
	s_addc_u32 s57, vcc_hi, s19
	s_mov_b32 m0, s34
	s_nop 0
	global_load_lds_dwordx4 v162, s[56:57]
	s_add_u32 s56, s82, 0x40080
	s_addc_u32 s57, s83, 0
	s_add_i32 s27, s58, s74
	s_mov_b32 m0, s27
	s_nop 0
	global_load_lds_dwordx4 v144, s[56:57]
	s_add_i32 m0, s27, 0x2000
	s_nop 0
	global_load_lds_dwordx4 v162, s[56:57]
	s_waitcnt lgkmcnt(0)
	s_waitcnt vmcnt(8)
	s_barrier
	v_mfma_f32_16x16x32_bf16 v[48:51], v[64:67], v[80:83], v[48:51]
	v_mfma_f32_16x16x32_bf16 v[20:23], v[72:75], v[80:83], v[20:23]
	v_mfma_f32_16x16x32_bf16 v[60:63], v[64:67], v[88:91], v[60:63]
	v_mfma_f32_16x16x32_bf16 v[28:31], v[72:75], v[88:91], v[28:31]
	v_mfma_f32_16x16x32_bf16 v[56:59], v[64:67], v[188:191], v[56:59]
	v_mfma_f32_16x16x32_bf16 v[16:19], v[72:75], v[188:191], v[16:19]
	v_mfma_f32_16x16x32_bf16 v[52:55], v[64:67], v[196:199], v[52:55]
	v_mfma_f32_16x16x32_bf16 v[24:27], v[72:75], v[196:199], v[24:27]
	v_mfma_f32_16x16x32_bf16 v[48:51], v[68:71], v[84:87], v[48:51]
	v_mfma_f32_16x16x32_bf16 v[20:23], v[76:79], v[84:87], v[20:23]
	v_mfma_f32_16x16x32_bf16 v[60:63], v[68:71], v[92:95], v[60:63]
	v_mfma_f32_16x16x32_bf16 v[28:31], v[76:79], v[92:95], v[28:31]
	v_mfma_f32_16x16x32_bf16 v[56:59], v[68:71], v[192:195], v[56:59]
	v_mfma_f32_16x16x32_bf16 v[16:19], v[76:79], v[192:195], v[16:19]
	v_mfma_f32_16x16x32_bf16 v[52:55], v[68:71], v[200:203], v[52:55]
	v_mfma_f32_16x16x32_bf16 v[24:27], v[76:79], v[200:203], v[24:27]
	v_mfma_f32_16x16x32_bf16 v[44:47], v[222:225], v[80:83], v[44:47]
	v_mfma_f32_16x16x32_bf16 v[12:15], v[232:235], v[80:83], v[12:15]
	v_mfma_f32_16x16x32_bf16 v[40:43], v[222:225], v[88:91], v[40:43]
	v_mfma_f32_16x16x32_bf16 v[8:11], v[232:235], v[88:91], v[8:11]
	v_mfma_f32_16x16x32_bf16 v[36:39], v[222:225], v[188:191], v[36:39]
	v_mfma_f32_16x16x32_bf16 v[4:7], v[232:235], v[188:191], v[4:7]
	v_mfma_f32_16x16x32_bf16 v[32:35], v[222:225], v[196:199], v[32:35]
	v_mfma_f32_16x16x32_bf16 v[0:3], v[232:235], v[196:199], v[0:3]
	v_mfma_f32_16x16x32_bf16 v[44:47], v[228:231], v[84:87], v[44:47]
	v_mfma_f32_16x16x32_bf16 v[12:15], v[236:239], v[84:87], v[12:15]
	v_mfma_f32_16x16x32_bf16 v[40:43], v[228:231], v[92:95], v[40:43]
	v_mfma_f32_16x16x32_bf16 v[8:11], v[236:239], v[92:95], v[8:11]
	v_mfma_f32_16x16x32_bf16 v[36:39], v[228:231], v[192:195], v[36:39]
	v_mfma_f32_16x16x32_bf16 v[4:7], v[236:239], v[192:195], v[4:7]
	v_mfma_f32_16x16x32_bf16 v[32:35], v[228:231], v[200:203], v[32:35]
	v_mfma_f32_16x16x32_bf16 v[0:3], v[236:239], v[200:203], v[0:3]
	s_barrier
	s_add_i32 s37, s37, 2
	s_add_u32 s86, s86, 0x100
	s_addc_u32 s87, s87, 0
	s_add_u32 s33, s33, 0x100
	s_addc_u32 s36, s36, 0
	s_cmp_gt_u32 s37, 13
.LBB0_125:
	s_nop 0
	s_add_u32 s27, s86, 0xfffc0080
	s_addc_u32 s56, s87, -1
	s_add_i32 s57, 0, 0x10000
	ds_read_b128 v[64:67], v217
	ds_read_b128 v[68:71], v217 offset:1024
	ds_read_b128 v[72:75], v217 offset:2048
	ds_read_b128 v[76:79], v217 offset:3072
	s_cmp_eq_u32 s37, 12
	s_cselect_b32 vcc_hi, s1, s56
	s_cselect_b32 vcc_lo, s10, s27
	s_cselect_b32 s83, s11, s36
	s_cselect_b32 s82, s25, s33
	s_add_i32 m0, s75, 0xc000
	ds_read_b128 v[80:83], v220
	ds_read_b128 v[84:87], v220 offset:1024
	ds_read_b128 v[88:91], v220 offset:2048
	ds_read_b128 v[92:95], v220 offset:3072
	ds_read_b128 v[188:191], v220 offset:4096
	ds_read_b128 v[192:195], v220 offset:5120
	ds_read_b128 v[196:199], v220 offset:6144
	ds_read_b128 v[200:203], v220 offset:7168
	s_waitcnt lgkmcnt(8)
	ds_read_b128 v[204:207], v217 offset:16384
	ds_read_b128 v[222:225], v217 offset:17408
	ds_read_b128 v[228:231], v217 offset:18432
	ds_read_b128 v[232:235], v217 offset:19456
	global_load_lds_dwordx4 v164, s[86:87]
	s_add_i32 m0, s75, 0xe000
	s_nop 0
	global_load_lds_dwordx4 v166, s[86:87]
	s_waitcnt lgkmcnt(0)
	s_waitcnt vmcnt(8)
	s_barrier
	v_mfma_f32_16x16x32_bf16 v[146:149], v[64:67], v[80:83], v[146:149]
	v_mfma_f32_16x16x32_bf16 v[116:119], v[72:75], v[80:83], v[116:119]
	v_mfma_f32_16x16x32_bf16 v[158:161], v[64:67], v[88:91], v[158:161]
	v_mfma_f32_16x16x32_bf16 v[124:127], v[72:75], v[88:91], v[124:127]
	v_mfma_f32_16x16x32_bf16 v[154:157], v[64:67], v[188:191], v[154:157]
	v_mfma_f32_16x16x32_bf16 v[112:115], v[72:75], v[188:191], v[112:115]
	v_mfma_f32_16x16x32_bf16 v[150:153], v[64:67], v[196:199], v[150:153]
	v_mfma_f32_16x16x32_bf16 v[120:123], v[72:75], v[196:199], v[120:123]
	v_mfma_f32_16x16x32_bf16 v[146:149], v[68:71], v[84:87], v[146:149]
	v_mfma_f32_16x16x32_bf16 v[116:119], v[76:79], v[84:87], v[116:119]
	v_mfma_f32_16x16x32_bf16 v[158:161], v[68:71], v[92:95], v[158:161]
	v_mfma_f32_16x16x32_bf16 v[124:127], v[76:79], v[92:95], v[124:127]
	v_mfma_f32_16x16x32_bf16 v[154:157], v[68:71], v[192:195], v[154:157]
	v_mfma_f32_16x16x32_bf16 v[112:115], v[76:79], v[192:195], v[112:115]
	v_mfma_f32_16x16x32_bf16 v[150:153], v[68:71], v[200:203], v[150:153]
	v_mfma_f32_16x16x32_bf16 v[120:123], v[76:79], v[200:203], v[120:123]
	v_mfma_f32_16x16x32_bf16 v[140:143], v[204:207], v[80:83], v[140:143]
	v_mfma_f32_16x16x32_bf16 v[80:83], v[228:231], v[80:83], v[108:111]
	v_mfma_f32_16x16x32_bf16 v[140:143], v[222:225], v[84:87], v[140:143]
	v_mfma_f32_16x16x32_bf16 v[80:83], v[232:235], v[84:87], v[80:83]
	v_mfma_f32_16x16x32_bf16 v[84:87], v[204:207], v[88:91], v[136:139]
	v_mfma_f32_16x16x32_bf16 v[88:91], v[228:231], v[88:91], v[104:107]
	v_mfma_f32_16x16x32_bf16 v[100:103], v[228:231], v[188:191], v[100:103]
	v_mfma_f32_16x16x32_bf16 v[104:107], v[204:207], v[196:199], v[128:131]
	v_mfma_f32_16x16x32_bf16 v[96:99], v[228:231], v[196:199], v[96:99]
	v_mfma_f32_16x16x32_bf16 v[84:87], v[222:225], v[92:95], v[84:87]
	v_mfma_f32_16x16x32_bf16 v[88:91], v[232:235], v[92:95], v[88:91]
	v_mfma_f32_16x16x32_bf16 v[92:95], v[204:207], v[188:191], v[132:135]
	v_mfma_f32_16x16x32_bf16 v[100:103], v[232:235], v[192:195], v[100:103]
	v_mfma_f32_16x16x32_bf16 v[128:131], v[222:225], v[200:203], v[104:107]
	v_mfma_f32_16x16x32_bf16 v[96:99], v[232:235], v[200:203], v[96:99]
	v_mfma_f32_16x16x32_bf16 v[92:95], v[222:225], v[192:195], v[92:95]
	s_barrier
	s_add_i32 s27, 0, 0x14000
	s_add_i32 s56, s57, s74
	s_mov_b32 m0, s56
	s_nop 0
	global_load_lds_dwordx4 v144, s[82:83]
	s_add_i32 m0, s56, 0x2000
	s_nop 0
	global_load_lds_dwordx4 v162, s[82:83]
	s_mov_b32 m0, s75
	ds_read_b128 v[104:107], v220 offset:16384
	ds_read_b128 v[108:111], v220 offset:17408
	ds_read_b128 v[132:135], v220 offset:18432
	ds_read_b128 v[136:139], v220 offset:19456
	ds_read_b128 v[188:191], v220 offset:20480
	ds_read_b128 v[192:195], v220 offset:21504
	ds_read_b128 v[196:199], v220 offset:22528
	ds_read_b128 v[200:203], v220 offset:23552
	global_load_lds_dwordx4 v144, vcc
	s_mov_b32 m0, s85
	s_nop 0
	global_load_lds_dwordx4 v162, vcc
	s_add_u32 s56, s82, 0x40000
	s_addc_u32 s57, s83, 0
	s_add_i32 s27, s27, s74
	s_mov_b32 m0, s27
	s_nop 0
	global_load_lds_dwordx4 v144, s[56:57]
	s_add_i32 m0, s27, 0x2000
	s_nop 0
	global_load_lds_dwordx4 v162, s[56:57]
	s_waitcnt lgkmcnt(0)
	s_waitcnt vmcnt(8)
	s_barrier
	v_mfma_f32_16x16x32_bf16 v[48:51], v[64:67], v[104:107], v[48:51]
	v_mfma_f32_16x16x32_bf16 v[20:23], v[72:75], v[104:107], v[20:23]
	v_mfma_f32_16x16x32_bf16 v[60:63], v[64:67], v[132:135], v[60:63]
	v_mfma_f32_16x16x32_bf16 v[28:31], v[72:75], v[132:135], v[28:31]
	v_mfma_f32_16x16x32_bf16 v[56:59], v[64:67], v[188:191], v[56:59]
	v_mfma_f32_16x16x32_bf16 v[16:19], v[72:75], v[188:191], v[16:19]
	v_mfma_f32_16x16x32_bf16 v[52:55], v[64:67], v[196:199], v[52:55]
	v_mfma_f32_16x16x32_bf16 v[24:27], v[72:75], v[196:199], v[24:27]
	v_mfma_f32_16x16x32_bf16 v[48:51], v[68:71], v[108:111], v[48:51]
	v_mfma_f32_16x16x32_bf16 v[20:23], v[76:79], v[108:111], v[20:23]
	v_mfma_f32_16x16x32_bf16 v[60:63], v[68:71], v[136:139], v[60:63]
	v_mfma_f32_16x16x32_bf16 v[28:31], v[76:79], v[136:139], v[28:31]
	v_mfma_f32_16x16x32_bf16 v[56:59], v[68:71], v[192:195], v[56:59]
	v_mfma_f32_16x16x32_bf16 v[16:19], v[76:79], v[192:195], v[16:19]
	v_mfma_f32_16x16x32_bf16 v[52:55], v[68:71], v[200:203], v[52:55]
	v_mfma_f32_16x16x32_bf16 v[24:27], v[76:79], v[200:203], v[24:27]
	v_mfma_f32_16x16x32_bf16 v[44:47], v[204:207], v[104:107], v[44:47]
	v_mfma_f32_16x16x32_bf16 v[12:15], v[228:231], v[104:107], v[12:15]
	v_mfma_f32_16x16x32_bf16 v[40:43], v[204:207], v[132:135], v[40:43]
	v_mfma_f32_16x16x32_bf16 v[8:11], v[228:231], v[132:135], v[8:11]
	v_mfma_f32_16x16x32_bf16 v[36:39], v[204:207], v[188:191], v[36:39]
	v_mfma_f32_16x16x32_bf16 v[4:7], v[228:231], v[188:191], v[4:7]
	v_mfma_f32_16x16x32_bf16 v[32:35], v[204:207], v[196:199], v[32:35]
	v_mfma_f32_16x16x32_bf16 v[0:3], v[228:231], v[196:199], v[0:3]
	v_mfma_f32_16x16x32_bf16 v[44:47], v[222:225], v[108:111], v[44:47]
	v_mfma_f32_16x16x32_bf16 v[12:15], v[232:235], v[108:111], v[12:15]
	v_mfma_f32_16x16x32_bf16 v[40:43], v[222:225], v[136:139], v[40:43]
	v_mfma_f32_16x16x32_bf16 v[8:11], v[232:235], v[136:139], v[8:11]
	v_mfma_f32_16x16x32_bf16 v[36:39], v[222:225], v[192:195], v[36:39]
	v_mfma_f32_16x16x32_bf16 v[4:7], v[232:235], v[192:195], v[4:7]
	v_mfma_f32_16x16x32_bf16 v[32:35], v[222:225], v[200:203], v[32:35]
	v_mfma_f32_16x16x32_bf16 v[0:3], v[232:235], v[200:203], v[0:3]
	s_barrier
	s_add_i32 s27, 0, 0x18000
	ds_read_b128 v[64:67], v217 offset:32768
	ds_read_b128 v[68:71], v217 offset:33792
	ds_read_b128 v[72:75], v217 offset:34816
	ds_read_b128 v[76:79], v217 offset:35840
	s_add_u32 s56, vcc_lo, 0x40000
	s_addc_u32 s57, vcc_hi, 0
	s_mov_b32 m0, s98
	ds_read_b128 v[104:107], v220 offset:32768
	ds_read_b128 v[108:111], v220 offset:33792
	ds_read_b128 v[132:135], v220 offset:34816
	ds_read_b128 v[188:191], v220 offset:35840
	ds_read_b128 v[192:195], v220 offset:36864
	ds_read_b128 v[196:199], v220 offset:37888
	ds_read_b128 v[200:203], v220 offset:38912
	ds_read_b128 v[204:207], v220 offset:39936
	s_waitcnt lgkmcnt(8)
	ds_read_b128 v[222:225], v217 offset:49152
	ds_read_b128 v[228:231], v217 offset:50176
	ds_read_b128 v[232:235], v217 offset:51200
	ds_read_b128 v[236:239], v217 offset:52224
	global_load_lds_dwordx4 v144, s[56:57]
	s_mov_b32 m0, s29
	s_nop 0
	global_load_lds_dwordx4 v162, s[56:57]
	s_waitcnt lgkmcnt(0)
	s_waitcnt vmcnt(8)
	s_barrier
	v_mfma_f32_16x16x32_bf16 v[136:139], v[64:67], v[104:107], v[146:149]
	v_mfma_f32_16x16x32_bf16 v[146:149], v[68:71], v[108:111], v[136:139]
	v_mfma_f32_16x16x32_bf16 v[136:139], v[64:67], v[132:135], v[158:161]
	v_mfma_f32_16x16x32_bf16 v[158:161], v[68:71], v[188:191], v[136:139]
	v_mfma_f32_16x16x32_bf16 v[136:139], v[64:67], v[192:195], v[154:157]
	v_mfma_f32_16x16x32_bf16 v[116:119], v[72:75], v[104:107], v[116:119]
	v_mfma_f32_16x16x32_bf16 v[124:127], v[72:75], v[132:135], v[124:127]
	v_mfma_f32_16x16x32_bf16 v[154:157], v[68:71], v[196:199], v[136:139]
	v_mfma_f32_16x16x32_bf16 v[112:115], v[72:75], v[192:195], v[112:115]
	v_mfma_f32_16x16x32_bf16 v[136:139], v[64:67], v[200:203], v[150:153]
	v_mfma_f32_16x16x32_bf16 v[120:123], v[72:75], v[200:203], v[120:123]
	v_mfma_f32_16x16x32_bf16 v[116:119], v[76:79], v[108:111], v[116:119]
	v_mfma_f32_16x16x32_bf16 v[124:127], v[76:79], v[188:191], v[124:127]
	v_mfma_f32_16x16x32_bf16 v[112:115], v[76:79], v[196:199], v[112:115]
	v_mfma_f32_16x16x32_bf16 v[150:153], v[68:71], v[204:207], v[136:139]
	v_mfma_f32_16x16x32_bf16 v[120:123], v[76:79], v[204:207], v[120:123]
	v_mfma_f32_16x16x32_bf16 v[136:139], v[222:225], v[104:107], v[140:143]
	v_mfma_f32_16x16x32_bf16 v[80:83], v[232:235], v[104:107], v[80:83]
	v_mfma_f32_16x16x32_bf16 v[140:143], v[228:231], v[108:111], v[136:139]
	v_mfma_f32_16x16x32_bf16 v[108:111], v[236:239], v[108:111], v[80:83]
	v_mfma_f32_16x16x32_bf16 v[80:83], v[222:225], v[132:135], v[84:87]
	v_mfma_f32_16x16x32_bf16 v[136:139], v[228:231], v[188:191], v[80:83]
	v_mfma_f32_16x16x32_bf16 v[80:83], v[232:235], v[132:135], v[88:91]
	v_mfma_f32_16x16x32_bf16 v[104:107], v[236:239], v[188:191], v[80:83]
	v_mfma_f32_16x16x32_bf16 v[80:83], v[222:225], v[192:195], v[92:95]
	v_mfma_f32_16x16x32_bf16 v[132:135], v[228:231], v[196:199], v[80:83]
	v_mfma_f32_16x16x32_bf16 v[80:83], v[232:235], v[192:195], v[100:103]
	v_mfma_f32_16x16x32_bf16 v[100:103], v[236:239], v[196:199], v[80:83]
	v_mfma_f32_16x16x32_bf16 v[80:83], v[222:225], v[200:203], v[128:131]
	v_mfma_f32_16x16x32_bf16 v[128:131], v[228:231], v[204:207], v[80:83]
	v_mfma_f32_16x16x32_bf16 v[80:83], v[232:235], v[200:203], v[96:99]
	v_mfma_f32_16x16x32_bf16 v[96:99], v[236:239], v[204:207], v[80:83]
	s_barrier
	s_nop 0
	s_add_i32 s58, 0, 0x1c000
	s_add_i32 s27, s27, s74
	s_add_u32 s56, s82, s18
	s_addc_u32 s57, s83, s19
	s_mov_b32 m0, s27
	s_nop 0
	global_load_lds_dwordx4 v144, s[56:57]
	s_add_u32 s56, s82, s18
	s_addc_u32 s57, s83, s19
	s_add_i32 m0, s27, 0x2000
	s_nop 0
	global_load_lds_dwordx4 v162, s[56:57]
	s_nop 0
	s_mov_b32 m0, s31
	s_add_u32 s56, vcc_lo, s18
	s_addc_u32 s57, vcc_hi, s19
	s_nop 2
	ds_read_b128 v[80:83], v220 offset:49152
	ds_read_b128 v[84:87], v220 offset:50176
	ds_read_b128 v[88:91], v220 offset:51200
	ds_read_b128 v[92:95], v220 offset:52224
	ds_read_b128 v[188:191], v220 offset:53248
	ds_read_b128 v[192:195], v220 offset:54272
	ds_read_b128 v[196:199], v220 offset:55296
	ds_read_b128 v[200:203], v220 offset:56320
	global_load_lds_dwordx4 v144, s[56:57]
	s_add_u32 s56, vcc_lo, s18
	s_addc_u32 s57, vcc_hi, s19
	s_mov_b32 m0, s34
	s_nop 0
	global_load_lds_dwordx4 v162, s[56:57]
	s_add_u32 s56, s82, 0x40080
	s_addc_u32 s57, s83, 0
	s_add_i32 s27, s58, s74
	s_mov_b32 m0, s27
	s_nop 0
	global_load_lds_dwordx4 v144, s[56:57]
	s_add_i32 m0, s27, 0x2000
	s_nop 0
	global_load_lds_dwordx4 v162, s[56:57]
	s_waitcnt lgkmcnt(0)
	s_waitcnt vmcnt(8)
	s_barrier
	v_mfma_f32_16x16x32_bf16 v[48:51], v[64:67], v[80:83], v[48:51]
	v_mfma_f32_16x16x32_bf16 v[20:23], v[72:75], v[80:83], v[20:23]
	v_mfma_f32_16x16x32_bf16 v[60:63], v[64:67], v[88:91], v[60:63]
	v_mfma_f32_16x16x32_bf16 v[28:31], v[72:75], v[88:91], v[28:31]
	v_mfma_f32_16x16x32_bf16 v[56:59], v[64:67], v[188:191], v[56:59]
	v_mfma_f32_16x16x32_bf16 v[16:19], v[72:75], v[188:191], v[16:19]
	v_mfma_f32_16x16x32_bf16 v[52:55], v[64:67], v[196:199], v[52:55]
	v_mfma_f32_16x16x32_bf16 v[24:27], v[72:75], v[196:199], v[24:27]
	v_mfma_f32_16x16x32_bf16 v[48:51], v[68:71], v[84:87], v[48:51]
	v_mfma_f32_16x16x32_bf16 v[20:23], v[76:79], v[84:87], v[20:23]
	v_mfma_f32_16x16x32_bf16 v[60:63], v[68:71], v[92:95], v[60:63]
	v_mfma_f32_16x16x32_bf16 v[28:31], v[76:79], v[92:95], v[28:31]
	v_mfma_f32_16x16x32_bf16 v[56:59], v[68:71], v[192:195], v[56:59]
	v_mfma_f32_16x16x32_bf16 v[16:19], v[76:79], v[192:195], v[16:19]
	v_mfma_f32_16x16x32_bf16 v[52:55], v[68:71], v[200:203], v[52:55]
	v_mfma_f32_16x16x32_bf16 v[24:27], v[76:79], v[200:203], v[24:27]
	v_mfma_f32_16x16x32_bf16 v[44:47], v[222:225], v[80:83], v[44:47]
	v_mfma_f32_16x16x32_bf16 v[12:15], v[232:235], v[80:83], v[12:15]
	v_mfma_f32_16x16x32_bf16 v[40:43], v[222:225], v[88:91], v[40:43]
	v_mfma_f32_16x16x32_bf16 v[8:11], v[232:235], v[88:91], v[8:11]
	v_mfma_f32_16x16x32_bf16 v[36:39], v[222:225], v[188:191], v[36:39]
	v_mfma_f32_16x16x32_bf16 v[4:7], v[232:235], v[188:191], v[4:7]
	v_mfma_f32_16x16x32_bf16 v[32:35], v[222:225], v[196:199], v[32:35]
	v_mfma_f32_16x16x32_bf16 v[0:3], v[232:235], v[196:199], v[0:3]
	v_mfma_f32_16x16x32_bf16 v[44:47], v[228:231], v[84:87], v[44:47]
	v_mfma_f32_16x16x32_bf16 v[12:15], v[236:239], v[84:87], v[12:15]
	v_mfma_f32_16x16x32_bf16 v[40:43], v[228:231], v[92:95], v[40:43]
	v_mfma_f32_16x16x32_bf16 v[8:11], v[236:239], v[92:95], v[8:11]
	v_mfma_f32_16x16x32_bf16 v[36:39], v[228:231], v[192:195], v[36:39]
	v_mfma_f32_16x16x32_bf16 v[4:7], v[236:239], v[192:195], v[4:7]
	v_mfma_f32_16x16x32_bf16 v[32:35], v[228:231], v[200:203], v[32:35]
	v_mfma_f32_16x16x32_bf16 v[0:3], v[236:239], v[200:203], v[0:3]
	s_barrier
	s_add_i32 s37, s37, 2
	s_add_u32 s86, s86, 0x100
	s_addc_u32 s87, s87, 0
	s_add_u32 s33, s33, 0x100
	s_addc_u32 s36, s36, 0
	s_cmp_gt_u32 s37, 13
	s_cbranch_scc0 .LBB0_125
	s_lshl_b32 s1, s84, 8
	v_readlane_b32 s10, v254, 61
	s_add_i32 s1, s1, s10
	v_or_b32_e32 v198, s1, v216
	s_add_i32 s10, s1, 0x80
	v_or_b32_e32 v168, s10, v216
	v_lshl_or_b32 v188, s0, 7, v219
	v_lshlrev_b32_e32 v190, 2, v188
	v_lshlrev_b32_e32 v189, 1, v188
	s_ashr_i32 s11, s1, 5
	s_movk_i32 s10, 0xb00
	s_movk_i32 s20, 0x1600
	s_mov_b32 s101, 0xbfb8aa3b
	s_cmp_eq_u32 s84, s100
	s_cbranch_scc1 .Ldepi_w
	v_ashrrev_i32_e32 v199, 31, v198
	v_ashrrev_i32_e32 v169, 31, v168
	v_lshl_add_u64 v[170:171], v[198:199], 3, s[48:49]
	v_lshl_add_u64 v[172:173], v[168:169], 3, s[48:49]
	global_load_dwordx2 v[176:177], v[170:171], off
	global_load_dwordx2 v[202:203], v[170:171], off offset:128
	global_load_dwordx2 v[206:207], v[170:171], off offset:256
	global_load_dwordx2 v[222:223], v[170:171], off offset:384
	global_load_dwordx2 v[200:201], v[172:173], off
	global_load_dwordx2 v[196:197], v[172:173], off offset:128
	global_load_dwordx2 v[194:195], v[172:173], off offset:256
	global_load_dwordx2 v[192:193], v[172:173], off offset:384

.LBB0_181:
	v_readlane_b32 s20, v254, 47
	s_add_i32 s31, s20, 4
	s_cmp_lt_u32 s31, 11
	s_cselect_b64 s[34:35], -1, 0
	s_and_b64 s[34:35], s[34:35], s[0:1]
	v_readlane_b32 s56, v254, 23
	s_and_b64 s[34:35], s[34:35], exec
	v_readlane_b32 s57, v254, 24
	s_cselect_b32 s51, s57, 0
	s_cselect_b32 s50, s56, 0
	s_sub_i32 s31, s20, 25
	s_cmp_lt_u32 s31, -6
	s_cselect_b64 s[34:35], -1, 0
	s_or_b64 s[0:1], s[34:35], s[0:1]
	v_readlane_b32 s40, v252, 0
	s_and_b64 s[0:1], s[0:1], exec
	v_readlane_b32 s42, v252, 2
	v_readlane_b32 s43, v252, 3
	v_bfe_u32 v19, v18, 4, 2
	s_cselect_b32 s95, 0, s43
	s_cselect_b32 s94, 0, s42
	s_add_u32 s52, s54, s38
	v_and_b32_e32 v20, 15, v18
	v_lshlrev_b32_e32 v21, 4, v19
	v_lshlrev_b32_e32 v18, 2, v18
	s_addc_u32 s53, s55, s39
	v_lshl_or_b32 v206, s27, 6, v20
	v_lshl_or_b32 v20, v20, 6, v21
	s_lshl_b32 s0, s27, 13
	v_and_b32_e32 v18, 32, v18
	s_add_i32 m0, s85, 0x18000
	v_lshl_add_u64 v[0:1], v[0:1], 0, s[18:19]
	v_bitop3_b32 v21, v20, s0, v18 bitop3:0xde
	s_lshl_b32 s0, s30, 5
	s_waitcnt vmcnt(2)
	s_barrier
	global_load_lds_dwordx4 v[0:1], off
	v_lshl_add_u64 v[0:1], v[2:3], 0, s[18:19]
	s_add_i32 m0, s85, 0x1a000
	s_add_i32 s30, s85, 0x8000
	global_load_lds_dwordx4 v[0:1], off
	v_lshl_add_u64 v[0:1], v[4:5], 0, s[18:19]
	s_mov_b32 m0, s30
	s_add_i32 s31, s85, 0xa000
	global_load_lds_dwordx4 v[0:1], off
	v_lshl_add_u64 v[0:1], v[6:7], 0, s[18:19]
	s_mov_b32 m0, s31
	s_lshr_b32 s34, s25, 6
	global_load_lds_dwordx4 v[0:1], off
	s_add_i32 m0, s85, 0x1c000
	v_lshl_add_u64 v[0:1], v[8:9], 0, s[18:19]
	global_load_lds_dwordx4 v[0:1], off
	v_lshl_add_u64 v[0:1], v[10:11], 0, s[18:19]
	s_add_i32 m0, s85, 0x1e000
	s_and_b32 s0, s0, 0x60
	global_load_lds_dwordx4 v[0:1], off
	s_lshl_b32 s1, s0, 7
	s_add_i32 s82, s34, -2
	s_ashr_i32 s35, s29, 31
	v_add_u32_e32 v0, v14, v12
	s_cmp_lg_u64 s[50:51], 0
	v_add_lshl_u32 v0, v0, v13, 1
	v_mov_b32_e32 v1, v145
	s_waitcnt vmcnt(6)
	s_cselect_b64 s[92:93], -1, 0
	s_cmp_eq_u64 s[94:95], 0
	v_lshl_add_u64 v[190:191], s[98:99], 0, v[0:1]
	v_add_u32_e32 v0, v17, v15
	s_cselect_b64 s[72:73], -1, 0
	s_cmp_lg_u64 s[94:95], 0
	v_add_lshl_u32 v0, v0, v16, 1
	s_mov_b32 s81, 0
	v_bitop3_b32 v207, v20, s1, v18 bitop3:0xde
	v_add_u32_e32 v207, 0x10000, v207
	v_cmp_eq_u32_e64 s[38:39], 0, v19
	s_cselect_b64 s[74:75], -1, 0
	v_lshl_or_b32 v216, v19, 3, s0
	v_lshl_add_u64 v[192:193], s[98:99], 0, v[0:1]
	v_add_u32_e32 v217, 0, v21
	v_readlane_b32 s58, v254, 25
	v_readlane_b32 s59, v254, 26
	v_readlane_b32 s60, v254, 27
	v_readlane_b32 s61, v254, 28
	v_readlane_b32 s62, v254, 29
	v_readlane_b32 s63, v254, 30
	v_readlane_b32 s64, v254, 31
	v_readlane_b32 s65, v254, 32
	v_readlane_b32 s66, v254, 33
	v_readlane_b32 s67, v254, 34
	v_readlane_b32 s68, v254, 35
	v_readlane_b32 s69, v254, 36
	v_readlane_b32 s70, v254, 37
	v_readlane_b32 s71, v254, 38
	v_readlane_b32 s41, v252, 1
	s_barrier
	v_readfirstlane_b32 s101, v208
	s_nop 3
	s_lshr_b32 s101, s101, 8
	s_cmp_eq_u32 s101, 0
	s_cbranch_scc1 .Lprio_ce_done
	s_setprio 1

.LBB0_195:
	s_add_u32 s42, s78, 0x80
	s_addc_u32 s43, s79, 0
	s_add_u32 s33, s44, 0x100
	s_addc_u32 s37, s45, 0
	s_mov_b32 s27, 0
	s_waitcnt lgkmcnt(0)
	s_add_i32 s56, s27, 2
	s_add_u32 s44, s42, 0x80
	s_addc_u32 s45, s43, 0
	s_add_i32 s57, 0, 0x10000
	ds_read_b128 v[128:131], v207
	ds_read_b128 v[132:135], v207 offset:1024
	ds_read_b128 v[136:139], v207 offset:2048
	ds_read_b128 v[140:143], v207 offset:3072
	s_cmp_eq_u32 s82, s27
	s_cselect_b32 s45, s77, s45
	s_cselect_b32 s44, s76, s44
	s_cselect_b32 s79, s1, s37
	s_cselect_b32 s78, s0, s33
	v_lshl_add_u64 v[176:177], s[42:43], 0, v[190:191]
	s_add_i32 m0, s85, 0xc000
	ds_read_b128 v[146:149], v217
	ds_read_b128 v[150:153], v217 offset:1024
	ds_read_b128 v[154:157], v217 offset:2048
	ds_read_b128 v[158:161], v217 offset:3072
	ds_read_b128 v[162:165], v217 offset:4096
	ds_read_b128 v[166:169], v217 offset:5120
	ds_read_b128 v[194:197], v217 offset:6144
	ds_read_b128 v[198:201], v217 offset:7168
	s_waitcnt lgkmcnt(8)
	ds_read_b128 v[202:205], v207 offset:16384
	ds_read_b128 v[218:221], v207 offset:17408
	ds_read_b128 v[222:225], v207 offset:18432
	ds_read_b128 v[228:231], v207 offset:19456
	global_load_lds_dwordx4 v[176:177], off
	v_lshl_add_u64 v[176:177], s[42:43], 0, v[192:193]
	s_add_i32 m0, s85, 0xe000
	s_nop 0
	global_load_lds_dwordx4 v[176:177], off
	s_waitcnt lgkmcnt(0)
	s_waitcnt vmcnt(8)
	s_barrier
	v_mfma_f32_16x16x32_bf16 v[124:127], v[128:131], v[146:149], 0
	v_mfma_f32_16x16x32_bf16 v[120:123], v[136:139], v[146:149], 0
	v_mfma_f32_16x16x32_bf16 v[108:111], v[128:131], v[154:157], 0
	v_mfma_f32_16x16x32_bf16 v[104:107], v[136:139], v[154:157], 0
	v_mfma_f32_16x16x32_bf16 v[92:95], v[128:131], v[162:165], 0
	v_mfma_f32_16x16x32_bf16 v[88:91], v[136:139], v[162:165], 0
	v_mfma_f32_16x16x32_bf16 v[76:79], v[128:131], v[194:197], 0
	v_mfma_f32_16x16x32_bf16 v[72:75], v[136:139], v[194:197], 0
	v_mfma_f32_16x16x32_bf16 v[124:127], v[132:135], v[150:153], v[124:127]
	v_mfma_f32_16x16x32_bf16 v[120:123], v[140:143], v[150:153], v[120:123]
	v_mfma_f32_16x16x32_bf16 v[108:111], v[132:135], v[158:161], v[108:111]
	v_mfma_f32_16x16x32_bf16 v[104:107], v[140:143], v[158:161], v[104:107]
	v_mfma_f32_16x16x32_bf16 v[92:95], v[132:135], v[166:169], v[92:95]
	v_mfma_f32_16x16x32_bf16 v[88:91], v[140:143], v[166:169], v[88:91]
	v_mfma_f32_16x16x32_bf16 v[76:79], v[132:135], v[198:201], v[76:79]
	v_mfma_f32_16x16x32_bf16 v[72:75], v[140:143], v[198:201], v[72:75]
	v_mfma_f32_16x16x32_bf16 v[116:119], v[202:205], v[146:149], 0
	v_mfma_f32_16x16x32_bf16 v[112:115], v[222:225], v[146:149], 0
	v_mfma_f32_16x16x32_bf16 v[100:103], v[202:205], v[154:157], 0
	v_mfma_f32_16x16x32_bf16 v[96:99], v[222:225], v[154:157], 0
	v_mfma_f32_16x16x32_bf16 v[84:87], v[202:205], v[162:165], 0
	v_mfma_f32_16x16x32_bf16 v[80:83], v[222:225], v[162:165], 0
	v_mfma_f32_16x16x32_bf16 v[68:71], v[202:205], v[194:197], 0
	v_mfma_f32_16x16x32_bf16 v[64:67], v[222:225], v[194:197], 0
	v_mfma_f32_16x16x32_bf16 v[116:119], v[218:221], v[150:153], v[116:119]
	v_mfma_f32_16x16x32_bf16 v[112:115], v[228:231], v[150:153], v[112:115]
	v_mfma_f32_16x16x32_bf16 v[100:103], v[218:221], v[158:161], v[100:103]
	v_mfma_f32_16x16x32_bf16 v[96:99], v[228:231], v[158:161], v[96:99]
	v_mfma_f32_16x16x32_bf16 v[84:87], v[218:221], v[166:169], v[84:87]
	v_mfma_f32_16x16x32_bf16 v[80:83], v[228:231], v[166:169], v[80:83]
	v_mfma_f32_16x16x32_bf16 v[68:71], v[218:221], v[198:201], v[68:71]
	v_mfma_f32_16x16x32_bf16 v[64:67], v[228:231], v[198:201], v[64:67]
	s_barrier
	s_add_i32 s27, 0, 0x14000
	s_add_i32 s57, s57, s84
	v_lshl_add_u64 v[176:177], s[78:79], 0, v[144:145]
	s_mov_b32 m0, s57
	v_lshl_add_u64 v[232:233], s[78:79], 0, v[188:189]
	global_load_lds_dwordx4 v[176:177], off
	s_add_i32 m0, s57, 0x2000
	s_nop 0
	global_load_lds_dwordx4 v[232:233], off
	s_mov_b32 m0, s85
	v_lshl_add_u64 v[234:235], s[44:45], 0, v[144:145]
	ds_read_b128 v[146:149], v217 offset:16384
	ds_read_b128 v[150:153], v217 offset:17408
	ds_read_b128 v[154:157], v217 offset:18432
	ds_read_b128 v[158:161], v217 offset:19456
	ds_read_b128 v[162:165], v217 offset:20480
	ds_read_b128 v[166:169], v217 offset:21504
	ds_read_b128 v[194:197], v217 offset:22528
	ds_read_b128 v[198:201], v217 offset:23552
	global_load_lds_dwordx4 v[234:235], off
	v_lshl_add_u64 v[236:237], s[44:45], 0, v[188:189]
	s_mov_b32 m0, s86
	s_nop 0
	global_load_lds_dwordx4 v[236:237], off
	s_add_u32 s58, s78, s98
	s_addc_u32 s59, s79, 0
	s_add_i32 s27, s27, s84
	v_lshl_add_u64 v[238:239], s[58:59], 0, v[144:145]
	s_mov_b32 m0, s27
	v_lshl_add_u64 v[240:241], s[58:59], 0, v[188:189]
	global_load_lds_dwordx4 v[238:239], off
	s_add_i32 m0, s27, 0x2000
	s_nop 0
	global_load_lds_dwordx4 v[240:241], off
	s_waitcnt lgkmcnt(0)
	s_waitcnt vmcnt(8)
	s_barrier
	v_mfma_f32_16x16x32_bf16 v[60:63], v[128:131], v[146:149], 0
	v_mfma_f32_16x16x32_bf16 v[56:59], v[136:139], v[146:149], 0
	v_mfma_f32_16x16x32_bf16 v[44:47], v[128:131], v[154:157], 0
	v_mfma_f32_16x16x32_bf16 v[40:43], v[136:139], v[154:157], 0
	v_mfma_f32_16x16x32_bf16 v[28:31], v[128:131], v[162:165], 0
	v_mfma_f32_16x16x32_bf16 v[24:27], v[136:139], v[162:165], 0
	v_mfma_f32_16x16x32_bf16 v[12:15], v[128:131], v[194:197], 0
	v_mfma_f32_16x16x32_bf16 v[8:11], v[136:139], v[194:197], 0
	v_mfma_f32_16x16x32_bf16 v[60:63], v[132:135], v[150:153], v[60:63]
	v_mfma_f32_16x16x32_bf16 v[56:59], v[140:143], v[150:153], v[56:59]
	v_mfma_f32_16x16x32_bf16 v[44:47], v[132:135], v[158:161], v[44:47]
	v_mfma_f32_16x16x32_bf16 v[40:43], v[140:143], v[158:161], v[40:43]
	v_mfma_f32_16x16x32_bf16 v[28:31], v[132:135], v[166:169], v[28:31]
	v_mfma_f32_16x16x32_bf16 v[24:27], v[140:143], v[166:169], v[24:27]
	v_mfma_f32_16x16x32_bf16 v[12:15], v[132:135], v[198:201], v[12:15]
	v_mfma_f32_16x16x32_bf16 v[8:11], v[140:143], v[198:201], v[8:11]
	v_mfma_f32_16x16x32_bf16 v[52:55], v[202:205], v[146:149], 0
	v_mfma_f32_16x16x32_bf16 v[48:51], v[222:225], v[146:149], 0
	v_mfma_f32_16x16x32_bf16 v[36:39], v[202:205], v[154:157], 0
	v_mfma_f32_16x16x32_bf16 v[32:35], v[222:225], v[154:157], 0
	v_mfma_f32_16x16x32_bf16 v[20:23], v[202:205], v[162:165], 0
	v_mfma_f32_16x16x32_bf16 v[16:19], v[222:225], v[162:165], 0
	v_mfma_f32_16x16x32_bf16 v[4:7], v[202:205], v[194:197], 0
	v_mfma_f32_16x16x32_bf16 v[0:3], v[222:225], v[194:197], 0
	v_mfma_f32_16x16x32_bf16 v[52:55], v[218:221], v[150:153], v[52:55]
	v_mfma_f32_16x16x32_bf16 v[48:51], v[228:231], v[150:153], v[48:51]
	v_mfma_f32_16x16x32_bf16 v[36:39], v[218:221], v[158:161], v[36:39]
	v_mfma_f32_16x16x32_bf16 v[32:35], v[228:231], v[158:161], v[32:35]
	v_mfma_f32_16x16x32_bf16 v[20:23], v[218:221], v[166:169], v[20:23]
	v_mfma_f32_16x16x32_bf16 v[16:19], v[228:231], v[166:169], v[16:19]
	v_mfma_f32_16x16x32_bf16 v[4:7], v[218:221], v[198:201], v[4:7]
	v_mfma_f32_16x16x32_bf16 v[0:3], v[228:231], v[198:201], v[0:3]
	s_barrier
	s_nop 0
	s_add_i32 s27, 0, 0x18000
	ds_read_b128 v[128:131], v207 offset:32768
	ds_read_b128 v[132:135], v207 offset:33792
	ds_read_b128 v[136:139], v207 offset:34816
	ds_read_b128 v[140:143], v207 offset:35840
	s_add_u32 s44, s44, s98
	s_addc_u32 s45, s45, 0
	s_mov_b32 m0, s87
	ds_read_b128 v[146:149], v217 offset:32768
	ds_read_b128 v[150:153], v217 offset:33792
	ds_read_b128 v[154:157], v217 offset:34816
	ds_read_b128 v[158:161], v217 offset:35840
	ds_read_b128 v[162:165], v217 offset:36864
	ds_read_b128 v[166:169], v217 offset:37888
	ds_read_b128 v[194:197], v217 offset:38912
	ds_read_b128 v[198:201], v217 offset:39936
	s_waitcnt lgkmcnt(8)
	ds_read_b128 v[202:205], v207 offset:49152
	ds_read_b128 v[218:221], v207 offset:50176
	ds_read_b128 v[222:225], v207 offset:51200
	ds_read_b128 v[228:231], v207 offset:52224
	global_load_lds_dwordx4 v144, s[44:45]
	s_mov_b32 m0, s80
	s_nop 0
	global_load_lds_dwordx4 v188, s[44:45]
	s_waitcnt lgkmcnt(0)
	s_waitcnt vmcnt(8)
	s_barrier
	v_mfma_f32_16x16x32_bf16 v[124:127], v[128:131], v[146:149], v[124:127]
	v_mfma_f32_16x16x32_bf16 v[120:123], v[136:139], v[146:149], v[120:123]
	v_mfma_f32_16x16x32_bf16 v[108:111], v[128:131], v[154:157], v[108:111]
	v_mfma_f32_16x16x32_bf16 v[104:107], v[136:139], v[154:157], v[104:107]
	v_mfma_f32_16x16x32_bf16 v[92:95], v[128:131], v[162:165], v[92:95]
	v_mfma_f32_16x16x32_bf16 v[88:91], v[136:139], v[162:165], v[88:91]
	v_mfma_f32_16x16x32_bf16 v[76:79], v[128:131], v[194:197], v[76:79]
	v_mfma_f32_16x16x32_bf16 v[72:75], v[136:139], v[194:197], v[72:75]
	v_mfma_f32_16x16x32_bf16 v[124:127], v[132:135], v[150:153], v[124:127]
	v_mfma_f32_16x16x32_bf16 v[120:123], v[140:143], v[150:153], v[120:123]
	v_mfma_f32_16x16x32_bf16 v[108:111], v[132:135], v[158:161], v[108:111]
	v_mfma_f32_16x16x32_bf16 v[104:107], v[140:143], v[158:161], v[104:107]
	v_mfma_f32_16x16x32_bf16 v[92:95], v[132:135], v[166:169], v[92:95]
	v_mfma_f32_16x16x32_bf16 v[88:91], v[140:143], v[166:169], v[88:91]
	v_mfma_f32_16x16x32_bf16 v[76:79], v[132:135], v[198:201], v[76:79]
	v_mfma_f32_16x16x32_bf16 v[72:75], v[140:143], v[198:201], v[72:75]
	v_mfma_f32_16x16x32_bf16 v[116:119], v[202:205], v[146:149], v[116:119]
	v_mfma_f32_16x16x32_bf16 v[112:115], v[222:225], v[146:149], v[112:115]
	v_mfma_f32_16x16x32_bf16 v[100:103], v[202:205], v[154:157], v[100:103]
	v_mfma_f32_16x16x32_bf16 v[96:99], v[222:225], v[154:157], v[96:99]
	v_mfma_f32_16x16x32_bf16 v[84:87], v[202:205], v[162:165], v[84:87]
	v_mfma_f32_16x16x32_bf16 v[80:83], v[222:225], v[162:165], v[80:83]
	v_mfma_f32_16x16x32_bf16 v[68:71], v[202:205], v[194:197], v[68:71]
	v_mfma_f32_16x16x32_bf16 v[64:67], v[222:225], v[194:197], v[64:67]
	v_mfma_f32_16x16x32_bf16 v[116:119], v[218:221], v[150:153], v[116:119]
	v_mfma_f32_16x16x32_bf16 v[112:115], v[228:231], v[150:153], v[112:115]
	v_mfma_f32_16x16x32_bf16 v[100:103], v[218:221], v[158:161], v[100:103]
	v_mfma_f32_16x16x32_bf16 v[96:99], v[228:231], v[158:161], v[96:99]
	v_mfma_f32_16x16x32_bf16 v[84:87], v[218:221], v[166:169], v[84:87]
	v_mfma_f32_16x16x32_bf16 v[80:83], v[228:231], v[166:169], v[80:83]
	v_mfma_f32_16x16x32_bf16 v[68:71], v[218:221], v[198:201], v[68:71]
	v_mfma_f32_16x16x32_bf16 v[64:67], v[228:231], v[198:201], v[64:67]
	s_barrier
	s_add_i32 s44, 0, 0x1c000
	s_add_i32 s27, s27, s84
	v_lshl_add_u64 v[176:177], v[176:177], 0, s[18:19]
	s_mov_b32 m0, s27
	s_nop 0
	global_load_lds_dwordx4 v[176:177], off
	v_lshl_add_u64 v[176:177], v[232:233], 0, s[18:19]
	s_add_i32 m0, s27, 0x2000
	s_nop 0
	global_load_lds_dwordx4 v[176:177], off
	s_mov_b32 m0, s30
	v_lshl_add_u64 v[176:177], v[234:235], 0, s[18:19]
	ds_read_b128 v[146:149], v217 offset:49152
	ds_read_b128 v[150:153], v217 offset:50176
	ds_read_b128 v[154:157], v217 offset:51200
	ds_read_b128 v[158:161], v217 offset:52224
	ds_read_b128 v[162:165], v217 offset:53248
	ds_read_b128 v[166:169], v217 offset:54272
	ds_read_b128 v[194:197], v217 offset:55296
	ds_read_b128 v[198:201], v217 offset:56320
	global_load_lds_dwordx4 v[176:177], off
	v_lshl_add_u64 v[176:177], v[236:237], 0, s[18:19]
	s_mov_b32 m0, s31
	s_nop 0
	global_load_lds_dwordx4 v[176:177], off
	s_nop 0
	s_add_i32 s27, s44, s84
	v_lshl_add_u64 v[238:239], v[238:239], 0, s[18:19]
	s_mov_b32 m0, s27
	s_nop 0
	global_load_lds_dwordx4 v[238:239], off
	v_lshl_add_u64 v[240:241], v[240:241], 0, s[18:19]
	s_add_i32 m0, s27, 0x2000
	s_nop 0
	global_load_lds_dwordx4 v[240:241], off
	s_waitcnt lgkmcnt(0)
	s_waitcnt vmcnt(8)
	s_barrier
	v_mfma_f32_16x16x32_bf16 v[60:63], v[128:131], v[146:149], v[60:63]
	v_mfma_f32_16x16x32_bf16 v[56:59], v[136:139], v[146:149], v[56:59]
	v_mfma_f32_16x16x32_bf16 v[44:47], v[128:131], v[154:157], v[44:47]
	v_mfma_f32_16x16x32_bf16 v[40:43], v[136:139], v[154:157], v[40:43]
	v_mfma_f32_16x16x32_bf16 v[28:31], v[128:131], v[162:165], v[28:31]
	v_mfma_f32_16x16x32_bf16 v[24:27], v[136:139], v[162:165], v[24:27]
	v_mfma_f32_16x16x32_bf16 v[12:15], v[128:131], v[194:197], v[12:15]
	v_mfma_f32_16x16x32_bf16 v[8:11], v[136:139], v[194:197], v[8:11]
	v_mfma_f32_16x16x32_bf16 v[60:63], v[132:135], v[150:153], v[60:63]
	v_mfma_f32_16x16x32_bf16 v[56:59], v[140:143], v[150:153], v[56:59]
	v_mfma_f32_16x16x32_bf16 v[44:47], v[132:135], v[158:161], v[44:47]
	v_mfma_f32_16x16x32_bf16 v[40:43], v[140:143], v[158:161], v[40:43]
	v_mfma_f32_16x16x32_bf16 v[28:31], v[132:135], v[166:169], v[28:31]
	v_mfma_f32_16x16x32_bf16 v[24:27], v[140:143], v[166:169], v[24:27]
	v_mfma_f32_16x16x32_bf16 v[12:15], v[132:135], v[198:201], v[12:15]
	v_mfma_f32_16x16x32_bf16 v[8:11], v[140:143], v[198:201], v[8:11]
	v_mfma_f32_16x16x32_bf16 v[52:55], v[202:205], v[146:149], v[52:55]
	v_mfma_f32_16x16x32_bf16 v[48:51], v[222:225], v[146:149], v[48:51]
	v_mfma_f32_16x16x32_bf16 v[36:39], v[202:205], v[154:157], v[36:39]
	v_mfma_f32_16x16x32_bf16 v[32:35], v[222:225], v[154:157], v[32:35]
	v_mfma_f32_16x16x32_bf16 v[20:23], v[202:205], v[162:165], v[20:23]
	v_mfma_f32_16x16x32_bf16 v[16:19], v[222:225], v[162:165], v[16:19]
	v_mfma_f32_16x16x32_bf16 v[4:7], v[202:205], v[194:197], v[4:7]
	v_mfma_f32_16x16x32_bf16 v[0:3], v[222:225], v[194:197], v[0:3]
	v_mfma_f32_16x16x32_bf16 v[52:55], v[218:221], v[150:153], v[52:55]
	v_mfma_f32_16x16x32_bf16 v[48:51], v[228:231], v[150:153], v[48:51]
	v_mfma_f32_16x16x32_bf16 v[36:39], v[218:221], v[158:161], v[36:39]
	v_mfma_f32_16x16x32_bf16 v[32:35], v[228:231], v[158:161], v[32:35]
	v_mfma_f32_16x16x32_bf16 v[20:23], v[218:221], v[166:169], v[20:23]
	v_mfma_f32_16x16x32_bf16 v[16:19], v[228:231], v[166:169], v[16:19]
	v_mfma_f32_16x16x32_bf16 v[4:7], v[218:221], v[198:201], v[4:7]
	v_mfma_f32_16x16x32_bf16 v[0:3], v[228:231], v[198:201], v[0:3]
	s_barrier
	s_add_u32 s42, s42, 0x100
	s_addc_u32 s43, s43, 0
	s_add_u32 s33, s33, 0x100
	s_addc_u32 s37, s37, 0
	s_cmp_ge_u32 s56, s34
	s_mov_b32 s27, s56
.LBB0_196:
	s_add_i32 s56, s27, 2
	s_add_u32 s44, s42, 0x80
	s_addc_u32 s45, s43, 0
	s_add_i32 s57, 0, 0x10000
	ds_read_b128 v[128:131], v207
	ds_read_b128 v[132:135], v207 offset:1024
	ds_read_b128 v[136:139], v207 offset:2048
	ds_read_b128 v[140:143], v207 offset:3072
	s_cmp_eq_u32 s82, s27
	s_cselect_b32 s45, s77, s45
	s_cselect_b32 s44, s76, s44
	s_cselect_b32 s79, s1, s37
	s_cselect_b32 s78, s0, s33
	v_lshl_add_u64 v[176:177], s[42:43], 0, v[190:191]
	s_add_i32 m0, s85, 0xc000
	ds_read_b128 v[146:149], v217
	ds_read_b128 v[150:153], v217 offset:1024
	ds_read_b128 v[154:157], v217 offset:2048
	ds_read_b128 v[158:161], v217 offset:3072
	ds_read_b128 v[162:165], v217 offset:4096
	ds_read_b128 v[166:169], v217 offset:5120
	ds_read_b128 v[194:197], v217 offset:6144
	ds_read_b128 v[198:201], v217 offset:7168
	s_waitcnt lgkmcnt(8)
	ds_read_b128 v[202:205], v207 offset:16384
	ds_read_b128 v[218:221], v207 offset:17408
	ds_read_b128 v[222:225], v207 offset:18432
	ds_read_b128 v[228:231], v207 offset:19456
	global_load_lds_dwordx4 v[176:177], off
	v_lshl_add_u64 v[176:177], s[42:43], 0, v[192:193]
	s_add_i32 m0, s85, 0xe000
	s_nop 0
	global_load_lds_dwordx4 v[176:177], off
	s_waitcnt lgkmcnt(0)
	s_waitcnt vmcnt(8)
	s_barrier
	v_mfma_f32_16x16x32_bf16 v[124:127], v[128:131], v[146:149], v[124:127]
	v_mfma_f32_16x16x32_bf16 v[120:123], v[136:139], v[146:149], v[120:123]
	v_mfma_f32_16x16x32_bf16 v[108:111], v[128:131], v[154:157], v[108:111]
	v_mfma_f32_16x16x32_bf16 v[104:107], v[136:139], v[154:157], v[104:107]
	v_mfma_f32_16x16x32_bf16 v[92:95], v[128:131], v[162:165], v[92:95]
	v_mfma_f32_16x16x32_bf16 v[88:91], v[136:139], v[162:165], v[88:91]
	v_mfma_f32_16x16x32_bf16 v[76:79], v[128:131], v[194:197], v[76:79]
	v_mfma_f32_16x16x32_bf16 v[72:75], v[136:139], v[194:197], v[72:75]
	v_mfma_f32_16x16x32_bf16 v[124:127], v[132:135], v[150:153], v[124:127]
	v_mfma_f32_16x16x32_bf16 v[120:123], v[140:143], v[150:153], v[120:123]
	v_mfma_f32_16x16x32_bf16 v[108:111], v[132:135], v[158:161], v[108:111]
	v_mfma_f32_16x16x32_bf16 v[104:107], v[140:143], v[158:161], v[104:107]
	v_mfma_f32_16x16x32_bf16 v[92:95], v[132:135], v[166:169], v[92:95]
	v_mfma_f32_16x16x32_bf16 v[88:91], v[140:143], v[166:169], v[88:91]
	v_mfma_f32_16x16x32_bf16 v[76:79], v[132:135], v[198:201], v[76:79]
	v_mfma_f32_16x16x32_bf16 v[72:75], v[140:143], v[198:201], v[72:75]
	v_mfma_f32_16x16x32_bf16 v[116:119], v[202:205], v[146:149], v[116:119]
	v_mfma_f32_16x16x32_bf16 v[112:115], v[222:225], v[146:149], v[112:115]
	v_mfma_f32_16x16x32_bf16 v[100:103], v[202:205], v[154:157], v[100:103]
	v_mfma_f32_16x16x32_bf16 v[96:99], v[222:225], v[154:157], v[96:99]
	v_mfma_f32_16x16x32_bf16 v[84:87], v[202:205], v[162:165], v[84:87]
	v_mfma_f32_16x16x32_bf16 v[80:83], v[222:225], v[162:165], v[80:83]
	v_mfma_f32_16x16x32_bf16 v[68:71], v[202:205], v[194:197], v[68:71]
	v_mfma_f32_16x16x32_bf16 v[64:67], v[222:225], v[194:197], v[64:67]
	v_mfma_f32_16x16x32_bf16 v[116:119], v[218:221], v[150:153], v[116:119]
	v_mfma_f32_16x16x32_bf16 v[112:115], v[228:231], v[150:153], v[112:115]
	v_mfma_f32_16x16x32_bf16 v[100:103], v[218:221], v[158:161], v[100:103]
	v_mfma_f32_16x16x32_bf16 v[96:99], v[228:231], v[158:161], v[96:99]
	v_mfma_f32_16x16x32_bf16 v[84:87], v[218:221], v[166:169], v[84:87]
	v_mfma_f32_16x16x32_bf16 v[80:83], v[228:231], v[166:169], v[80:83]
	v_mfma_f32_16x16x32_bf16 v[68:71], v[218:221], v[198:201], v[68:71]
	v_mfma_f32_16x16x32_bf16 v[64:67], v[228:231], v[198:201], v[64:67]
	s_barrier
	s_add_i32 s27, 0, 0x14000
	s_add_i32 s57, s57, s84
	v_lshl_add_u64 v[176:177], s[78:79], 0, v[144:145]
	s_mov_b32 m0, s57
	v_lshl_add_u64 v[232:233], s[78:79], 0, v[188:189]
	global_load_lds_dwordx4 v[176:177], off
	s_add_i32 m0, s57, 0x2000
	s_nop 0
	global_load_lds_dwordx4 v[232:233], off
	s_mov_b32 m0, s85
	v_lshl_add_u64 v[234:235], s[44:45], 0, v[144:145]
	ds_read_b128 v[146:149], v217 offset:16384
	ds_read_b128 v[150:153], v217 offset:17408
	ds_read_b128 v[154:157], v217 offset:18432
	ds_read_b128 v[158:161], v217 offset:19456
	ds_read_b128 v[162:165], v217 offset:20480
	ds_read_b128 v[166:169], v217 offset:21504
	ds_read_b128 v[194:197], v217 offset:22528
	ds_read_b128 v[198:201], v217 offset:23552
	global_load_lds_dwordx4 v[234:235], off
	v_lshl_add_u64 v[236:237], s[44:45], 0, v[188:189]
	s_mov_b32 m0, s86
	s_nop 0
	global_load_lds_dwordx4 v[236:237], off
	s_add_u32 s58, s78, s98
	s_addc_u32 s59, s79, 0
	s_add_i32 s27, s27, s84
	v_lshl_add_u64 v[238:239], s[58:59], 0, v[144:145]
	s_mov_b32 m0, s27
	v_lshl_add_u64 v[240:241], s[58:59], 0, v[188:189]
	global_load_lds_dwordx4 v[238:239], off
	s_add_i32 m0, s27, 0x2000
	s_nop 0
	global_load_lds_dwordx4 v[240:241], off
	s_waitcnt lgkmcnt(0)
	s_waitcnt vmcnt(8)
	s_barrier
	v_mfma_f32_16x16x32_bf16 v[60:63], v[128:131], v[146:149], v[60:63]
	v_mfma_f32_16x16x32_bf16 v[56:59], v[136:139], v[146:149], v[56:59]
	v_mfma_f32_16x16x32_bf16 v[44:47], v[128:131], v[154:157], v[44:47]
	v_mfma_f32_16x16x32_bf16 v[40:43], v[136:139], v[154:157], v[40:43]
	v_mfma_f32_16x16x32_bf16 v[28:31], v[128:131], v[162:165], v[28:31]
	v_mfma_f32_16x16x32_bf16 v[24:27], v[136:139], v[162:165], v[24:27]
	v_mfma_f32_16x16x32_bf16 v[12:15], v[128:131], v[194:197], v[12:15]
	v_mfma_f32_16x16x32_bf16 v[8:11], v[136:139], v[194:197], v[8:11]
	v_mfma_f32_16x16x32_bf16 v[60:63], v[132:135], v[150:153], v[60:63]
	v_mfma_f32_16x16x32_bf16 v[56:59], v[140:143], v[150:153], v[56:59]
	v_mfma_f32_16x16x32_bf16 v[44:47], v[132:135], v[158:161], v[44:47]
	v_mfma_f32_16x16x32_bf16 v[40:43], v[140:143], v[158:161], v[40:43]
	v_mfma_f32_16x16x32_bf16 v[28:31], v[132:135], v[166:169], v[28:31]
	v_mfma_f32_16x16x32_bf16 v[24:27], v[140:143], v[166:169], v[24:27]
	v_mfma_f32_16x16x32_bf16 v[12:15], v[132:135], v[198:201], v[12:15]
	v_mfma_f32_16x16x32_bf16 v[8:11], v[140:143], v[198:201], v[8:11]
	v_mfma_f32_16x16x32_bf16 v[52:55], v[202:205], v[146:149], v[52:55]
	v_mfma_f32_16x16x32_bf16 v[48:51], v[222:225], v[146:149], v[48:51]
	v_mfma_f32_16x16x32_bf16 v[36:39], v[202:205], v[154:157], v[36:39]
	v_mfma_f32_16x16x32_bf16 v[32:35], v[222:225], v[154:157], v[32:35]
	v_mfma_f32_16x16x32_bf16 v[20:23], v[202:205], v[162:165], v[20:23]
	v_mfma_f32_16x16x32_bf16 v[16:19], v[222:225], v[162:165], v[16:19]
	v_mfma_f32_16x16x32_bf16 v[4:7], v[202:205], v[194:197], v[4:7]
	v_mfma_f32_16x16x32_bf16 v[0:3], v[222:225], v[194:197], v[0:3]
	v_mfma_f32_16x16x32_bf16 v[52:55], v[218:221], v[150:153], v[52:55]
	v_mfma_f32_16x16x32_bf16 v[48:51], v[228:231], v[150:153], v[48:51]
	v_mfma_f32_16x16x32_bf16 v[36:39], v[218:221], v[158:161], v[36:39]
	v_mfma_f32_16x16x32_bf16 v[32:35], v[228:231], v[158:161], v[32:35]
	v_mfma_f32_16x16x32_bf16 v[20:23], v[218:221], v[166:169], v[20:23]
	v_mfma_f32_16x16x32_bf16 v[16:19], v[228:231], v[166:169], v[16:19]
	v_mfma_f32_16x16x32_bf16 v[4:7], v[218:221], v[198:201], v[4:7]
	v_mfma_f32_16x16x32_bf16 v[0:3], v[228:231], v[198:201], v[0:3]
	s_barrier
	s_nop 0
	s_add_i32 s27, 0, 0x18000
	ds_read_b128 v[128:131], v207 offset:32768
	ds_read_b128 v[132:135], v207 offset:33792
	ds_read_b128 v[136:139], v207 offset:34816
	ds_read_b128 v[140:143], v207 offset:35840
	s_add_u32 s44, s44, s98
	s_addc_u32 s45, s45, 0
	s_mov_b32 m0, s87
	ds_read_b128 v[146:149], v217 offset:32768
	ds_read_b128 v[150:153], v217 offset:33792
	ds_read_b128 v[154:157], v217 offset:34816
	ds_read_b128 v[158:161], v217 offset:35840
	ds_read_b128 v[162:165], v217 offset:36864
	ds_read_b128 v[166:169], v217 offset:37888
	ds_read_b128 v[194:197], v217 offset:38912
	ds_read_b128 v[198:201], v217 offset:39936
	s_waitcnt lgkmcnt(8)
	ds_read_b128 v[202:205], v207 offset:49152
	ds_read_b128 v[218:221], v207 offset:50176
	ds_read_b128 v[222:225], v207 offset:51200
	ds_read_b128 v[228:231], v207 offset:52224
	global_load_lds_dwordx4 v144, s[44:45]
	s_mov_b32 m0, s80
	s_nop 0
	global_load_lds_dwordx4 v188, s[44:45]
	s_waitcnt lgkmcnt(0)
	s_waitcnt vmcnt(8)
	s_barrier
	v_mfma_f32_16x16x32_bf16 v[124:127], v[128:131], v[146:149], v[124:127]
	v_mfma_f32_16x16x32_bf16 v[120:123], v[136:139], v[146:149], v[120:123]
	v_mfma_f32_16x16x32_bf16 v[108:111], v[128:131], v[154:157], v[108:111]
	v_mfma_f32_16x16x32_bf16 v[104:107], v[136:139], v[154:157], v[104:107]
	v_mfma_f32_16x16x32_bf16 v[92:95], v[128:131], v[162:165], v[92:95]
	v_mfma_f32_16x16x32_bf16 v[88:91], v[136:139], v[162:165], v[88:91]
	v_mfma_f32_16x16x32_bf16 v[76:79], v[128:131], v[194:197], v[76:79]
	v_mfma_f32_16x16x32_bf16 v[72:75], v[136:139], v[194:197], v[72:75]
	v_mfma_f32_16x16x32_bf16 v[124:127], v[132:135], v[150:153], v[124:127]
	v_mfma_f32_16x16x32_bf16 v[120:123], v[140:143], v[150:153], v[120:123]
	v_mfma_f32_16x16x32_bf16 v[108:111], v[132:135], v[158:161], v[108:111]
	v_mfma_f32_16x16x32_bf16 v[104:107], v[140:143], v[158:161], v[104:107]
	v_mfma_f32_16x16x32_bf16 v[92:95], v[132:135], v[166:169], v[92:95]
	v_mfma_f32_16x16x32_bf16 v[88:91], v[140:143], v[166:169], v[88:91]
	v_mfma_f32_16x16x32_bf16 v[76:79], v[132:135], v[198:201], v[76:79]
	v_mfma_f32_16x16x32_bf16 v[72:75], v[140:143], v[198:201], v[72:75]
	v_mfma_f32_16x16x32_bf16 v[116:119], v[202:205], v[146:149], v[116:119]
	v_mfma_f32_16x16x32_bf16 v[112:115], v[222:225], v[146:149], v[112:115]
	v_mfma_f32_16x16x32_bf16 v[100:103], v[202:205], v[154:157], v[100:103]
	v_mfma_f32_16x16x32_bf16 v[96:99], v[222:225], v[154:157], v[96:99]
	v_mfma_f32_16x16x32_bf16 v[84:87], v[202:205], v[162:165], v[84:87]
	v_mfma_f32_16x16x32_bf16 v[80:83], v[222:225], v[162:165], v[80:83]
	v_mfma_f32_16x16x32_bf16 v[68:71], v[202:205], v[194:197], v[68:71]
	v_mfma_f32_16x16x32_bf16 v[64:67], v[222:225], v[194:197], v[64:67]
	v_mfma_f32_16x16x32_bf16 v[116:119], v[218:221], v[150:153], v[116:119]
	v_mfma_f32_16x16x32_bf16 v[112:115], v[228:231], v[150:153], v[112:115]
	v_mfma_f32_16x16x32_bf16 v[100:103], v[218:221], v[158:161], v[100:103]
	v_mfma_f32_16x16x32_bf16 v[96:99], v[228:231], v[158:161], v[96:99]
	v_mfma_f32_16x16x32_bf16 v[84:87], v[218:221], v[166:169], v[84:87]
	v_mfma_f32_16x16x32_bf16 v[80:83], v[228:231], v[166:169], v[80:83]
	v_mfma_f32_16x16x32_bf16 v[68:71], v[218:221], v[198:201], v[68:71]
	v_mfma_f32_16x16x32_bf16 v[64:67], v[228:231], v[198:201], v[64:67]
	s_barrier
	s_add_i32 s44, 0, 0x1c000
	s_add_i32 s27, s27, s84
	v_lshl_add_u64 v[176:177], v[176:177], 0, s[18:19]
	s_mov_b32 m0, s27
	s_nop 0
	global_load_lds_dwordx4 v[176:177], off
	v_lshl_add_u64 v[176:177], v[232:233], 0, s[18:19]
	s_add_i32 m0, s27, 0x2000
	s_nop 0
	global_load_lds_dwordx4 v[176:177], off
	s_mov_b32 m0, s30
	v_lshl_add_u64 v[176:177], v[234:235], 0, s[18:19]
	ds_read_b128 v[146:149], v217 offset:49152
	ds_read_b128 v[150:153], v217 offset:50176
	ds_read_b128 v[154:157], v217 offset:51200
	ds_read_b128 v[158:161], v217 offset:52224
	ds_read_b128 v[162:165], v217 offset:53248
	ds_read_b128 v[166:169], v217 offset:54272
	ds_read_b128 v[194:197], v217 offset:55296
	ds_read_b128 v[198:201], v217 offset:56320
	global_load_lds_dwordx4 v[176:177], off
	v_lshl_add_u64 v[176:177], v[236:237], 0, s[18:19]
	s_mov_b32 m0, s31
	s_nop 0
	global_load_lds_dwordx4 v[176:177], off
	s_nop 0
	s_add_i32 s27, s44, s84
	v_lshl_add_u64 v[238:239], v[238:239], 0, s[18:19]
	s_mov_b32 m0, s27
	s_nop 0
	global_load_lds_dwordx4 v[238:239], off
	v_lshl_add_u64 v[240:241], v[240:241], 0, s[18:19]
	s_add_i32 m0, s27, 0x2000
	s_nop 0
	global_load_lds_dwordx4 v[240:241], off
	s_waitcnt lgkmcnt(0)
	s_waitcnt vmcnt(8)
	s_barrier
	v_mfma_f32_16x16x32_bf16 v[60:63], v[128:131], v[146:149], v[60:63]
	v_mfma_f32_16x16x32_bf16 v[56:59], v[136:139], v[146:149], v[56:59]
	v_mfma_f32_16x16x32_bf16 v[44:47], v[128:131], v[154:157], v[44:47]
	v_mfma_f32_16x16x32_bf16 v[40:43], v[136:139], v[154:157], v[40:43]
	v_mfma_f32_16x16x32_bf16 v[28:31], v[128:131], v[162:165], v[28:31]
	v_mfma_f32_16x16x32_bf16 v[24:27], v[136:139], v[162:165], v[24:27]
	v_mfma_f32_16x16x32_bf16 v[12:15], v[128:131], v[194:197], v[12:15]
	v_mfma_f32_16x16x32_bf16 v[8:11], v[136:139], v[194:197], v[8:11]
	v_mfma_f32_16x16x32_bf16 v[60:63], v[132:135], v[150:153], v[60:63]
	v_mfma_f32_16x16x32_bf16 v[56:59], v[140:143], v[150:153], v[56:59]
	v_mfma_f32_16x16x32_bf16 v[44:47], v[132:135], v[158:161], v[44:47]
	v_mfma_f32_16x16x32_bf16 v[40:43], v[140:143], v[158:161], v[40:43]
	v_mfma_f32_16x16x32_bf16 v[28:31], v[132:135], v[166:169], v[28:31]
	v_mfma_f32_16x16x32_bf16 v[24:27], v[140:143], v[166:169], v[24:27]
	v_mfma_f32_16x16x32_bf16 v[12:15], v[132:135], v[198:201], v[12:15]
	v_mfma_f32_16x16x32_bf16 v[8:11], v[140:143], v[198:201], v[8:11]
	v_mfma_f32_16x16x32_bf16 v[52:55], v[202:205], v[146:149], v[52:55]
	v_mfma_f32_16x16x32_bf16 v[48:51], v[222:225], v[146:149], v[48:51]
	v_mfma_f32_16x16x32_bf16 v[36:39], v[202:205], v[154:157], v[36:39]
	v_mfma_f32_16x16x32_bf16 v[32:35], v[222:225], v[154:157], v[32:35]
	v_mfma_f32_16x16x32_bf16 v[20:23], v[202:205], v[162:165], v[20:23]
	v_mfma_f32_16x16x32_bf16 v[16:19], v[222:225], v[162:165], v[16:19]
	v_mfma_f32_16x16x32_bf16 v[4:7], v[202:205], v[194:197], v[4:7]
	v_mfma_f32_16x16x32_bf16 v[0:3], v[222:225], v[194:197], v[0:3]
	v_mfma_f32_16x16x32_bf16 v[52:55], v[218:221], v[150:153], v[52:55]
	v_mfma_f32_16x16x32_bf16 v[48:51], v[228:231], v[150:153], v[48:51]
	v_mfma_f32_16x16x32_bf16 v[36:39], v[218:221], v[158:161], v[36:39]
	v_mfma_f32_16x16x32_bf16 v[32:35], v[228:231], v[158:161], v[32:35]
	v_mfma_f32_16x16x32_bf16 v[20:23], v[218:221], v[166:169], v[20:23]
	v_mfma_f32_16x16x32_bf16 v[16:19], v[228:231], v[166:169], v[16:19]
	v_mfma_f32_16x16x32_bf16 v[4:7], v[218:221], v[198:201], v[4:7]
	v_mfma_f32_16x16x32_bf16 v[0:3], v[228:231], v[198:201], v[0:3]
	s_barrier
	s_add_u32 s42, s42, 0x100
	s_addc_u32 s43, s43, 0
	s_add_u32 s33, s33, 0x100
	s_addc_u32 s37, s37, 0
	s_cmp_ge_u32 s56, s34
	s_mov_b32 s27, s56
	s_cbranch_scc0 .LBB0_196
	v_lshl_add_u32 v194, s11, 8, v206
	v_ashrrev_i32_e32 v195, 31, v194
	v_lshl_or_b32 v196, s10, 8, v216
	v_lshlrev_b64 v[128:129], 11, v[194:195]
	v_ashrrev_i32_e32 v197, 31, v196
	s_and_b64 vcc, exec, s[92:93]
	v_or_b32_e32 v198, 16, v194
	v_lshl_add_u64 v[200:201], s[54:55], 0, v[128:129]
	s_cbranch_vccz .LBB0_215
	v_lshlrev_b64 v[128:129], 12, v[194:195]
	v_lshl_add_u64 v[128:129], s[50:51], 0, v[128:129]
	v_lshlrev_b64 v[130:131], 2, v[196:197]
	v_lshl_add_u64 v[128:129], v[128:129], 0, v[130:131]
	global_load_dwordx4 v[146:149], v[128:129], off offset:16
	global_load_dwordx4 v[150:153], v[128:129], off
	global_load_dwordx4 v[154:157], v[128:129], off offset:528
	global_load_dwordx4 v[158:161], v[128:129], off offset:512
	v_ashrrev_i32_e32 v199, 31, v198
	v_lshlrev_b64 v[128:129], 12, v[198:199]
	v_lshl_add_u64 v[128:129], s[50:51], 0, v[128:129]
	v_lshl_add_u64 v[132:133], v[128:129], 0, v[130:131]
	global_load_dwordx4 v[136:139], v[132:133], off offset:16
	global_load_dwordx4 v[140:143], v[132:133], off
	global_load_dwordx4 v[128:131], v[132:133], off offset:528
	s_nop 0
	global_load_dwordx4 v[132:135], v[132:133], off offset:512
	v_lshl_add_u64 v[166:167], v[196:197], 1, v[200:201]
	s_waitcnt vmcnt(0)
	v_pk_add_f32 v[164:165], v[120:121], v[146:147]
	v_pk_add_f32 v[152:153], v[126:127], v[152:153]
	v_pk_add_f32 v[150:151], v[124:125], v[150:151]
	v_pk_add_f32 v[162:163], v[122:123], v[148:149]
	v_cvt_pk_bf16_f32 v146, v150, v151
	v_cvt_pk_bf16_f32 v147, v152, v153
	v_cvt_pk_bf16_f32 v148, v164, v165
	v_pk_add_f32 v[156:157], v[114:115], v[156:157]
	v_cvt_pk_bf16_f32 v149, v162, v163
	global_store_dwordx4 v[166:167], v[146:149], off
	v_pk_add_f32 v[154:155], v[112:113], v[154:155]
	s_nop 0
	v_mul_f32_e32 v146, v151, v151
	v_mul_f32_e32 v147, v153, v153
	v_fmac_f32_e32 v146, v150, v150
	v_fmac_f32_e32 v147, v152, v152
	v_add_f32_e32 v146, v146, v147
	v_mul_f32_e32 v147, v165, v165
	v_mul_f32_e32 v148, v163, v163
	v_fmac_f32_e32 v147, v164, v164
	v_fmac_f32_e32 v148, v162, v162
	v_add_f32_e32 v147, v147, v148
	v_add_f32_e32 v162, v146, v147
	v_pk_add_f32 v[150:151], v[118:119], v[160:161]
	v_pk_add_f32 v[152:153], v[116:117], v[158:159]
	s_nop 0
	v_cvt_pk_bf16_f32 v146, v152, v153
	v_cvt_pk_bf16_f32 v147, v150, v151
	v_cvt_pk_bf16_f32 v148, v154, v155
	v_cvt_pk_bf16_f32 v149, v156, v157
	global_store_dwordx4 v[166:167], v[146:149], off offset:256
	s_nop 1
	v_mul_f32_e32 v146, v153, v153
	v_mul_f32_e32 v147, v151, v151
	v_fmac_f32_e32 v146, v152, v152
	v_fmac_f32_e32 v147, v150, v150
	v_add_f32_e32 v146, v146, v147
	v_mul_f32_e32 v147, v155, v155
	v_mul_f32_e32 v148, v157, v157
	v_fmac_f32_e32 v147, v154, v154
	v_fmac_f32_e32 v148, v156, v156
	v_add_f32_e32 v147, v147, v148
	v_and_b32_e32 v148, 64, v214
	v_add_f32_e32 v146, v146, v147
	v_xor_b32_e32 v147, 16, v214
	v_add_u32_e32 v148, 64, v148
	v_cmp_lt_i32_e32 vcc, v147, v148
	v_add_f32_e32 v146, v162, v146
	s_nop 0
	v_cndmask_b32_e32 v147, v214, v147, vcc
	v_lshlrev_b32_e32 v218, 2, v147
	ds_bpermute_b32 v147, v218, v146
	s_waitcnt lgkmcnt(0)
	v_add_f32_e32 v146, v146, v147
	v_xor_b32_e32 v147, 32, v214
	v_cmp_lt_i32_e32 vcc, v147, v148
	s_nop 1
	v_cndmask_b32_e32 v147, v214, v147, vcc
	v_lshlrev_b32_e32 v219, 2, v147
	ds_bpermute_b32 v147, v219, v146
	s_and_saveexec_b64 s[42:43], s[38:39]
	s_cbranch_execz .LBB0_200
	s_waitcnt lgkmcnt(0)
	v_add_f32_e32 v146, v146, v147
	v_fma_f32 v146, v146, s91, 0.5
	v_trunc_f32_e32 v146, v146
	v_mul_f32_e32 v147, 0x2f800000, v146
	v_floor_f32_e32 v147, v147
	v_fmac_f32_e32 v146, 0xcf800000, v147
	v_cvt_u32_f32_e32 v146, v146
	v_cvt_u32_f32_e32 v147, v147
	v_lshl_add_u64 v[148:149], v[194:195], 3, s[52:53]
	global_atomic_add_x2 v[148:149], v[146:147], off

.LBB0_321:
	v_readlane_b32 s1, v252, 32
	s_add_u32 s1, s1, s27
	v_readlane_b32 s8, v252, 33
	s_addc_u32 s10, s8, s10
	v_writelane_b32 v254, s36, 58
	s_lshl_b64 s[30:31], s[36:37], 22
	s_sub_u32 s27, 0, s30
	v_writelane_b32 v254, s37, 59
	s_subb_u32 s33, 0, s31
	s_add_u32 s96, s1, s27
	v_readlane_b32 s8, v254, 52
	s_addc_u32 s97, s10, s33
	s_lshl_b32 s30, s8, 6
	s_and_b32 s1, s25, 3
	s_add_i32 m0, s83, 0x18000
	v_lshl_add_u64 v[6:7], v[6:7], 0, s[18:19]
	s_ashr_i32 s31, s30, 31
	s_lshl_b32 s25, s11, 13
	s_lshl_b32 s36, s1, 12
	s_waitcnt vmcnt(2)
	s_barrier
	global_load_lds_dwordx4 v[6:7], off
	v_lshl_add_u64 v[4:5], v[4:5], 0, s[18:19]
	s_add_i32 m0, s83, 0x1a000
	s_add_i32 s87, s83, 0x8000
	s_add_i32 s79, s83, 0xa000
	global_load_lds_dwordx4 v[4:5], off
	v_lshl_add_u64 v[2:3], v[2:3], 0, s[18:19]
	s_mov_b32 m0, s87
	s_add_u32 s34, s72, 0x40080
	global_load_lds_dwordx4 v[2:3], off
	v_lshl_add_u64 v[0:1], v[0:1], 0, s[18:19]
	s_mov_b32 m0, s79
	s_addc_u32 s35, s73, 0
	global_load_lds_dwordx4 v[0:1], off
	s_add_i32 m0, s83, 0x1c000
	v_lshl_add_u64 v[0:1], s[34:35], 0, v[148:149]
	global_load_lds_dwordx4 v[0:1], off
	v_lshl_add_u64 v[0:1], s[34:35], 0, v[146:147]
	s_add_i32 m0, s83, 0x1e000
	v_readlane_b32 s9, v254, 53
	global_load_lds_dwordx4 v[0:1], off
	v_lshrrev_b32_e32 v0, 1, v9
	v_and_b32_e32 v0, 24, v0
	v_and_b32_e32 v1, 15, v9
	v_lshlrev_b32_e32 v2, 1, v0
	v_lshl_or_b32 v151, s11, 6, v1
	v_lshl_or_b32 v1, v1, 6, v2
	v_lshlrev_b32_e32 v2, 2, v9
	v_and_b32_e32 v2, 32, v2
	v_bitop3_b32 v3, v1, s25, v2 bitop3:0xde
	v_bitop3_b32 v216, v1, s36, v2 bitop3:0xde
	v_add_u32_e32 v216, 0x10000, v216
	v_lshlrev_b32_e32 v1, 14, v12
	v_and_b32_e32 v1, 0xffff8000, v1
	v_lshl_or_b32 v150, s1, 6, v0
	v_writelane_b32 v254, s22, 60
	s_add_u32 s1, s22, s27
	v_lshl_add_u32 v1, v13, 11, v1
	v_and_b32_e32 v2, 1, v12
	v_writelane_b32 v254, s1, 52
	v_lshl_or_b32 v1, v2, 6, v1
	v_readlane_b32 s1, v254, 54
	v_lshl_add_u32 v152, v14, 1, v1
	v_lshlrev_b32_e32 v1, 14, v8
	s_addc_u32 s1, s1, s33
	v_and_b32_e32 v1, 0xffff8000, v1
	s_waitcnt vmcnt(6)
	v_writelane_b32 v254, s1, 61
	v_lshl_add_u32 v1, v10, 11, v1
	v_and_b32_e32 v2, 1, v8
	s_lshl_b64 s[8:9], s[30:31], 2
	v_lshl_or_b32 v1, v2, 6, v1
	v_writelane_b32 v254, s8, 62
	s_sext_i32_i8 s10, s38
	v_mov_b32_e32 v153, v145
	v_lshl_add_u32 v154, v11, 1, v1
	v_mov_b32_e32 v155, v145
	s_mov_b32 s22, 0
	v_add_u32_e32 v217, 0, v3
	v_writelane_b32 v254, s9, 63
	v_lshlrev_b32_e32 v218, 2, v0
	s_barrier
	v_readfirstlane_b32 s101, v208
	s_nop 3
	s_lshr_b32 s101, s101, 8
	s_cmp_eq_u32 s101, 0
	s_cbranch_scc1 .Lprio_a1_done
	s_setprio 1

.LBB0_325:
	s_nop 0
	s_ashr_i32 s93, s92, 31
	s_lshl_b64 s[30:31], s[92:93], 19
	s_add_u32 s94, s54, s30
	v_cmp_lt_i64_e32 vcc, s[50:51], v[186:187]
	s_addc_u32 s95, s55, s31
	s_and_b64 s[30:31], vcc, exec
	s_cselect_b32 s1, s95, s53
	s_cselect_b32 s11, s94, s52
	s_ashr_i32 s9, s8, 31
	s_lshl_b64 s[30:31], s[8:9], 19
	s_add_u32 s28, s80, s30
	s_addc_u32 s29, s78, s31
	s_and_b64 s[30:31], vcc, exec
	s_cselect_b32 s25, s29, s73
	s_cselect_b32 s30, s28, s72
	s_add_u32 s52, s52, 0x40080
	s_addc_u32 s53, s53, 0
	s_add_u32 s31, s72, 0x100
	s_addc_u32 s33, s73, 0
	s_mov_b32 s34, -2
	s_add_u32 s27, s52, 0xfffc0080
	s_addc_u32 s35, s53, -1
	s_add_i32 s36, 0, 0x10000
	ds_read_b128 v[128:131], v216
	ds_read_b128 v[132:135], v216 offset:1024
	ds_read_b128 v[136:139], v216 offset:2048
	ds_read_b128 v[140:143], v216 offset:3072
	s_cmp_eq_u32 s34, 12
	s_cselect_b32 s75, s1, s35
	s_cselect_b32 s74, s11, s27
	s_cselect_b32 s73, s25, s33
	s_cselect_b32 s72, s30, s31
	s_add_i32 m0, s83, 0xc000
	ds_read_b128 v[156:159], v217
	ds_read_b128 v[160:163], v217 offset:1024
	ds_read_b128 v[164:167], v217 offset:2048
	ds_read_b128 v[188:191], v217 offset:3072
	ds_read_b128 v[192:195], v217 offset:4096
	ds_read_b128 v[196:199], v217 offset:5120
	ds_read_b128 v[200:203], v217 offset:6144
	ds_read_b128 v[204:207], v217 offset:7168
	s_waitcnt lgkmcnt(8)
	ds_read_b128 v[220:223], v216 offset:16384
	ds_read_b128 v[228:231], v216 offset:17408
	ds_read_b128 v[232:235], v216 offset:18432
	ds_read_b128 v[236:239], v216 offset:19456
	global_load_lds_dwordx4 v152, s[52:53]
	s_add_i32 m0, s83, 0xe000
	s_nop 0
	global_load_lds_dwordx4 v154, s[52:53]
	s_waitcnt lgkmcnt(0)
	s_waitcnt vmcnt(8)
	s_barrier
	v_mfma_f32_16x16x32_bf16 v[124:127], v[128:131], v[156:159], 0
	v_mfma_f32_16x16x32_bf16 v[120:123], v[136:139], v[156:159], 0
	v_mfma_f32_16x16x32_bf16 v[108:111], v[128:131], v[164:167], 0
	v_mfma_f32_16x16x32_bf16 v[104:107], v[136:139], v[164:167], 0
	v_mfma_f32_16x16x32_bf16 v[92:95], v[128:131], v[192:195], 0
	v_mfma_f32_16x16x32_bf16 v[88:91], v[136:139], v[192:195], 0
	v_mfma_f32_16x16x32_bf16 v[76:79], v[128:131], v[200:203], 0
	v_mfma_f32_16x16x32_bf16 v[72:75], v[136:139], v[200:203], 0
	v_mfma_f32_16x16x32_bf16 v[124:127], v[132:135], v[160:163], v[124:127]
	v_mfma_f32_16x16x32_bf16 v[120:123], v[140:143], v[160:163], v[120:123]
	v_mfma_f32_16x16x32_bf16 v[108:111], v[132:135], v[188:191], v[108:111]
	v_mfma_f32_16x16x32_bf16 v[104:107], v[140:143], v[188:191], v[104:107]
	v_mfma_f32_16x16x32_bf16 v[92:95], v[132:135], v[196:199], v[92:95]
	v_mfma_f32_16x16x32_bf16 v[88:91], v[140:143], v[196:199], v[88:91]
	v_mfma_f32_16x16x32_bf16 v[76:79], v[132:135], v[204:207], v[76:79]
	v_mfma_f32_16x16x32_bf16 v[72:75], v[140:143], v[204:207], v[72:75]
	v_mfma_f32_16x16x32_bf16 v[116:119], v[220:223], v[156:159], 0
	v_mfma_f32_16x16x32_bf16 v[112:115], v[232:235], v[156:159], 0
	v_mfma_f32_16x16x32_bf16 v[100:103], v[220:223], v[164:167], 0
	v_mfma_f32_16x16x32_bf16 v[96:99], v[232:235], v[164:167], 0
	v_mfma_f32_16x16x32_bf16 v[84:87], v[220:223], v[192:195], 0
	v_mfma_f32_16x16x32_bf16 v[80:83], v[232:235], v[192:195], 0
	v_mfma_f32_16x16x32_bf16 v[68:71], v[220:223], v[200:203], 0
	v_mfma_f32_16x16x32_bf16 v[64:67], v[232:235], v[200:203], 0
	v_mfma_f32_16x16x32_bf16 v[116:119], v[228:231], v[160:163], v[116:119]
	v_mfma_f32_16x16x32_bf16 v[112:115], v[236:239], v[160:163], v[112:115]
	v_mfma_f32_16x16x32_bf16 v[100:103], v[228:231], v[188:191], v[100:103]
	v_mfma_f32_16x16x32_bf16 v[96:99], v[236:239], v[188:191], v[96:99]
	v_mfma_f32_16x16x32_bf16 v[84:87], v[228:231], v[196:199], v[84:87]
	v_mfma_f32_16x16x32_bf16 v[80:83], v[236:239], v[196:199], v[80:83]
	v_mfma_f32_16x16x32_bf16 v[68:71], v[228:231], v[204:207], v[68:71]
	v_mfma_f32_16x16x32_bf16 v[64:67], v[236:239], v[204:207], v[64:67]
	s_barrier
	s_add_i32 s27, 0, 0x14000
	s_add_i32 s35, s36, s81
	s_mov_b32 m0, s35
	s_nop 0
	global_load_lds_dwordx4 v148, s[72:73]
	s_add_i32 m0, s35, 0x2000
	s_nop 0
	global_load_lds_dwordx4 v146, s[72:73]
	s_mov_b32 m0, s83
	ds_read_b128 v[156:159], v217 offset:16384
	ds_read_b128 v[160:163], v217 offset:17408
	ds_read_b128 v[164:167], v217 offset:18432
	ds_read_b128 v[188:191], v217 offset:19456
	ds_read_b128 v[192:195], v217 offset:20480
	ds_read_b128 v[196:199], v217 offset:21504
	ds_read_b128 v[200:203], v217 offset:22528
	ds_read_b128 v[204:207], v217 offset:23552
	global_load_lds_dwordx4 v148, s[74:75]
	s_mov_b32 m0, s84
	s_nop 0
	global_load_lds_dwordx4 v146, s[74:75]
	s_add_u32 s36, s72, 0x40000
	s_addc_u32 s37, s73, 0
	s_add_i32 s27, s27, s81
	s_mov_b32 m0, s27
	s_nop 0
	global_load_lds_dwordx4 v148, s[36:37]
	s_add_i32 m0, s27, 0x2000
	s_nop 0
	global_load_lds_dwordx4 v146, s[36:37]
	s_waitcnt lgkmcnt(0)
	s_waitcnt vmcnt(8)
	s_barrier
	v_mfma_f32_16x16x32_bf16 v[60:63], v[128:131], v[156:159], 0
	v_mfma_f32_16x16x32_bf16 v[56:59], v[136:139], v[156:159], 0
	v_mfma_f32_16x16x32_bf16 v[44:47], v[128:131], v[164:167], 0
	v_mfma_f32_16x16x32_bf16 v[40:43], v[136:139], v[164:167], 0
	v_mfma_f32_16x16x32_bf16 v[28:31], v[128:131], v[192:195], 0
	v_mfma_f32_16x16x32_bf16 v[24:27], v[136:139], v[192:195], 0
	v_mfma_f32_16x16x32_bf16 v[12:15], v[128:131], v[200:203], 0
	v_mfma_f32_16x16x32_bf16 v[8:11], v[136:139], v[200:203], 0
	v_mfma_f32_16x16x32_bf16 v[60:63], v[132:135], v[160:163], v[60:63]
	v_mfma_f32_16x16x32_bf16 v[56:59], v[140:143], v[160:163], v[56:59]
	v_mfma_f32_16x16x32_bf16 v[44:47], v[132:135], v[188:191], v[44:47]
	v_mfma_f32_16x16x32_bf16 v[40:43], v[140:143], v[188:191], v[40:43]
	v_mfma_f32_16x16x32_bf16 v[28:31], v[132:135], v[196:199], v[28:31]
	v_mfma_f32_16x16x32_bf16 v[24:27], v[140:143], v[196:199], v[24:27]
	v_mfma_f32_16x16x32_bf16 v[12:15], v[132:135], v[204:207], v[12:15]
	v_mfma_f32_16x16x32_bf16 v[8:11], v[140:143], v[204:207], v[8:11]
	v_mfma_f32_16x16x32_bf16 v[52:55], v[220:223], v[156:159], 0
	v_mfma_f32_16x16x32_bf16 v[48:51], v[232:235], v[156:159], 0
	v_mfma_f32_16x16x32_bf16 v[36:39], v[220:223], v[164:167], 0
	v_mfma_f32_16x16x32_bf16 v[32:35], v[232:235], v[164:167], 0
	v_mfma_f32_16x16x32_bf16 v[20:23], v[220:223], v[192:195], 0
	v_mfma_f32_16x16x32_bf16 v[16:19], v[232:235], v[192:195], 0
	v_mfma_f32_16x16x32_bf16 v[4:7], v[220:223], v[200:203], 0
	v_mfma_f32_16x16x32_bf16 v[0:3], v[232:235], v[200:203], 0
	v_mfma_f32_16x16x32_bf16 v[52:55], v[228:231], v[160:163], v[52:55]
	v_mfma_f32_16x16x32_bf16 v[48:51], v[236:239], v[160:163], v[48:51]
	v_mfma_f32_16x16x32_bf16 v[36:39], v[228:231], v[188:191], v[36:39]
	v_mfma_f32_16x16x32_bf16 v[32:35], v[236:239], v[188:191], v[32:35]
	v_mfma_f32_16x16x32_bf16 v[20:23], v[228:231], v[196:199], v[20:23]
	v_mfma_f32_16x16x32_bf16 v[16:19], v[236:239], v[196:199], v[16:19]
	v_mfma_f32_16x16x32_bf16 v[4:7], v[228:231], v[204:207], v[4:7]
	v_mfma_f32_16x16x32_bf16 v[0:3], v[236:239], v[204:207], v[0:3]
	s_barrier
	s_add_i32 s27, 0, 0x18000
	ds_read_b128 v[128:131], v216 offset:32768
	ds_read_b128 v[132:135], v216 offset:33792
	ds_read_b128 v[136:139], v216 offset:34816
	ds_read_b128 v[140:143], v216 offset:35840
	s_add_u32 s36, s74, 0x40000
	s_addc_u32 s37, s75, 0
	s_mov_b32 m0, s85
	ds_read_b128 v[156:159], v217 offset:32768
	ds_read_b128 v[160:163], v217 offset:33792
	ds_read_b128 v[164:167], v217 offset:34816
	ds_read_b128 v[188:191], v217 offset:35840
	ds_read_b128 v[192:195], v217 offset:36864
	ds_read_b128 v[196:199], v217 offset:37888
	ds_read_b128 v[200:203], v217 offset:38912
	ds_read_b128 v[204:207], v217 offset:39936
	s_waitcnt lgkmcnt(8)
	ds_read_b128 v[220:223], v216 offset:49152
	ds_read_b128 v[228:231], v216 offset:50176
	ds_read_b128 v[232:235], v216 offset:51200
	ds_read_b128 v[236:239], v216 offset:52224
	global_load_lds_dwordx4 v148, s[36:37]
	s_mov_b32 m0, s86
	s_nop 0
	global_load_lds_dwordx4 v146, s[36:37]
	s_waitcnt lgkmcnt(0)
	s_waitcnt vmcnt(8)
	s_barrier
	v_mfma_f32_16x16x32_bf16 v[124:127], v[128:131], v[156:159], v[124:127]
	v_mfma_f32_16x16x32_bf16 v[120:123], v[136:139], v[156:159], v[120:123]
	v_mfma_f32_16x16x32_bf16 v[108:111], v[128:131], v[164:167], v[108:111]
	v_mfma_f32_16x16x32_bf16 v[104:107], v[136:139], v[164:167], v[104:107]
	v_mfma_f32_16x16x32_bf16 v[92:95], v[128:131], v[192:195], v[92:95]
	v_mfma_f32_16x16x32_bf16 v[88:91], v[136:139], v[192:195], v[88:91]
	v_mfma_f32_16x16x32_bf16 v[76:79], v[128:131], v[200:203], v[76:79]
	v_mfma_f32_16x16x32_bf16 v[72:75], v[136:139], v[200:203], v[72:75]
	v_mfma_f32_16x16x32_bf16 v[124:127], v[132:135], v[160:163], v[124:127]
	v_mfma_f32_16x16x32_bf16 v[120:123], v[140:143], v[160:163], v[120:123]
	v_mfma_f32_16x16x32_bf16 v[108:111], v[132:135], v[188:191], v[108:111]
	v_mfma_f32_16x16x32_bf16 v[104:107], v[140:143], v[188:191], v[104:107]
	v_mfma_f32_16x16x32_bf16 v[92:95], v[132:135], v[196:199], v[92:95]
	v_mfma_f32_16x16x32_bf16 v[88:91], v[140:143], v[196:199], v[88:91]
	v_mfma_f32_16x16x32_bf16 v[76:79], v[132:135], v[204:207], v[76:79]
	v_mfma_f32_16x16x32_bf16 v[72:75], v[140:143], v[204:207], v[72:75]
	v_mfma_f32_16x16x32_bf16 v[116:119], v[220:223], v[156:159], v[116:119]
	v_mfma_f32_16x16x32_bf16 v[112:115], v[232:235], v[156:159], v[112:115]
	v_mfma_f32_16x16x32_bf16 v[100:103], v[220:223], v[164:167], v[100:103]
	v_mfma_f32_16x16x32_bf16 v[96:99], v[232:235], v[164:167], v[96:99]
	v_mfma_f32_16x16x32_bf16 v[84:87], v[220:223], v[192:195], v[84:87]
	v_mfma_f32_16x16x32_bf16 v[80:83], v[232:235], v[192:195], v[80:83]
	v_mfma_f32_16x16x32_bf16 v[68:71], v[220:223], v[200:203], v[68:71]
	v_mfma_f32_16x16x32_bf16 v[64:67], v[232:235], v[200:203], v[64:67]
	v_mfma_f32_16x16x32_bf16 v[116:119], v[228:231], v[160:163], v[116:119]
	v_mfma_f32_16x16x32_bf16 v[112:115], v[236:239], v[160:163], v[112:115]
	v_mfma_f32_16x16x32_bf16 v[100:103], v[228:231], v[188:191], v[100:103]
	v_mfma_f32_16x16x32_bf16 v[96:99], v[236:239], v[188:191], v[96:99]
	v_mfma_f32_16x16x32_bf16 v[84:87], v[228:231], v[196:199], v[84:87]
	v_mfma_f32_16x16x32_bf16 v[80:83], v[236:239], v[196:199], v[80:83]
	v_mfma_f32_16x16x32_bf16 v[68:71], v[228:231], v[204:207], v[68:71]
	v_mfma_f32_16x16x32_bf16 v[64:67], v[236:239], v[204:207], v[64:67]
	s_barrier
	s_add_i32 s35, 0, 0x1c000
	s_add_i32 s27, s27, s81
	s_add_u32 s36, s72, s18
	s_addc_u32 s37, s73, s19
	s_mov_b32 m0, s27
	s_nop 0
	global_load_lds_dwordx4 v148, s[36:37]
	s_add_u32 s36, s72, s18
	s_addc_u32 s37, s73, s19
	s_add_i32 m0, s27, 0x2000
	s_nop 0
	global_load_lds_dwordx4 v146, s[36:37]
	s_mov_b32 m0, s87
	s_add_u32 s36, s74, s18
	s_addc_u32 s37, s75, s19
	ds_read_b128 v[156:159], v217 offset:49152
	ds_read_b128 v[160:163], v217 offset:50176
	ds_read_b128 v[164:167], v217 offset:51200
	ds_read_b128 v[188:191], v217 offset:52224
	ds_read_b128 v[192:195], v217 offset:53248
	ds_read_b128 v[196:199], v217 offset:54272
	ds_read_b128 v[200:203], v217 offset:55296
	ds_read_b128 v[204:207], v217 offset:56320
	global_load_lds_dwordx4 v148, s[36:37]
	s_add_u32 s36, s74, s18
	s_addc_u32 s37, s75, s19
	s_mov_b32 m0, s79
	s_nop 0
	global_load_lds_dwordx4 v146, s[36:37]
	s_add_u32 s36, s72, 0x40080
	s_addc_u32 s37, s73, 0
	s_add_i32 s27, s35, s81
	s_mov_b32 m0, s27
	s_nop 0
	global_load_lds_dwordx4 v148, s[36:37]
	s_add_i32 m0, s27, 0x2000
	s_nop 0
	global_load_lds_dwordx4 v146, s[36:37]
	s_waitcnt lgkmcnt(0)
	s_waitcnt vmcnt(8)
	s_barrier
	v_mfma_f32_16x16x32_bf16 v[60:63], v[128:131], v[156:159], v[60:63]
	v_mfma_f32_16x16x32_bf16 v[56:59], v[136:139], v[156:159], v[56:59]
	v_mfma_f32_16x16x32_bf16 v[44:47], v[128:131], v[164:167], v[44:47]
	v_mfma_f32_16x16x32_bf16 v[40:43], v[136:139], v[164:167], v[40:43]
	v_mfma_f32_16x16x32_bf16 v[28:31], v[128:131], v[192:195], v[28:31]
	v_mfma_f32_16x16x32_bf16 v[24:27], v[136:139], v[192:195], v[24:27]
	v_mfma_f32_16x16x32_bf16 v[12:15], v[128:131], v[200:203], v[12:15]
	v_mfma_f32_16x16x32_bf16 v[8:11], v[136:139], v[200:203], v[8:11]
	v_mfma_f32_16x16x32_bf16 v[60:63], v[132:135], v[160:163], v[60:63]
	v_mfma_f32_16x16x32_bf16 v[56:59], v[140:143], v[160:163], v[56:59]
	v_mfma_f32_16x16x32_bf16 v[44:47], v[132:135], v[188:191], v[44:47]
	v_mfma_f32_16x16x32_bf16 v[40:43], v[140:143], v[188:191], v[40:43]
	v_mfma_f32_16x16x32_bf16 v[28:31], v[132:135], v[196:199], v[28:31]
	v_mfma_f32_16x16x32_bf16 v[24:27], v[140:143], v[196:199], v[24:27]
	v_mfma_f32_16x16x32_bf16 v[12:15], v[132:135], v[204:207], v[12:15]
	v_mfma_f32_16x16x32_bf16 v[8:11], v[140:143], v[204:207], v[8:11]
	v_mfma_f32_16x16x32_bf16 v[52:55], v[220:223], v[156:159], v[52:55]
	v_mfma_f32_16x16x32_bf16 v[48:51], v[232:235], v[156:159], v[48:51]
	v_mfma_f32_16x16x32_bf16 v[36:39], v[220:223], v[164:167], v[36:39]
	v_mfma_f32_16x16x32_bf16 v[32:35], v[232:235], v[164:167], v[32:35]
	v_mfma_f32_16x16x32_bf16 v[20:23], v[220:223], v[192:195], v[20:23]
	v_mfma_f32_16x16x32_bf16 v[16:19], v[232:235], v[192:195], v[16:19]
	v_mfma_f32_16x16x32_bf16 v[4:7], v[220:223], v[200:203], v[4:7]
	v_mfma_f32_16x16x32_bf16 v[0:3], v[232:235], v[200:203], v[0:3]
	v_mfma_f32_16x16x32_bf16 v[52:55], v[228:231], v[160:163], v[52:55]
	v_mfma_f32_16x16x32_bf16 v[48:51], v[236:239], v[160:163], v[48:51]
	v_mfma_f32_16x16x32_bf16 v[36:39], v[228:231], v[188:191], v[36:39]
	v_mfma_f32_16x16x32_bf16 v[32:35], v[236:239], v[188:191], v[32:35]
	v_mfma_f32_16x16x32_bf16 v[20:23], v[228:231], v[196:199], v[20:23]
	v_mfma_f32_16x16x32_bf16 v[16:19], v[236:239], v[196:199], v[16:19]
	v_mfma_f32_16x16x32_bf16 v[4:7], v[228:231], v[204:207], v[4:7]
	v_mfma_f32_16x16x32_bf16 v[0:3], v[236:239], v[204:207], v[0:3]
	s_barrier
	s_add_i32 s34, s34, 2
	s_add_u32 s52, s52, 0x100
	s_addc_u32 s53, s53, 0
	s_add_u32 s31, s31, 0x100
	s_addc_u32 s33, s33, 0
	s_cmp_gt_u32 s34, 13
.LBB0_326:
	s_nop 0
	s_add_u32 s27, s52, 0xfffc0080
	s_addc_u32 s35, s53, -1
	s_add_i32 s36, 0, 0x10000
	ds_read_b128 v[128:131], v216
	ds_read_b128 v[132:135], v216 offset:1024
	ds_read_b128 v[136:139], v216 offset:2048
	ds_read_b128 v[140:143], v216 offset:3072
	s_cmp_eq_u32 s34, 12
	s_cselect_b32 s75, s1, s35
	s_cselect_b32 s74, s11, s27
	s_cselect_b32 s73, s25, s33
	s_cselect_b32 s72, s30, s31
	s_add_i32 m0, s83, 0xc000
	ds_read_b128 v[156:159], v217
	ds_read_b128 v[160:163], v217 offset:1024
	ds_read_b128 v[164:167], v217 offset:2048
	ds_read_b128 v[188:191], v217 offset:3072
	ds_read_b128 v[192:195], v217 offset:4096
	ds_read_b128 v[196:199], v217 offset:5120
	ds_read_b128 v[200:203], v217 offset:6144
	ds_read_b128 v[204:207], v217 offset:7168
	s_waitcnt lgkmcnt(8)
	ds_read_b128 v[220:223], v216 offset:16384
	ds_read_b128 v[228:231], v216 offset:17408
	ds_read_b128 v[232:235], v216 offset:18432
	ds_read_b128 v[236:239], v216 offset:19456
	global_load_lds_dwordx4 v152, s[52:53]
	s_add_i32 m0, s83, 0xe000
	s_nop 0
	global_load_lds_dwordx4 v154, s[52:53]
	s_waitcnt lgkmcnt(0)
	s_waitcnt vmcnt(8)
	s_barrier
	v_mfma_f32_16x16x32_bf16 v[124:127], v[128:131], v[156:159], v[124:127]
	v_mfma_f32_16x16x32_bf16 v[120:123], v[136:139], v[156:159], v[120:123]
	v_mfma_f32_16x16x32_bf16 v[108:111], v[128:131], v[164:167], v[108:111]
	v_mfma_f32_16x16x32_bf16 v[104:107], v[136:139], v[164:167], v[104:107]
	v_mfma_f32_16x16x32_bf16 v[92:95], v[128:131], v[192:195], v[92:95]
	v_mfma_f32_16x16x32_bf16 v[88:91], v[136:139], v[192:195], v[88:91]
	v_mfma_f32_16x16x32_bf16 v[76:79], v[128:131], v[200:203], v[76:79]
	v_mfma_f32_16x16x32_bf16 v[72:75], v[136:139], v[200:203], v[72:75]
	v_mfma_f32_16x16x32_bf16 v[124:127], v[132:135], v[160:163], v[124:127]
	v_mfma_f32_16x16x32_bf16 v[120:123], v[140:143], v[160:163], v[120:123]
	v_mfma_f32_16x16x32_bf16 v[108:111], v[132:135], v[188:191], v[108:111]
	v_mfma_f32_16x16x32_bf16 v[104:107], v[140:143], v[188:191], v[104:107]
	v_mfma_f32_16x16x32_bf16 v[92:95], v[132:135], v[196:199], v[92:95]
	v_mfma_f32_16x16x32_bf16 v[88:91], v[140:143], v[196:199], v[88:91]
	v_mfma_f32_16x16x32_bf16 v[76:79], v[132:135], v[204:207], v[76:79]
	v_mfma_f32_16x16x32_bf16 v[72:75], v[140:143], v[204:207], v[72:75]
	v_mfma_f32_16x16x32_bf16 v[116:119], v[220:223], v[156:159], v[116:119]
	v_mfma_f32_16x16x32_bf16 v[112:115], v[232:235], v[156:159], v[112:115]
	v_mfma_f32_16x16x32_bf16 v[100:103], v[220:223], v[164:167], v[100:103]
	v_mfma_f32_16x16x32_bf16 v[96:99], v[232:235], v[164:167], v[96:99]
	v_mfma_f32_16x16x32_bf16 v[84:87], v[220:223], v[192:195], v[84:87]
	v_mfma_f32_16x16x32_bf16 v[80:83], v[232:235], v[192:195], v[80:83]
	v_mfma_f32_16x16x32_bf16 v[68:71], v[220:223], v[200:203], v[68:71]
	v_mfma_f32_16x16x32_bf16 v[64:67], v[232:235], v[200:203], v[64:67]
	v_mfma_f32_16x16x32_bf16 v[116:119], v[228:231], v[160:163], v[116:119]
	v_mfma_f32_16x16x32_bf16 v[112:115], v[236:239], v[160:163], v[112:115]
	v_mfma_f32_16x16x32_bf16 v[100:103], v[228:231], v[188:191], v[100:103]
	v_mfma_f32_16x16x32_bf16 v[96:99], v[236:239], v[188:191], v[96:99]
	v_mfma_f32_16x16x32_bf16 v[84:87], v[228:231], v[196:199], v[84:87]
	v_mfma_f32_16x16x32_bf16 v[80:83], v[236:239], v[196:199], v[80:83]
	v_mfma_f32_16x16x32_bf16 v[68:71], v[228:231], v[204:207], v[68:71]
	v_mfma_f32_16x16x32_bf16 v[64:67], v[236:239], v[204:207], v[64:67]
	s_barrier
	s_add_i32 s27, 0, 0x14000
	s_add_i32 s35, s36, s81
	s_mov_b32 m0, s35
	s_nop 0
	global_load_lds_dwordx4 v148, s[72:73]
	s_add_i32 m0, s35, 0x2000
	s_nop 0
	global_load_lds_dwordx4 v146, s[72:73]
	s_mov_b32 m0, s83
	ds_read_b128 v[156:159], v217 offset:16384
	ds_read_b128 v[160:163], v217 offset:17408
	ds_read_b128 v[164:167], v217 offset:18432
	ds_read_b128 v[188:191], v217 offset:19456
	ds_read_b128 v[192:195], v217 offset:20480
	ds_read_b128 v[196:199], v217 offset:21504
	ds_read_b128 v[200:203], v217 offset:22528
	ds_read_b128 v[204:207], v217 offset:23552
	global_load_lds_dwordx4 v148, s[74:75]
	s_mov_b32 m0, s84
	s_nop 0
	global_load_lds_dwordx4 v146, s[74:75]
	s_add_u32 s36, s72, 0x40000
	s_addc_u32 s37, s73, 0
	s_add_i32 s27, s27, s81
	s_mov_b32 m0, s27
	s_nop 0
	global_load_lds_dwordx4 v148, s[36:37]
	s_add_i32 m0, s27, 0x2000
	s_nop 0
	global_load_lds_dwordx4 v146, s[36:37]
	s_waitcnt lgkmcnt(0)
	s_waitcnt vmcnt(8)
	s_barrier
	v_mfma_f32_16x16x32_bf16 v[60:63], v[128:131], v[156:159], v[60:63]
	v_mfma_f32_16x16x32_bf16 v[56:59], v[136:139], v[156:159], v[56:59]
	v_mfma_f32_16x16x32_bf16 v[44:47], v[128:131], v[164:167], v[44:47]
	v_mfma_f32_16x16x32_bf16 v[40:43], v[136:139], v[164:167], v[40:43]
	v_mfma_f32_16x16x32_bf16 v[28:31], v[128:131], v[192:195], v[28:31]
	v_mfma_f32_16x16x32_bf16 v[24:27], v[136:139], v[192:195], v[24:27]
	v_mfma_f32_16x16x32_bf16 v[12:15], v[128:131], v[200:203], v[12:15]
	v_mfma_f32_16x16x32_bf16 v[8:11], v[136:139], v[200:203], v[8:11]
	v_mfma_f32_16x16x32_bf16 v[60:63], v[132:135], v[160:163], v[60:63]
	v_mfma_f32_16x16x32_bf16 v[56:59], v[140:143], v[160:163], v[56:59]
	v_mfma_f32_16x16x32_bf16 v[44:47], v[132:135], v[188:191], v[44:47]
	v_mfma_f32_16x16x32_bf16 v[40:43], v[140:143], v[188:191], v[40:43]
	v_mfma_f32_16x16x32_bf16 v[28:31], v[132:135], v[196:199], v[28:31]
	v_mfma_f32_16x16x32_bf16 v[24:27], v[140:143], v[196:199], v[24:27]
	v_mfma_f32_16x16x32_bf16 v[12:15], v[132:135], v[204:207], v[12:15]
	v_mfma_f32_16x16x32_bf16 v[8:11], v[140:143], v[204:207], v[8:11]
	v_mfma_f32_16x16x32_bf16 v[52:55], v[220:223], v[156:159], v[52:55]
	v_mfma_f32_16x16x32_bf16 v[48:51], v[232:235], v[156:159], v[48:51]
	v_mfma_f32_16x16x32_bf16 v[36:39], v[220:223], v[164:167], v[36:39]
	v_mfma_f32_16x16x32_bf16 v[32:35], v[232:235], v[164:167], v[32:35]
	v_mfma_f32_16x16x32_bf16 v[20:23], v[220:223], v[192:195], v[20:23]
	v_mfma_f32_16x16x32_bf16 v[16:19], v[232:235], v[192:195], v[16:19]
	v_mfma_f32_16x16x32_bf16 v[4:7], v[220:223], v[200:203], v[4:7]
	v_mfma_f32_16x16x32_bf16 v[0:3], v[232:235], v[200:203], v[0:3]
	v_mfma_f32_16x16x32_bf16 v[52:55], v[228:231], v[160:163], v[52:55]
	v_mfma_f32_16x16x32_bf16 v[48:51], v[236:239], v[160:163], v[48:51]
	v_mfma_f32_16x16x32_bf16 v[36:39], v[228:231], v[188:191], v[36:39]
	v_mfma_f32_16x16x32_bf16 v[32:35], v[236:239], v[188:191], v[32:35]
	v_mfma_f32_16x16x32_bf16 v[20:23], v[228:231], v[196:199], v[20:23]
	v_mfma_f32_16x16x32_bf16 v[16:19], v[236:239], v[196:199], v[16:19]
	v_mfma_f32_16x16x32_bf16 v[4:7], v[228:231], v[204:207], v[4:7]
	v_mfma_f32_16x16x32_bf16 v[0:3], v[236:239], v[204:207], v[0:3]
	s_barrier
	s_add_i32 s27, 0, 0x18000
	ds_read_b128 v[128:131], v216 offset:32768
	ds_read_b128 v[132:135], v216 offset:33792
	ds_read_b128 v[136:139], v216 offset:34816
	ds_read_b128 v[140:143], v216 offset:35840
	s_add_u32 s36, s74, 0x40000
	s_addc_u32 s37, s75, 0
	s_mov_b32 m0, s85
	ds_read_b128 v[156:159], v217 offset:32768
	ds_read_b128 v[160:163], v217 offset:33792
	ds_read_b128 v[164:167], v217 offset:34816
	ds_read_b128 v[188:191], v217 offset:35840
	ds_read_b128 v[192:195], v217 offset:36864
	ds_read_b128 v[196:199], v217 offset:37888
	ds_read_b128 v[200:203], v217 offset:38912
	ds_read_b128 v[204:207], v217 offset:39936
	s_waitcnt lgkmcnt(8)
	ds_read_b128 v[220:223], v216 offset:49152
	ds_read_b128 v[228:231], v216 offset:50176
	ds_read_b128 v[232:235], v216 offset:51200
	ds_read_b128 v[236:239], v216 offset:52224
	global_load_lds_dwordx4 v148, s[36:37]
	s_mov_b32 m0, s86
	s_nop 0
	global_load_lds_dwordx4 v146, s[36:37]
	s_waitcnt lgkmcnt(0)
	s_waitcnt vmcnt(8)
	s_barrier
	v_mfma_f32_16x16x32_bf16 v[124:127], v[128:131], v[156:159], v[124:127]
	v_mfma_f32_16x16x32_bf16 v[120:123], v[136:139], v[156:159], v[120:123]
	v_mfma_f32_16x16x32_bf16 v[108:111], v[128:131], v[164:167], v[108:111]
	v_mfma_f32_16x16x32_bf16 v[104:107], v[136:139], v[164:167], v[104:107]
	v_mfma_f32_16x16x32_bf16 v[92:95], v[128:131], v[192:195], v[92:95]
	v_mfma_f32_16x16x32_bf16 v[88:91], v[136:139], v[192:195], v[88:91]
	v_mfma_f32_16x16x32_bf16 v[76:79], v[128:131], v[200:203], v[76:79]
	v_mfma_f32_16x16x32_bf16 v[72:75], v[136:139], v[200:203], v[72:75]
	v_mfma_f32_16x16x32_bf16 v[124:127], v[132:135], v[160:163], v[124:127]
	v_mfma_f32_16x16x32_bf16 v[120:123], v[140:143], v[160:163], v[120:123]
	v_mfma_f32_16x16x32_bf16 v[108:111], v[132:135], v[188:191], v[108:111]
	v_mfma_f32_16x16x32_bf16 v[104:107], v[140:143], v[188:191], v[104:107]
	v_mfma_f32_16x16x32_bf16 v[92:95], v[132:135], v[196:199], v[92:95]
	v_mfma_f32_16x16x32_bf16 v[88:91], v[140:143], v[196:199], v[88:91]
	v_mfma_f32_16x16x32_bf16 v[76:79], v[132:135], v[204:207], v[76:79]
	v_mfma_f32_16x16x32_bf16 v[72:75], v[140:143], v[204:207], v[72:75]
	v_mfma_f32_16x16x32_bf16 v[116:119], v[220:223], v[156:159], v[116:119]
	v_mfma_f32_16x16x32_bf16 v[112:115], v[232:235], v[156:159], v[112:115]
	v_mfma_f32_16x16x32_bf16 v[100:103], v[220:223], v[164:167], v[100:103]
	v_mfma_f32_16x16x32_bf16 v[96:99], v[232:235], v[164:167], v[96:99]
	v_mfma_f32_16x16x32_bf16 v[84:87], v[220:223], v[192:195], v[84:87]
	v_mfma_f32_16x16x32_bf16 v[80:83], v[232:235], v[192:195], v[80:83]
	v_mfma_f32_16x16x32_bf16 v[68:71], v[220:223], v[200:203], v[68:71]
	v_mfma_f32_16x16x32_bf16 v[64:67], v[232:235], v[200:203], v[64:67]
	v_mfma_f32_16x16x32_bf16 v[116:119], v[228:231], v[160:163], v[116:119]
	v_mfma_f32_16x16x32_bf16 v[112:115], v[236:239], v[160:163], v[112:115]
	v_mfma_f32_16x16x32_bf16 v[100:103], v[228:231], v[188:191], v[100:103]
	v_mfma_f32_16x16x32_bf16 v[96:99], v[236:239], v[188:191], v[96:99]
	v_mfma_f32_16x16x32_bf16 v[84:87], v[228:231], v[196:199], v[84:87]
	v_mfma_f32_16x16x32_bf16 v[80:83], v[236:239], v[196:199], v[80:83]
	v_mfma_f32_16x16x32_bf16 v[68:71], v[228:231], v[204:207], v[68:71]
	v_mfma_f32_16x16x32_bf16 v[64:67], v[236:239], v[204:207], v[64:67]
	s_barrier
	s_add_i32 s35, 0, 0x1c000
	s_add_i32 s27, s27, s81
	s_add_u32 s36, s72, s18
	s_addc_u32 s37, s73, s19
	s_mov_b32 m0, s27
	s_nop 0
	global_load_lds_dwordx4 v148, s[36:37]
	s_add_u32 s36, s72, s18
	s_addc_u32 s37, s73, s19
	s_add_i32 m0, s27, 0x2000
	s_nop 0
	global_load_lds_dwordx4 v146, s[36:37]
	s_mov_b32 m0, s87
	s_add_u32 s36, s74, s18
	s_addc_u32 s37, s75, s19
	ds_read_b128 v[156:159], v217 offset:49152
	ds_read_b128 v[160:163], v217 offset:50176
	ds_read_b128 v[164:167], v217 offset:51200
	ds_read_b128 v[188:191], v217 offset:52224
	ds_read_b128 v[192:195], v217 offset:53248
	ds_read_b128 v[196:199], v217 offset:54272
	ds_read_b128 v[200:203], v217 offset:55296
	ds_read_b128 v[204:207], v217 offset:56320
	global_load_lds_dwordx4 v148, s[36:37]
	s_add_u32 s36, s74, s18
	s_addc_u32 s37, s75, s19
	s_mov_b32 m0, s79
	s_nop 0
	global_load_lds_dwordx4 v146, s[36:37]
	s_add_u32 s36, s72, 0x40080
	s_addc_u32 s37, s73, 0
	s_add_i32 s27, s35, s81
	s_mov_b32 m0, s27
	s_nop 0
	global_load_lds_dwordx4 v148, s[36:37]
	s_add_i32 m0, s27, 0x2000
	s_nop 0
	global_load_lds_dwordx4 v146, s[36:37]
	s_waitcnt lgkmcnt(0)
	s_waitcnt vmcnt(8)
	s_barrier
	v_mfma_f32_16x16x32_bf16 v[60:63], v[128:131], v[156:159], v[60:63]
	v_mfma_f32_16x16x32_bf16 v[56:59], v[136:139], v[156:159], v[56:59]
	v_mfma_f32_16x16x32_bf16 v[44:47], v[128:131], v[164:167], v[44:47]
	v_mfma_f32_16x16x32_bf16 v[40:43], v[136:139], v[164:167], v[40:43]
	v_mfma_f32_16x16x32_bf16 v[28:31], v[128:131], v[192:195], v[28:31]
	v_mfma_f32_16x16x32_bf16 v[24:27], v[136:139], v[192:195], v[24:27]
	v_mfma_f32_16x16x32_bf16 v[12:15], v[128:131], v[200:203], v[12:15]
	v_mfma_f32_16x16x32_bf16 v[8:11], v[136:139], v[200:203], v[8:11]
	v_mfma_f32_16x16x32_bf16 v[60:63], v[132:135], v[160:163], v[60:63]
	v_mfma_f32_16x16x32_bf16 v[56:59], v[140:143], v[160:163], v[56:59]
	v_mfma_f32_16x16x32_bf16 v[44:47], v[132:135], v[188:191], v[44:47]
	v_mfma_f32_16x16x32_bf16 v[40:43], v[140:143], v[188:191], v[40:43]
	v_mfma_f32_16x16x32_bf16 v[28:31], v[132:135], v[196:199], v[28:31]
	v_mfma_f32_16x16x32_bf16 v[24:27], v[140:143], v[196:199], v[24:27]
	v_mfma_f32_16x16x32_bf16 v[12:15], v[132:135], v[204:207], v[12:15]
	v_mfma_f32_16x16x32_bf16 v[8:11], v[140:143], v[204:207], v[8:11]
	v_mfma_f32_16x16x32_bf16 v[52:55], v[220:223], v[156:159], v[52:55]
	v_mfma_f32_16x16x32_bf16 v[48:51], v[232:235], v[156:159], v[48:51]
	v_mfma_f32_16x16x32_bf16 v[36:39], v[220:223], v[164:167], v[36:39]
	v_mfma_f32_16x16x32_bf16 v[32:35], v[232:235], v[164:167], v[32:35]
	v_mfma_f32_16x16x32_bf16 v[20:23], v[220:223], v[192:195], v[20:23]
	v_mfma_f32_16x16x32_bf16 v[16:19], v[232:235], v[192:195], v[16:19]
	v_mfma_f32_16x16x32_bf16 v[4:7], v[220:223], v[200:203], v[4:7]
	v_mfma_f32_16x16x32_bf16 v[0:3], v[232:235], v[200:203], v[0:3]
	v_mfma_f32_16x16x32_bf16 v[52:55], v[228:231], v[160:163], v[52:55]
	v_mfma_f32_16x16x32_bf16 v[48:51], v[236:239], v[160:163], v[48:51]
	v_mfma_f32_16x16x32_bf16 v[36:39], v[228:231], v[188:191], v[36:39]
	v_mfma_f32_16x16x32_bf16 v[32:35], v[236:239], v[188:191], v[32:35]
	v_mfma_f32_16x16x32_bf16 v[20:23], v[228:231], v[196:199], v[20:23]
	v_mfma_f32_16x16x32_bf16 v[16:19], v[236:239], v[196:199], v[16:19]
	v_mfma_f32_16x16x32_bf16 v[4:7], v[228:231], v[204:207], v[4:7]
	v_mfma_f32_16x16x32_bf16 v[0:3], v[236:239], v[204:207], v[0:3]
	s_barrier
	s_add_i32 s34, s34, 2
	s_add_u32 s52, s52, 0x100
	s_addc_u32 s53, s53, 0
	s_add_u32 s31, s31, 0x100
	s_addc_u32 s33, s33, 0
	s_cmp_gt_u32 s34, 13
	s_cbranch_scc0 .LBB0_326
	v_lshl_add_u32 v128, s0, 8, v151
	v_readlane_b32 s0, v252, 36
	v_ashrrev_i32_e32 v129, 31, v128
	v_readlane_b32 s1, v252, 37
	v_or_b32_e32 v132, 16, v128
	v_or_b32_e32 v136, 32, v128
	v_lshl_add_u64 v[130:131], v[128:129], 3, s[0:1]
	v_ashrrev_i32_e32 v133, 31, v132
	v_ashrrev_i32_e32 v137, 31, v136
	v_or_b32_e32 v140, 48, v128
	v_lshl_add_u64 v[134:135], v[132:133], 3, s[0:1]
	v_lshl_add_u64 v[138:139], v[136:137], 3, s[0:1]
	v_ashrrev_i32_e32 v141, 31, v140
	global_load_dwordx2 v[202:203], v[130:131], off
	global_load_dwordx2 v[200:201], v[134:135], off
	global_load_dwordx2 v[192:193], v[138:139], off
	global_load_dwordx2 v[166:167], v[130:131], off offset:1024
	v_add_u32_e32 v164, 0x90, v128
	v_add_u32_e32 v158, 0xa0, v128
	v_add_u32_e32 v156, 0xb0, v128
	v_lshl_add_u64 v[142:143], v[140:141], 3, s[0:1]
	v_ashrrev_i32_e32 v165, 31, v164
	v_ashrrev_i32_e32 v159, 31, v158
	v_ashrrev_i32_e32 v157, 31, v156
	v_lshl_add_u64 v[130:131], v[164:165], 3, s[0:1]
	v_lshl_add_u64 v[134:135], v[158:159], 3, s[0:1]
	v_lshl_add_u64 v[138:139], v[156:157], 3, s[0:1]
	global_load_dwordx2 v[196:197], v[142:143], off
	global_load_dwordx2 v[188:189], v[130:131], off
	global_load_dwordx2 v[162:163], v[134:135], off
	global_load_dwordx2 v[160:161], v[138:139], off
	v_add_u32_e32 v168, 0x80, v128
	s_mov_b64 s[0:1], -1
	s_cmp_gt_u32 s10, 1
	v_lshlrev_b32_e32 v144, 1, v150
	v_ashrrev_i32_e32 v169, 31, v168
	v_lshlrev_b64 v[204:205], 10, v[128:129]
	v_lshlrev_b64 v[198:199], 10, v[132:133]
	v_lshlrev_b64 v[194:195], 10, v[136:137]
	v_lshlrev_b64 v[190:191], 10, v[140:141]
	s_waitcnt vmcnt(0)
	v_ffbh_u32_e32 v222, v203
	v_ffbh_u32_e32 v221, v201
	v_ffbh_u32_e32 v220, v193
	v_ffbh_u32_e32 v219, v197
	s_cbranch_scc0 .LBB0_329
	s_cmp_lt_u32 s10, 4
	s_cselect_b64 vcc, -1, 0
	v_readlane_b32 s56, v254, 23
	s_and_b64 s[0:1], vcc, exec
	v_readlane_b32 s70, v254, 37
	v_readlane_b32 s36, v252, 15
	v_readlane_b32 s71, v254, 38
	v_readlane_b32 s37, v252, 16
	s_cselect_b32 s0, s70, s36
	s_mov_b32 s11, 0x4400000
	v_readlane_b32 s30, v254, 62
	s_cselect_b32 s1, s71, s37
	s_cselect_b32 s11, s11, 0x4800000
	v_readlane_b32 s31, v254, 63
	s_add_u32 s0, s0, s30
	s_addc_u32 s1, s1, s31
	global_load_dwordx4 v[136:139], v218, s[0:1] offset:16
	global_load_dwordx4 v[140:143], v218, s[0:1]
	global_load_dwordx4 v[128:131], v218, s[0:1] offset:144
	global_load_dwordx4 v[132:135], v218, s[0:1] offset:128
	v_and_b32_e32 v177, 64, v214
	v_xor_b32_e32 v176, 16, v214
	v_add_u32_e32 v177, 64, v177
	v_cndmask_b32_e32 v223, 1.0, v215, vcc
	v_cmp_lt_i32_e32 vcc, v176, v177
	v_readlane_b32 s9, v254, 52
	s_add_u32 s11, s9, s11
	v_cndmask_b32_e32 v176, v214, v176, vcc
	v_lshlrev_b32_e32 v225, 2, v176
	v_xor_b32_e32 v176, 32, v214
	v_cmp_lt_i32_e32 vcc, v176, v177
	v_readlane_b32 s9, v254, 61
	s_addc_u32 s25, s9, 0
	v_cndmask_b32_e32 v176, v214, v176, vcc
	v_lshlrev_b32_e32 v224, 2, v176
	v_min_u32_e32 v176, 32, v222
	v_lshlrev_b64 v[228:229], v176, v[202:203]
	v_min_u32_e32 v177, 1, v228
	v_or_b32_e32 v177, v229, v177
	v_cvt_f32_u32_e32 v177, v177
	v_sub_u32_e32 v176, 32, v176
	s_lshl_b32 s0, s10, 9
	s_and_b32 s0, s0, 0x200
	v_ldexp_f32 v176, v177, v176
	v_mul_f32_e32 v176, 0x35800000, v176
	v_fmamk_f32 v176, v176, 0x3a800000, v210
	s_add_u32 s0, s11, s0
	v_rsq_f32_e32 v176, v176
	s_addc_u32 s1, s25, 0
	v_lshl_add_u64 v[206:207], s[0:1], 0, v[144:145]
	v_readlane_b32 s48, v252, 27
	v_mov_b32_e32 v228, v176
	v_pk_mul_f32 v[230:231], v[124:125], v[228:229] op_sel_hi:[1,0]
	v_pk_mul_f32 v[232:233], v[126:127], v[228:229] op_sel_hi:[1,0]
	v_pk_mul_f32 v[236:237], v[230:231], v[230:231]
	v_pk_mul_f32 v[234:235], v[232:233], v[232:233]
	v_pk_mul_f32 v[250:251], v[114:115], v[228:229] op_sel_hi:[1,0]
	v_pk_mov_b32 v[238:239], v[236:237], v[234:235] op_sel:[1,0]
	v_mov_b32_e32 v237, v235
	v_pk_add_f32 v[234:235], v[238:239], v[236:237]
	v_pk_mul_f32 v[236:237], v[120:121], v[228:229] op_sel_hi:[1,0]
	v_pk_mul_f32 v[238:239], v[122:123], v[228:229] op_sel_hi:[1,0]
	v_pk_mul_f32 v[242:243], v[236:237], v[236:237]
	v_pk_mul_f32 v[240:241], v[238:239], v[238:239]
	v_pk_add_f32 v[234:235], v[234:235], v[234:235] op_sel_hi:[0,1]
	v_pk_mov_b32 v[244:245], v[242:243], v[240:241] op_sel:[1,0]
	v_mov_b32_e32 v243, v241
	v_pk_add_f32 v[240:241], v[244:245], v[242:243]
	v_pk_mul_f32 v[244:245], v[116:117], v[228:229] op_sel_hi:[1,0]
	v_pk_mul_f32 v[242:243], v[118:119], v[228:229] op_sel_hi:[1,0]
	v_mul_f32_e32 v234, v244, v244
	v_pk_fma_f32 v[246:247], v[244:245], v[244:245], v[234:235] op_sel_hi:[1,1,0]
	v_mul_f32_e32 v234, v242, v242
	v_pk_add_f32 v[240:241], v[240:241], v[240:241] op_sel_hi:[0,1]
	v_pk_fma_f32 v[248:249], v[242:243], v[242:243], v[234:235] op_sel_hi:[1,1,0]
	v_pk_mul_f32 v[176:177], v[112:113], v[228:229] op_sel_hi:[1,0]
	v_mul_f32_e32 v234, v250, v250
	v_mul_f32_e32 v246, v176, v176
	v_mul_f32_e32 v248, v177, v177
	v_mul_f32_e32 v240, v251, v251
	v_pk_add_f32 v[228:229], v[246:247], v[248:249]
	v_pk_add_f32 v[234:235], v[234:235], v[240:241]
	v_lshl_add_u64 v[240:241], v[206:207], 0, v[204:205]
	v_pk_add_f32 v[228:229], v[228:229], v[234:235]
	v_readlane_b32 s57, v254, 24
	v_add_f32_e32 v228, v228, v229
	ds_bpermute_b32 v229, v225, v228
	v_readlane_b32 s58, v254, 25
	v_readlane_b32 s59, v254, 26
	v_readlane_b32 s60, v254, 27
	v_readlane_b32 s61, v254, 28
	s_waitcnt lgkmcnt(0)
	v_add_f32_e32 v228, v228, v229
	ds_bpermute_b32 v229, v224, v228
	v_readlane_b32 s62, v254, 29
	v_readlane_b32 s63, v254, 30
	v_readlane_b32 s64, v254, 31
	v_readlane_b32 s65, v254, 32
	s_waitcnt lgkmcnt(0)
	v_add_f32_e32 v228, v228, v229
	v_fmamk_f32 v228, v228, 0x3c800000, v210
	v_readlane_b32 s66, v254, 33
	v_rsq_f32_e32 v228, v228
	v_readlane_b32 s67, v254, 34
	v_readlane_b32 s68, v254, 35
	v_readlane_b32 s69, v254, 36
	v_mul_f32_e32 v234, v223, v228
	v_pk_mul_f32 v[228:229], v[230:231], v[234:235] op_sel_hi:[1,0]
	v_pk_mul_f32 v[230:231], v[232:233], v[234:235] op_sel_hi:[1,0]
	s_waitcnt vmcnt(2)
	v_pk_mul_f32 v[228:229], v[140:141], v[228:229]
	v_pk_mul_f32 v[230:231], v[142:143], v[230:231]
	v_pk_mul_f32 v[232:233], v[236:237], v[234:235] op_sel_hi:[1,0]
	v_pk_mul_f32 v[236:237], v[238:239], v[234:235] op_sel_hi:[1,0]
	v_cvt_pk_bf16_f32 v228, v228, v229
	v_cvt_pk_bf16_f32 v229, v230, v231
	v_pk_mul_f32 v[232:233], v[136:137], v[232:233]
	v_pk_mul_f32 v[236:237], v[138:139], v[236:237]
	v_cvt_pk_bf16_f32 v230, v232, v233
	v_pk_mul_f32 v[176:177], v[176:177], v[234:235] op_sel_hi:[1,0]
	v_cvt_pk_bf16_f32 v231, v236, v237
	global_store_dwordx4 v[240:241], v[228:231], off
	v_pk_mul_f32 v[232:233], v[250:251], v[234:235] op_sel_hi:[1,0]
	s_waitcnt vmcnt(2)
	v_pk_mul_f32 v[176:177], v[128:129], v[176:177]
	v_pk_mul_f32 v[228:229], v[244:245], v[234:235] op_sel_hi:[1,0]
	v_pk_mul_f32 v[230:231], v[242:243], v[234:235] op_sel_hi:[1,0]
	s_waitcnt vmcnt(1)
	v_pk_mul_f32 v[228:229], v[132:133], v[228:229]
	v_pk_mul_f32 v[230:231], v[134:135], v[230:231]
	v_cvt_pk_bf16_f32 v228, v228, v229
	v_pk_mul_f32 v[232:233], v[130:131], v[232:233]
	v_cvt_pk_bf16_f32 v229, v230, v231
	v_cvt_pk_bf16_f32 v230, v176, v177
	s_nop 1
	v_readlane_b32 s38, v252, 17
	v_cvt_pk_bf16_f32 v231, v232, v233
	s_nop 1
	global_store_dwordx4 v[240:241], v[228:231], off offset:64
	v_readlane_b32 s39, v252, 18
	v_readlane_b32 s40, v252, 19
	v_min_u32_e32 v228, 32, v221
	v_lshlrev_b64 v[176:177], v228, v[200:201]
	v_min_u32_e32 v176, 1, v176
	v_or_b32_e32 v176, v177, v176
	v_cvt_f32_u32_e32 v176, v176
	v_sub_u32_e32 v177, 32, v228
	v_readlane_b32 s41, v252, 20
	v_readlane_b32 s42, v252, 21
	v_ldexp_f32 v176, v176, v177
	v_mul_f32_e32 v176, 0x35800000, v176
	v_fmamk_f32 v176, v176, 0x3a800000, v210
	v_readlane_b32 s43, v252, 22
	v_rsq_f32_e32 v176, v176
	v_readlane_b32 s44, v252, 23
	v_readlane_b32 s45, v252, 24
	v_readlane_b32 s46, v252, 25
	v_pk_mul_f32 v[228:229], v[108:109], v[176:177] op_sel_hi:[1,0]
	v_pk_mul_f32 v[230:231], v[110:111], v[176:177] op_sel_hi:[1,0]
	v_pk_mul_f32 v[234:235], v[228:229], v[228:229]
	v_pk_mul_f32 v[232:233], v[230:231], v[230:231]
	v_pk_mul_f32 v[248:249], v[98:99], v[176:177] op_sel_hi:[1,0]
	v_pk_mov_b32 v[236:237], v[234:235], v[232:233] op_sel:[1,0]
	v_mov_b32_e32 v235, v233
	v_pk_add_f32 v[232:233], v[236:237], v[234:235]
	v_pk_mul_f32 v[234:235], v[104:105], v[176:177] op_sel_hi:[1,0]
	v_pk_mul_f32 v[236:237], v[106:107], v[176:177] op_sel_hi:[1,0]
	v_pk_mul_f32 v[240:241], v[234:235], v[234:235]
	v_pk_mul_f32 v[238:239], v[236:237], v[236:237]
	v_pk_add_f32 v[232:233], v[232:233], v[232:233] op_sel_hi:[0,1]
	v_pk_mov_b32 v[242:243], v[240:241], v[238:239] op_sel:[1,0]
	v_mov_b32_e32 v241, v239
	v_pk_add_f32 v[238:239], v[242:243], v[240:241]
	v_pk_mul_f32 v[242:243], v[100:101], v[176:177] op_sel_hi:[1,0]
	v_pk_mul_f32 v[240:241], v[102:103], v[176:177] op_sel_hi:[1,0]
	v_mul_f32_e32 v232, v242, v242
	v_pk_fma_f32 v[244:245], v[242:243], v[242:243], v[232:233] op_sel_hi:[1,1,0]
	v_mul_f32_e32 v232, v240, v240
	v_pk_add_f32 v[238:239], v[238:239], v[238:239] op_sel_hi:[0,1]
	v_pk_fma_f32 v[246:247], v[240:241], v[240:241], v[232:233] op_sel_hi:[1,1,0]
	v_pk_mul_f32 v[176:177], v[96:97], v[176:177] op_sel_hi:[1,0]
	v_mul_f32_e32 v232, v248, v248
	v_mul_f32_e32 v244, v176, v176
	v_mul_f32_e32 v246, v177, v177
	v_mul_f32_e32 v238, v249, v249
	v_pk_add_f32 v[244:245], v[244:245], v[246:247]
	v_pk_add_f32 v[232:233], v[232:233], v[238:239]
	v_lshl_add_u64 v[238:239], v[206:207], 0, v[198:199]
	v_pk_add_f32 v[232:233], v[244:245], v[232:233]
	v_readlane_b32 s47, v252, 26
	v_add_f32_e32 v232, v232, v233
	ds_bpermute_b32 v233, v225, v232
	v_readlane_b32 s49, v252, 28
	v_readlane_b32 s50, v252, 29
	v_readlane_b32 s51, v252, 30
	v_readlane_b32 s48, v252, 40
	s_waitcnt lgkmcnt(0)
	v_add_f32_e32 v232, v232, v233
	ds_bpermute_b32 v233, v224, v232
	s_mov_b64 s[0:1], 0
	s_waitcnt lgkmcnt(0)
	v_add_f32_e32 v232, v232, v233
	v_fmamk_f32 v232, v232, 0x3c800000, v210
	s_nop 0
	v_rsq_f32_e32 v232, v232
	s_nop 0
	v_mul_f32_e32 v232, v223, v232
	v_pk_mul_f32 v[228:229], v[228:229], v[232:233] op_sel_hi:[1,0]
	v_pk_mul_f32 v[230:231], v[230:231], v[232:233] op_sel_hi:[1,0]
	v_pk_mul_f32 v[228:229], v[140:141], v[228:229]
	v_pk_mul_f32 v[230:231], v[142:143], v[230:231]
	v_pk_mul_f32 v[234:235], v[234:235], v[232:233] op_sel_hi:[1,0]
	v_pk_mul_f32 v[236:237], v[236:237], v[232:233] op_sel_hi:[1,0]
	v_cvt_pk_bf16_f32 v228, v228, v229
	v_cvt_pk_bf16_f32 v229, v230, v231
	v_pk_mul_f32 v[234:235], v[136:137], v[234:235]
	v_pk_mul_f32 v[236:237], v[138:139], v[236:237]
	v_cvt_pk_bf16_f32 v230, v234, v235
	v_pk_mul_f32 v[176:177], v[176:177], v[232:233] op_sel_hi:[1,0]
	v_cvt_pk_bf16_f32 v231, v236, v237
	global_store_dwordx4 v[238:239], v[228:231], off
	v_pk_mul_f32 v[176:177], v[128:129], v[176:177]
	s_nop 0
	v_pk_mul_f32 v[228:229], v[242:243], v[232:233] op_sel_hi:[1,0]
	v_pk_mul_f32 v[230:231], v[240:241], v[232:233] op_sel_hi:[1,0]
	v_pk_mul_f32 v[228:229], v[132:133], v[228:229]
	v_pk_mul_f32 v[230:231], v[134:135], v[230:231]
	v_pk_mul_f32 v[232:233], v[248:249], v[232:233] op_sel_hi:[1,0]
	v_cvt_pk_bf16_f32 v228, v228, v229
	v_cvt_pk_bf16_f32 v229, v230, v231
	v_cvt_pk_bf16_f32 v230, v176, v177
	s_nop 0
	v_pk_mul_f32 v[232:233], v[130:131], v[232:233]
	s_nop 0
	v_cvt_pk_bf16_f32 v231, v232, v233
	global_store_dwordx4 v[238:239], v[228:231], off offset:64
	s_nop 1
	v_min_u32_e32 v228, 32, v220
	v_lshlrev_b64 v[176:177], v228, v[192:193]
	v_min_u32_e32 v176, 1, v176
	v_or_b32_e32 v176, v177, v176
	v_cvt_f32_u32_e32 v176, v176
	v_sub_u32_e32 v177, 32, v228
	v_ldexp_f32 v176, v176, v177
	v_mul_f32_e32 v176, 0x35800000, v176
	v_fmamk_f32 v176, v176, 0x3a800000, v210
	s_nop 0
	v_rsq_f32_e32 v176, v176
	s_nop 0
	v_pk_mul_f32 v[228:229], v[92:93], v[176:177] op_sel_hi:[1,0]
	v_pk_mul_f32 v[230:231], v[94:95], v[176:177] op_sel_hi:[1,0]
	v_pk_mul_f32 v[234:235], v[228:229], v[228:229]
	v_pk_mul_f32 v[232:233], v[230:231], v[230:231]
	v_pk_mul_f32 v[248:249], v[82:83], v[176:177] op_sel_hi:[1,0]
	v_pk_mov_b32 v[236:237], v[234:235], v[232:233] op_sel:[1,0]
	v_mov_b32_e32 v235, v233
	v_pk_add_f32 v[232:233], v[236:237], v[234:235]
	v_pk_mul_f32 v[234:235], v[88:89], v[176:177] op_sel_hi:[1,0]
	v_pk_mul_f32 v[236:237], v[90:91], v[176:177] op_sel_hi:[1,0]
	v_pk_mul_f32 v[240:241], v[234:235], v[234:235]
	v_pk_mul_f32 v[238:239], v[236:237], v[236:237]
	v_pk_add_f32 v[232:233], v[232:233], v[232:233] op_sel_hi:[0,1]
	v_pk_mov_b32 v[242:243], v[240:241], v[238:239] op_sel:[1,0]
	v_mov_b32_e32 v241, v239
	v_pk_add_f32 v[238:239], v[242:243], v[240:241]
	v_pk_mul_f32 v[242:243], v[84:85], v[176:177] op_sel_hi:[1,0]
	v_pk_mul_f32 v[240:241], v[86:87], v[176:177] op_sel_hi:[1,0]
	v_mul_f32_e32 v232, v242, v242
	v_pk_fma_f32 v[244:245], v[242:243], v[242:243], v[232:233] op_sel_hi:[1,1,0]
	v_mul_f32_e32 v232, v240, v240
	v_pk_add_f32 v[238:239], v[238:239], v[238:239] op_sel_hi:[0,1]
	v_pk_fma_f32 v[246:247], v[240:241], v[240:241], v[232:233] op_sel_hi:[1,1,0]
	v_pk_mul_f32 v[176:177], v[80:81], v[176:177] op_sel_hi:[1,0]
	v_mul_f32_e32 v232, v248, v248
	v_mul_f32_e32 v244, v176, v176
	v_mul_f32_e32 v246, v177, v177
	v_mul_f32_e32 v238, v249, v249
	v_pk_add_f32 v[244:245], v[244:245], v[246:247]
	v_pk_add_f32 v[232:233], v[232:233], v[238:239]
	v_lshl_add_u64 v[238:239], v[206:207], 0, v[194:195]
	v_pk_add_f32 v[232:233], v[244:245], v[232:233]
	s_nop 0
	v_add_f32_e32 v232, v232, v233
	ds_bpermute_b32 v233, v225, v232
	s_waitcnt lgkmcnt(0)
	v_add_f32_e32 v232, v232, v233
	ds_bpermute_b32 v233, v224, v232
	s_waitcnt lgkmcnt(0)
	v_add_f32_e32 v232, v232, v233
	v_fmamk_f32 v232, v232, 0x3c800000, v210
	s_nop 0
	v_rsq_f32_e32 v232, v232
	s_nop 0
	v_mul_f32_e32 v232, v223, v232
	v_pk_mul_f32 v[228:229], v[228:229], v[232:233] op_sel_hi:[1,0]
	v_pk_mul_f32 v[230:231], v[230:231], v[232:233] op_sel_hi:[1,0]
	v_pk_mul_f32 v[228:229], v[140:141], v[228:229]
	v_pk_mul_f32 v[230:231], v[142:143], v[230:231]
	v_pk_mul_f32 v[234:235], v[234:235], v[232:233] op_sel_hi:[1,0]
	v_pk_mul_f32 v[236:237], v[236:237], v[232:233] op_sel_hi:[1,0]
	v_cvt_pk_bf16_f32 v228, v228, v229
	v_cvt_pk_bf16_f32 v229, v230, v231
	v_pk_mul_f32 v[234:235], v[136:137], v[234:235]
	v_pk_mul_f32 v[236:237], v[138:139], v[236:237]
	v_cvt_pk_bf16_f32 v230, v234, v235
	v_pk_mul_f32 v[176:177], v[176:177], v[232:233] op_sel_hi:[1,0]
	v_cvt_pk_bf16_f32 v231, v236, v237
	global_store_dwordx4 v[238:239], v[228:231], off
	v_pk_mul_f32 v[176:177], v[128:129], v[176:177]
	s_nop 0
	v_pk_mul_f32 v[228:229], v[242:243], v[232:233] op_sel_hi:[1,0]
	v_pk_mul_f32 v[230:231], v[240:241], v[232:233] op_sel_hi:[1,0]
	v_pk_mul_f32 v[228:229], v[132:133], v[228:229]
	v_pk_mul_f32 v[230:231], v[134:135], v[230:231]
	v_pk_mul_f32 v[232:233], v[248:249], v[232:233] op_sel_hi:[1,0]
	v_cvt_pk_bf16_f32 v228, v228, v229
	v_cvt_pk_bf16_f32 v229, v230, v231
	v_cvt_pk_bf16_f32 v230, v176, v177
	s_nop 0
	v_pk_mul_f32 v[232:233], v[130:131], v[232:233]
	s_nop 0
	v_cvt_pk_bf16_f32 v231, v232, v233
	global_store_dwordx4 v[238:239], v[228:231], off offset:64
	s_nop 1
	v_min_u32_e32 v228, 32, v219
	v_lshlrev_b64 v[176:177], v228, v[196:197]
	v_min_u32_e32 v176, 1, v176
	v_or_b32_e32 v176, v177, v176
	v_cvt_f32_u32_e32 v176, v176
	v_sub_u32_e32 v177, 32, v228
	v_ldexp_f32 v176, v176, v177
	v_mul_f32_e32 v176, 0x35800000, v176
	v_fmamk_f32 v176, v176, 0x3a800000, v210
	s_nop 0
	v_rsq_f32_e32 v176, v176
	s_nop 0
	v_pk_mul_f32 v[228:229], v[76:77], v[176:177] op_sel_hi:[1,0]
	v_pk_mul_f32 v[230:231], v[78:79], v[176:177] op_sel_hi:[1,0]
	v_pk_mul_f32 v[234:235], v[228:229], v[228:229]
	v_pk_mul_f32 v[232:233], v[230:231], v[230:231]
	v_pk_mul_f32 v[248:249], v[66:67], v[176:177] op_sel_hi:[1,0]
	v_pk_mov_b32 v[236:237], v[234:235], v[232:233] op_sel:[1,0]
	v_mov_b32_e32 v235, v233
	v_pk_add_f32 v[232:233], v[236:237], v[234:235]
	v_pk_mul_f32 v[234:235], v[72:73], v[176:177] op_sel_hi:[1,0]
	v_pk_mul_f32 v[236:237], v[74:75], v[176:177] op_sel_hi:[1,0]
	v_pk_mul_f32 v[240:241], v[234:235], v[234:235]
	v_pk_mul_f32 v[238:239], v[236:237], v[236:237]
	v_pk_add_f32 v[232:233], v[232:233], v[232:233] op_sel_hi:[0,1]
	v_pk_mov_b32 v[242:243], v[240:241], v[238:239] op_sel:[1,0]
	v_mov_b32_e32 v241, v239
	v_pk_add_f32 v[238:239], v[242:243], v[240:241]
	v_pk_mul_f32 v[242:243], v[68:69], v[176:177] op_sel_hi:[1,0]
	v_pk_mul_f32 v[240:241], v[70:71], v[176:177] op_sel_hi:[1,0]
	v_mul_f32_e32 v232, v242, v242
	v_pk_fma_f32 v[244:245], v[242:243], v[242:243], v[232:233] op_sel_hi:[1,1,0]
	v_mul_f32_e32 v232, v240, v240
	v_pk_add_f32 v[238:239], v[238:239], v[238:239] op_sel_hi:[0,1]
	v_pk_fma_f32 v[246:247], v[240:241], v[240:241], v[232:233] op_sel_hi:[1,1,0]
	v_pk_mul_f32 v[176:177], v[64:65], v[176:177] op_sel_hi:[1,0]
	v_mul_f32_e32 v232, v248, v248
	v_mul_f32_e32 v244, v176, v176
	v_mul_f32_e32 v246, v177, v177
	v_mul_f32_e32 v238, v249, v249
	v_pk_add_f32 v[244:245], v[244:245], v[246:247]
	v_pk_add_f32 v[232:233], v[232:233], v[238:239]
	v_lshl_add_u64 v[238:239], v[206:207], 0, v[190:191]
	v_pk_add_f32 v[232:233], v[244:245], v[232:233]
	s_nop 0
	v_add_f32_e32 v232, v232, v233
	ds_bpermute_b32 v233, v225, v232
	s_waitcnt lgkmcnt(0)
	v_add_f32_e32 v232, v232, v233
	ds_bpermute_b32 v233, v224, v232
	s_waitcnt lgkmcnt(0)
	v_add_f32_e32 v232, v232, v233
	v_fmamk_f32 v232, v232, 0x3c800000, v210
	s_nop 0
	v_rsq_f32_e32 v232, v232
	s_nop 0
	v_mul_f32_e32 v232, v223, v232
	v_pk_mul_f32 v[228:229], v[228:229], v[232:233] op_sel_hi:[1,0]
	v_pk_mul_f32 v[230:231], v[230:231], v[232:233] op_sel_hi:[1,0]
	v_pk_mul_f32 v[228:229], v[140:141], v[228:229]
	v_pk_mul_f32 v[230:231], v[142:143], v[230:231]
	v_pk_mul_f32 v[234:235], v[234:235], v[232:233] op_sel_hi:[1,0]
	v_pk_mul_f32 v[236:237], v[236:237], v[232:233] op_sel_hi:[1,0]
	v_pk_mul_f32 v[234:235], v[136:137], v[234:235]
	v_pk_mul_f32 v[236:237], v[138:139], v[236:237]
	v_cvt_pk_bf16_f32 v228, v228, v229
	v_cvt_pk_bf16_f32 v229, v230, v231
	v_cvt_pk_bf16_f32 v230, v234, v235
	v_pk_mul_f32 v[176:177], v[176:177], v[232:233] op_sel_hi:[1,0]
	v_cvt_pk_bf16_f32 v231, v236, v237
	global_store_dwordx4 v[238:239], v[228:231], off
	v_pk_mul_f32 v[176:177], v[128:129], v[176:177]
	s_nop 0
	v_pk_mul_f32 v[228:229], v[242:243], v[232:233] op_sel_hi:[1,0]
	v_pk_mul_f32 v[230:231], v[240:241], v[232:233] op_sel_hi:[1,0]
	v_pk_mul_f32 v[228:229], v[132:133], v[228:229]
	v_pk_mul_f32 v[230:231], v[134:135], v[230:231]
	v_pk_mul_f32 v[232:233], v[248:249], v[232:233] op_sel_hi:[1,0]
	v_cvt_pk_bf16_f32 v228, v228, v229
	v_cvt_pk_bf16_f32 v229, v230, v231
	v_cvt_pk_bf16_f32 v230, v176, v177
	v_ffbh_u32_e32 v176, v167
	v_pk_mul_f32 v[232:233], v[130:131], v[232:233]
	s_nop 0
	v_cvt_pk_bf16_f32 v231, v232, v233
	global_store_dwordx4 v[238:239], v[228:231], off offset:64
	s_nop 1
	v_min_u32_e32 v228, 32, v176
	v_lshlrev_b64 v[176:177], v228, v[166:167]
	v_min_u32_e32 v176, 1, v176
	v_or_b32_e32 v176, v177, v176
	v_cvt_f32_u32_e32 v176, v176
	v_sub_u32_e32 v177, 32, v228
	v_ldexp_f32 v176, v176, v177
	v_mul_f32_e32 v176, 0x35800000, v176
	v_fmamk_f32 v176, v176, 0x3a800000, v210
	s_nop 0
	v_rsq_f32_e32 v176, v176
	s_nop 0
	v_pk_mul_f32 v[228:229], v[60:61], v[176:177] op_sel_hi:[1,0]
	v_pk_mul_f32 v[230:231], v[62:63], v[176:177] op_sel_hi:[1,0]
	v_pk_mul_f32 v[234:235], v[228:229], v[228:229]
	v_pk_mul_f32 v[232:233], v[230:231], v[230:231]
	v_pk_mul_f32 v[248:249], v[50:51], v[176:177] op_sel_hi:[1,0]
	v_pk_mov_b32 v[236:237], v[234:235], v[232:233] op_sel:[1,0]
	v_mov_b32_e32 v235, v233
	v_pk_add_f32 v[232:233], v[236:237], v[234:235]
	v_pk_mul_f32 v[234:235], v[56:57], v[176:177] op_sel_hi:[1,0]
	v_pk_mul_f32 v[236:237], v[58:59], v[176:177] op_sel_hi:[1,0]
	v_pk_mul_f32 v[240:241], v[234:235], v[234:235]
	v_pk_mul_f32 v[238:239], v[236:237], v[236:237]
	v_pk_add_f32 v[232:233], v[232:233], v[232:233] op_sel_hi:[0,1]
	v_pk_mov_b32 v[242:243], v[240:241], v[238:239] op_sel:[1,0]
	v_mov_b32_e32 v241, v239
	v_pk_add_f32 v[238:239], v[242:243], v[240:241]
	v_pk_mul_f32 v[242:243], v[52:53], v[176:177] op_sel_hi:[1,0]
	v_pk_mul_f32 v[240:241], v[54:55], v[176:177] op_sel_hi:[1,0]
	v_mul_f32_e32 v232, v242, v242
	v_pk_fma_f32 v[244:245], v[242:243], v[242:243], v[232:233] op_sel_hi:[1,1,0]
	v_mul_f32_e32 v232, v240, v240
	v_pk_add_f32 v[238:239], v[238:239], v[238:239] op_sel_hi:[0,1]
	v_pk_fma_f32 v[246:247], v[240:241], v[240:241], v[232:233] op_sel_hi:[1,1,0]
	v_pk_mul_f32 v[176:177], v[48:49], v[176:177] op_sel_hi:[1,0]
	v_mul_f32_e32 v232, v248, v248
	v_mul_f32_e32 v244, v176, v176
	v_mul_f32_e32 v246, v177, v177
	v_mul_f32_e32 v238, v249, v249
	v_pk_add_f32 v[244:245], v[244:245], v[246:247]
	v_pk_add_f32 v[232:233], v[232:233], v[238:239]
	v_lshlrev_b64 v[238:239], 10, v[168:169]
	v_pk_add_f32 v[232:233], v[244:245], v[232:233]
	v_lshl_add_u64 v[238:239], v[206:207], 0, v[238:239]
	v_add_f32_e32 v232, v232, v233
	ds_bpermute_b32 v233, v225, v232
	s_waitcnt lgkmcnt(0)
	v_add_f32_e32 v232, v232, v233
	ds_bpermute_b32 v233, v224, v232
	s_waitcnt lgkmcnt(0)
	v_add_f32_e32 v232, v232, v233
	v_fmamk_f32 v232, v232, 0x3c800000, v210
	s_nop 0
	v_rsq_f32_e32 v232, v232
	s_nop 0
	v_mul_f32_e32 v232, v223, v232
	v_pk_mul_f32 v[228:229], v[228:229], v[232:233] op_sel_hi:[1,0]
	v_pk_mul_f32 v[230:231], v[230:231], v[232:233] op_sel_hi:[1,0]
	v_pk_mul_f32 v[228:229], v[140:141], v[228:229]
	v_pk_mul_f32 v[230:231], v[142:143], v[230:231]
	v_pk_mul_f32 v[234:235], v[234:235], v[232:233] op_sel_hi:[1,0]
	v_pk_mul_f32 v[236:237], v[236:237], v[232:233] op_sel_hi:[1,0]
	v_pk_mul_f32 v[234:235], v[136:137], v[234:235]
	v_pk_mul_f32 v[236:237], v[138:139], v[236:237]
	v_cvt_pk_bf16_f32 v228, v228, v229
	v_cvt_pk_bf16_f32 v229, v230, v231
	v_cvt_pk_bf16_f32 v230, v234, v235
	v_pk_mul_f32 v[176:177], v[176:177], v[232:233] op_sel_hi:[1,0]
	v_cvt_pk_bf16_f32 v231, v236, v237
	global_store_dwordx4 v[238:239], v[228:231], off
	v_pk_mul_f32 v[176:177], v[128:129], v[176:177]
	s_nop 0
	v_pk_mul_f32 v[228:229], v[242:243], v[232:233] op_sel_hi:[1,0]
	v_pk_mul_f32 v[230:231], v[240:241], v[232:233] op_sel_hi:[1,0]
	v_pk_mul_f32 v[228:229], v[132:133], v[228:229]
	v_pk_mul_f32 v[230:231], v[134:135], v[230:231]
	v_pk_mul_f32 v[232:233], v[248:249], v[232:233] op_sel_hi:[1,0]
	v_cvt_pk_bf16_f32 v228, v228, v229
	v_cvt_pk_bf16_f32 v229, v230, v231
	v_cvt_pk_bf16_f32 v230, v176, v177
	v_ffbh_u32_e32 v176, v189
	v_pk_mul_f32 v[232:233], v[130:131], v[232:233]
	s_nop 0
	v_cvt_pk_bf16_f32 v231, v232, v233
	global_store_dwordx4 v[238:239], v[228:231], off offset:64
	s_nop 1
	v_min_u32_e32 v228, 32, v176
	v_lshlrev_b64 v[176:177], v228, v[188:189]
	v_min_u32_e32 v176, 1, v176
	v_or_b32_e32 v176, v177, v176
	v_cvt_f32_u32_e32 v176, v176
	v_sub_u32_e32 v177, 32, v228
	v_ldexp_f32 v176, v176, v177
	v_mul_f32_e32 v176, 0x35800000, v176
	v_fmamk_f32 v176, v176, 0x3a800000, v210
	s_nop 0
	v_rsq_f32_e32 v176, v176
	s_nop 0
	v_pk_mul_f32 v[228:229], v[44:45], v[176:177] op_sel_hi:[1,0]
	v_pk_mul_f32 v[230:231], v[46:47], v[176:177] op_sel_hi:[1,0]
	v_pk_mul_f32 v[234:235], v[228:229], v[228:229]
	v_pk_mul_f32 v[232:233], v[230:231], v[230:231]
	v_pk_mul_f32 v[248:249], v[34:35], v[176:177] op_sel_hi:[1,0]
	v_pk_mov_b32 v[236:237], v[234:235], v[232:233] op_sel:[1,0]
	v_mov_b32_e32 v235, v233
	v_pk_add_f32 v[232:233], v[236:237], v[234:235]
	v_pk_mul_f32 v[234:235], v[40:41], v[176:177] op_sel_hi:[1,0]
	v_pk_mul_f32 v[236:237], v[42:43], v[176:177] op_sel_hi:[1,0]
	v_pk_mul_f32 v[240:241], v[234:235], v[234:235]
	v_pk_mul_f32 v[238:239], v[236:237], v[236:237]
	v_pk_add_f32 v[232:233], v[232:233], v[232:233] op_sel_hi:[0,1]
	v_pk_mov_b32 v[242:243], v[240:241], v[238:239] op_sel:[1,0]
	v_mov_b32_e32 v241, v239
	v_pk_add_f32 v[238:239], v[242:243], v[240:241]
	v_pk_mul_f32 v[242:243], v[36:37], v[176:177] op_sel_hi:[1,0]
	v_pk_mul_f32 v[240:241], v[38:39], v[176:177] op_sel_hi:[1,0]
	v_mul_f32_e32 v232, v242, v242
	v_pk_fma_f32 v[244:245], v[242:243], v[242:243], v[232:233] op_sel_hi:[1,1,0]
	v_mul_f32_e32 v232, v240, v240
	v_pk_add_f32 v[238:239], v[238:239], v[238:239] op_sel_hi:[0,1]
	v_pk_fma_f32 v[246:247], v[240:241], v[240:241], v[232:233] op_sel_hi:[1,1,0]
	v_pk_mul_f32 v[176:177], v[32:33], v[176:177] op_sel_hi:[1,0]
	v_mul_f32_e32 v232, v248, v248
	v_mul_f32_e32 v244, v176, v176
	v_mul_f32_e32 v246, v177, v177
	v_mul_f32_e32 v238, v249, v249
	v_pk_add_f32 v[244:245], v[244:245], v[246:247]
	v_pk_add_f32 v[232:233], v[232:233], v[238:239]
	v_lshlrev_b64 v[238:239], 10, v[164:165]
	v_pk_add_f32 v[232:233], v[244:245], v[232:233]
	v_lshl_add_u64 v[238:239], v[206:207], 0, v[238:239]
	v_add_f32_e32 v232, v232, v233
	ds_bpermute_b32 v233, v225, v232
	s_waitcnt lgkmcnt(0)
	v_add_f32_e32 v232, v232, v233
	ds_bpermute_b32 v233, v224, v232
	s_waitcnt lgkmcnt(0)
	v_add_f32_e32 v232, v232, v233
	v_fmamk_f32 v232, v232, 0x3c800000, v210
	s_nop 0
	v_rsq_f32_e32 v232, v232
	s_nop 0
	v_mul_f32_e32 v232, v223, v232
	v_pk_mul_f32 v[228:229], v[228:229], v[232:233] op_sel_hi:[1,0]
	v_pk_mul_f32 v[230:231], v[230:231], v[232:233] op_sel_hi:[1,0]
	v_pk_mul_f32 v[228:229], v[140:141], v[228:229]
	v_pk_mul_f32 v[230:231], v[142:143], v[230:231]
	v_pk_mul_f32 v[234:235], v[234:235], v[232:233] op_sel_hi:[1,0]
	v_pk_mul_f32 v[236:237], v[236:237], v[232:233] op_sel_hi:[1,0]
	v_pk_mul_f32 v[234:235], v[136:137], v[234:235]
	v_pk_mul_f32 v[236:237], v[138:139], v[236:237]
	v_cvt_pk_bf16_f32 v228, v228, v229
	v_cvt_pk_bf16_f32 v229, v230, v231
	v_cvt_pk_bf16_f32 v230, v234, v235
	v_pk_mul_f32 v[176:177], v[176:177], v[232:233] op_sel_hi:[1,0]
	v_cvt_pk_bf16_f32 v231, v236, v237
	global_store_dwordx4 v[238:239], v[228:231], off
	v_pk_mul_f32 v[176:177], v[128:129], v[176:177]
	s_nop 0
	v_pk_mul_f32 v[228:229], v[242:243], v[232:233] op_sel_hi:[1,0]
	v_pk_mul_f32 v[230:231], v[240:241], v[232:233] op_sel_hi:[1,0]
	v_pk_mul_f32 v[228:229], v[132:133], v[228:229]
	v_pk_mul_f32 v[230:231], v[134:135], v[230:231]
	v_pk_mul_f32 v[232:233], v[248:249], v[232:233] op_sel_hi:[1,0]
	v_cvt_pk_bf16_f32 v228, v228, v229
	v_cvt_pk_bf16_f32 v229, v230, v231
	v_cvt_pk_bf16_f32 v230, v176, v177
	v_ffbh_u32_e32 v176, v163
	v_pk_mul_f32 v[232:233], v[130:131], v[232:233]
	s_nop 0
	v_cvt_pk_bf16_f32 v231, v232, v233
	global_store_dwordx4 v[238:239], v[228:231], off offset:64
	s_nop 1
	v_min_u32_e32 v228, 32, v176
	v_lshlrev_b64 v[176:177], v228, v[162:163]
	v_min_u32_e32 v176, 1, v176
	v_or_b32_e32 v176, v177, v176
	v_cvt_f32_u32_e32 v176, v176
	v_sub_u32_e32 v177, 32, v228
	v_ldexp_f32 v176, v176, v177
	v_mul_f32_e32 v176, 0x35800000, v176
	v_fmamk_f32 v176, v176, 0x3a800000, v210
	s_nop 0
	v_rsq_f32_e32 v176, v176
	s_nop 0
	v_pk_mul_f32 v[228:229], v[28:29], v[176:177] op_sel_hi:[1,0]
	v_pk_mul_f32 v[230:231], v[30:31], v[176:177] op_sel_hi:[1,0]
	v_pk_mul_f32 v[234:235], v[228:229], v[228:229]
	v_pk_mul_f32 v[232:233], v[230:231], v[230:231]
	v_pk_mul_f32 v[248:249], v[18:19], v[176:177] op_sel_hi:[1,0]
	v_pk_mov_b32 v[236:237], v[234:235], v[232:233] op_sel:[1,0]
	v_mov_b32_e32 v235, v233
	v_pk_add_f32 v[232:233], v[236:237], v[234:235]
	v_pk_mul_f32 v[234:235], v[24:25], v[176:177] op_sel_hi:[1,0]
	v_pk_mul_f32 v[236:237], v[26:27], v[176:177] op_sel_hi:[1,0]
	v_pk_mul_f32 v[240:241], v[234:235], v[234:235]
	v_pk_mul_f32 v[238:239], v[236:237], v[236:237]
	v_pk_add_f32 v[232:233], v[232:233], v[232:233] op_sel_hi:[0,1]
	v_pk_mov_b32 v[242:243], v[240:241], v[238:239] op_sel:[1,0]
	v_mov_b32_e32 v241, v239
	v_pk_add_f32 v[238:239], v[242:243], v[240:241]
	v_pk_mul_f32 v[242:243], v[20:21], v[176:177] op_sel_hi:[1,0]
	v_pk_mul_f32 v[240:241], v[22:23], v[176:177] op_sel_hi:[1,0]
	v_mul_f32_e32 v232, v242, v242
	v_pk_fma_f32 v[244:245], v[242:243], v[242:243], v[232:233] op_sel_hi:[1,1,0]
	v_mul_f32_e32 v232, v240, v240
	v_pk_add_f32 v[238:239], v[238:239], v[238:239] op_sel_hi:[0,1]
	v_pk_fma_f32 v[246:247], v[240:241], v[240:241], v[232:233] op_sel_hi:[1,1,0]
	v_pk_mul_f32 v[176:177], v[16:17], v[176:177] op_sel_hi:[1,0]
	v_mul_f32_e32 v232, v248, v248
	v_mul_f32_e32 v244, v176, v176
	v_mul_f32_e32 v246, v177, v177
	v_mul_f32_e32 v238, v249, v249
	v_pk_add_f32 v[244:245], v[244:245], v[246:247]
	v_pk_add_f32 v[232:233], v[232:233], v[238:239]
	v_lshlrev_b64 v[238:239], 10, v[158:159]
	v_pk_add_f32 v[232:233], v[244:245], v[232:233]
	v_lshl_add_u64 v[238:239], v[206:207], 0, v[238:239]
	v_add_f32_e32 v232, v232, v233
	ds_bpermute_b32 v233, v225, v232
	s_waitcnt lgkmcnt(0)
	v_add_f32_e32 v232, v232, v233
	ds_bpermute_b32 v233, v224, v232
	s_waitcnt lgkmcnt(0)
	v_add_f32_e32 v232, v232, v233
	v_fmamk_f32 v232, v232, 0x3c800000, v210
	s_nop 0
	v_rsq_f32_e32 v232, v232
	s_nop 0
	v_mul_f32_e32 v232, v223, v232
	v_pk_mul_f32 v[228:229], v[228:229], v[232:233] op_sel_hi:[1,0]
	v_pk_mul_f32 v[230:231], v[230:231], v[232:233] op_sel_hi:[1,0]
	v_pk_mul_f32 v[228:229], v[140:141], v[228:229]
	v_pk_mul_f32 v[230:231], v[142:143], v[230:231]
	v_pk_mul_f32 v[234:235], v[234:235], v[232:233] op_sel_hi:[1,0]
	v_pk_mul_f32 v[236:237], v[236:237], v[232:233] op_sel_hi:[1,0]
	v_pk_mul_f32 v[234:235], v[136:137], v[234:235]
	v_pk_mul_f32 v[236:237], v[138:139], v[236:237]
	v_cvt_pk_bf16_f32 v228, v228, v229
	v_cvt_pk_bf16_f32 v229, v230, v231
	v_cvt_pk_bf16_f32 v230, v234, v235
	v_pk_mul_f32 v[176:177], v[176:177], v[232:233] op_sel_hi:[1,0]
	v_cvt_pk_bf16_f32 v231, v236, v237
	global_store_dwordx4 v[238:239], v[228:231], off
	v_pk_mul_f32 v[176:177], v[128:129], v[176:177]
	s_nop 0
	v_pk_mul_f32 v[228:229], v[242:243], v[232:233] op_sel_hi:[1,0]
	v_pk_mul_f32 v[230:231], v[240:241], v[232:233] op_sel_hi:[1,0]
	v_pk_mul_f32 v[228:229], v[132:133], v[228:229]
	v_pk_mul_f32 v[230:231], v[134:135], v[230:231]
	v_pk_mul_f32 v[232:233], v[248:249], v[232:233] op_sel_hi:[1,0]
	v_cvt_pk_bf16_f32 v228, v228, v229
	v_cvt_pk_bf16_f32 v229, v230, v231
	v_cvt_pk_bf16_f32 v230, v176, v177
	v_ffbh_u32_e32 v176, v161
	v_pk_mul_f32 v[232:233], v[130:131], v[232:233]
	s_nop 0
	v_cvt_pk_bf16_f32 v231, v232, v233
	global_store_dwordx4 v[238:239], v[228:231], off offset:64
	s_nop 1
	v_min_u32_e32 v228, 32, v176
	v_lshlrev_b64 v[176:177], v228, v[160:161]
	v_min_u32_e32 v176, 1, v176
	v_or_b32_e32 v176, v177, v176
	v_cvt_f32_u32_e32 v176, v176
	v_sub_u32_e32 v177, 32, v228
	v_ldexp_f32 v176, v176, v177
	v_mul_f32_e32 v176, 0x35800000, v176
	v_fmamk_f32 v176, v176, 0x3a800000, v210
	s_nop 0
	v_rsq_f32_e32 v176, v176
	s_nop 0
	v_pk_mul_f32 v[228:229], v[12:13], v[176:177] op_sel_hi:[1,0]
	v_pk_mul_f32 v[230:231], v[14:15], v[176:177] op_sel_hi:[1,0]
	v_pk_mul_f32 v[234:235], v[228:229], v[228:229]
	v_pk_mul_f32 v[232:233], v[230:231], v[230:231]
	v_pk_mul_f32 v[248:249], v[2:3], v[176:177] op_sel_hi:[1,0]
	v_pk_mov_b32 v[236:237], v[234:235], v[232:233] op_sel:[1,0]
	v_mov_b32_e32 v235, v233
	v_pk_add_f32 v[232:233], v[236:237], v[234:235]
	v_pk_mul_f32 v[234:235], v[8:9], v[176:177] op_sel_hi:[1,0]
	v_pk_mul_f32 v[236:237], v[10:11], v[176:177] op_sel_hi:[1,0]
	v_pk_mul_f32 v[240:241], v[234:235], v[234:235]
	v_pk_mul_f32 v[238:239], v[236:237], v[236:237]
	v_pk_add_f32 v[232:233], v[232:233], v[232:233] op_sel_hi:[0,1]
	v_pk_mov_b32 v[242:243], v[240:241], v[238:239] op_sel:[1,0]
	v_mov_b32_e32 v241, v239
	v_pk_add_f32 v[238:239], v[242:243], v[240:241]
	v_pk_mul_f32 v[242:243], v[4:5], v[176:177] op_sel_hi:[1,0]
	v_pk_mul_f32 v[240:241], v[6:7], v[176:177] op_sel_hi:[1,0]
	v_mul_f32_e32 v232, v242, v242
	v_pk_fma_f32 v[244:245], v[242:243], v[242:243], v[232:233] op_sel_hi:[1,1,0]
	v_mul_f32_e32 v232, v240, v240
	v_pk_add_f32 v[238:239], v[238:239], v[238:239] op_sel_hi:[0,1]
	v_pk_fma_f32 v[246:247], v[240:241], v[240:241], v[232:233] op_sel_hi:[1,1,0]
	v_pk_mul_f32 v[176:177], v[0:1], v[176:177] op_sel_hi:[1,0]
	v_mul_f32_e32 v232, v248, v248
	v_mul_f32_e32 v244, v176, v176
	v_mul_f32_e32 v246, v177, v177
	v_mul_f32_e32 v238, v249, v249
	v_pk_add_f32 v[244:245], v[244:245], v[246:247]
	v_pk_add_f32 v[232:233], v[232:233], v[238:239]
	s_nop 0
	v_pk_add_f32 v[232:233], v[244:245], v[232:233]
	s_nop 0
	v_add_f32_e32 v232, v232, v233
	ds_bpermute_b32 v225, v225, v232
	s_waitcnt lgkmcnt(0)
	v_add_f32_e32 v225, v232, v225
	ds_bpermute_b32 v224, v224, v225
	v_lshlrev_b64 v[232:233], 10, v[156:157]
	v_lshl_add_u64 v[206:207], v[206:207], 0, v[232:233]
	s_waitcnt lgkmcnt(0)
	v_add_f32_e32 v224, v225, v224
	v_fmamk_f32 v224, v224, 0x3c800000, v210
	s_nop 0
	v_rsq_f32_e32 v224, v224
	s_nop 0
	v_mul_f32_e32 v224, v223, v224
	v_pk_mul_f32 v[228:229], v[228:229], v[224:225] op_sel_hi:[1,0]
	v_pk_mul_f32 v[230:231], v[230:231], v[224:225] op_sel_hi:[1,0]
	v_pk_mul_f32 v[140:141], v[140:141], v[228:229]
	v_pk_mul_f32 v[142:143], v[142:143], v[230:231]
	v_pk_mul_f32 v[228:229], v[234:235], v[224:225] op_sel_hi:[1,0]
	v_pk_mul_f32 v[230:231], v[236:237], v[224:225] op_sel_hi:[1,0]
	s_nop 0
	v_pk_mul_f32 v[230:231], v[138:139], v[230:231]
	v_pk_mul_f32 v[138:139], v[136:137], v[228:229]
	v_cvt_pk_bf16_f32 v136, v140, v141
	v_cvt_pk_bf16_f32 v137, v142, v143
	s_nop 0
	v_cvt_pk_bf16_f32 v138, v138, v139
	v_cvt_pk_bf16_f32 v139, v230, v231
	global_store_dwordx4 v[206:207], v[136:139], off
	s_nop 1
	v_pk_mul_f32 v[136:137], v[242:243], v[224:225] op_sel_hi:[1,0]
	v_pk_mul_f32 v[138:139], v[240:241], v[224:225] op_sel_hi:[1,0]
	v_pk_mul_f32 v[132:133], v[132:133], v[136:137]
	v_pk_mul_f32 v[134:135], v[134:135], v[138:139]
	v_pk_mul_f32 v[136:137], v[176:177], v[224:225] op_sel_hi:[1,0]
	v_pk_mul_f32 v[138:139], v[248:249], v[224:225] op_sel_hi:[1,0]
	s_nop 0
	v_pk_mul_f32 v[138:139], v[130:131], v[138:139]
	v_pk_mul_f32 v[130:131], v[128:129], v[136:137]
	v_cvt_pk_bf16_f32 v128, v132, v133
	v_cvt_pk_bf16_f32 v129, v134, v135
	s_nop 0
	v_cvt_pk_bf16_f32 v130, v130, v131
	v_cvt_pk_bf16_f32 v131, v138, v139
	s_nop 1

.LBB0_341:
	s_lshl_b64 s[30:31], s[36:37], 13
	s_sub_u32 s30, 0, s30
	s_subb_u32 s31, 0, s31
	s_add_u32 s30, s22, s30
	v_readlane_b32 s22, v254, 54
	s_addc_u32 s31, s22, s31
	s_add_u32 s42, s30, 0x4c00000
	s_addc_u32 s43, s31, 0
	v_bfe_u32 v16, v8, 4, 2
	s_add_u32 s44, s30, 0x5000000
	v_and_b32_e32 v15, 15, v8
	v_lshlrev_b32_e32 v17, 4, v16
	v_lshlrev_b32_e32 v18, 2, v8
	s_addc_u32 s45, s31, 0
	v_lshl_or_b32 v190, s25, 6, v15
	v_lshl_or_b32 v17, v15, 6, v17
	s_lshl_b32 s25, s25, 13
	v_and_b32_e32 v18, 32, v18
	v_bitop3_b32 v19, v17, s25, v18 bitop3:0xde
	s_lshl_b32 s25, s27, 5
	s_and_b32 s79, s25, 0x60
	s_add_i32 m0, s77, 0x18000
	v_lshl_add_u64 v[6:7], v[6:7], 0, s[18:19]
	s_lshl_b32 s25, s79, 7
	s_waitcnt vmcnt(2)
	s_barrier
	global_load_lds_dwordx4 v[6:7], off
	v_lshl_add_u64 v[4:5], v[4:5], 0, s[18:19]
	s_add_i32 m0, s77, 0x1a000
	s_add_i32 s80, s77, 0x8000
	s_add_i32 s83, s77, 0xa000
	global_load_lds_dwordx4 v[4:5], off
	v_lshl_add_u64 v[2:3], v[2:3], 0, s[18:19]
	s_mov_b32 m0, s80
	s_add_u32 s30, s50, 0x40080
	global_load_lds_dwordx4 v[2:3], off
	v_lshl_add_u64 v[0:1], v[0:1], 0, s[18:19]
	s_mov_b32 m0, s83
	s_addc_u32 s31, s51, 0
	global_load_lds_dwordx4 v[0:1], off
	s_add_i32 m0, s77, 0x1c000
	v_lshl_add_u64 v[0:1], s[30:31], 0, v[148:149]
	global_load_lds_dwordx4 v[0:1], off
	v_lshl_add_u64 v[0:1], s[30:31], 0, v[152:153]
	s_add_i32 m0, s77, 0x1e000
	v_and_b32_e32 v3, 1, v9
	global_load_lds_dwordx4 v[0:1], off
	v_lshrrev_b32_e32 v1, 2, v8
	v_and_b32_e32 v2, 4, v1
	v_lshlrev_b32_e32 v1, 14, v9
	v_and_b32_e32 v1, 0xffff8000, v1
	v_lshl_add_u32 v1, v10, 11, v1
	v_lshl_or_b32 v1, v3, 6, v1
	v_lshl_add_u32 v156, v11, 1, v1
	v_lshlrev_b32_e32 v1, 14, v12
	v_and_b32_e32 v1, 0xffff8000, v1
	v_lshlrev_b32_e32 v191, 3, v16
	s_waitcnt vmcnt(6)
	v_readlane_b32 s30, v252, 36
	v_lshl_add_u32 v1, v13, 11, v1
	v_and_b32_e32 v3, 1, v12
	v_and_b32_e32 v0, 16, v191
	v_lshlrev_b32_e32 v144, 6, v16
	v_readlane_b32 s31, v252, 37
	v_lshl_or_b32 v1, v3, 6, v1
	s_sext_i32_i16 s11, s38
	v_bitop3_b32 v192, v17, s25, v18 bitop3:0xde
	v_add_u32_e32 v192, 0x10000, v192
	v_add_u32_e32 v193, 0xfffffe00, v190
	s_mov_b32 s84, 0
	v_cmp_eq_u32_e64 s[38:39], 0, v15
	v_lshl_add_u64 v[154:155], s[30:31], 0, v[144:145]
	v_mov_b32_e32 v157, v145
	v_lshl_add_u32 v158, v14, 1, v1
	v_mov_b32_e32 v159, v145
	v_add_u32_e32 v194, 0, v19
	v_lshlrev_b32_e32 v144, 1, v0
	v_lshlrev_b32_e32 v160, 1, v2
	s_barrier
	v_readfirstlane_b32 s101, v208
	s_nop 3
	s_lshr_b32 s101, s101, 8
	s_cmp_eq_u32 s101, 0
	s_cbranch_scc1 .Lprio_a2_done
	s_setprio 1

.LBB0_350:
	s_nop 0
	s_lshl_b32 s25, s84, 1
	s_add_i32 s25, s85, s25
	s_and_b32 s85, s25, 3
	s_lshl_b32 s25, s85, 19
	s_add_u32 s92, s74, s25
	v_cmp_lt_i64_e32 vcc, s[52:53], v[180:181]
	s_addc_u32 s93, s75, 0
	s_and_b64 s[30:31], vcc, exec
	s_cselect_b32 s25, s93, s1
	s_cselect_b32 s30, s92, s0
	s_ashr_i32 s47, s46, 31
	s_lshl_b64 s[34:35], s[46:47], 19
	s_add_u32 s94, s54, s34
	s_addc_u32 s95, s55, s35
	s_and_b64 s[34:35], vcc, exec
	s_cselect_b32 s31, s95, s51
	s_cselect_b32 s33, s94, s50
	s_add_u32 s0, s0, 0x40080
	s_addc_u32 s1, s1, 0
	s_add_u32 s34, s50, 0x100
	s_addc_u32 s35, s51, 0
	s_mov_b32 s36, -2
	s_add_u32 s27, s0, 0xfffc0080
	s_addc_u32 s37, s1, -1
	s_add_i32 s47, 0, 0x10000
	ds_read_b128 v[128:131], v192
	ds_read_b128 v[132:135], v192 offset:1024
	ds_read_b128 v[136:139], v192 offset:2048
	ds_read_b128 v[140:143], v192 offset:3072
	s_cmp_eq_u32 s36, 12
	s_cselect_b32 s53, s25, s37
	s_cselect_b32 s52, s30, s27
	s_cselect_b32 s51, s31, s35
	s_cselect_b32 s50, s33, s34
	s_add_i32 m0, s77, 0xc000
	ds_read_b128 v[162:165], v194
	ds_read_b128 v[166:169], v194 offset:1024
	ds_read_b128 v[196:199], v194 offset:2048
	ds_read_b128 v[200:203], v194 offset:3072
	ds_read_b128 v[204:207], v194 offset:4096
	ds_read_b128 v[216:219], v194 offset:5120
	ds_read_b128 v[220:223], v194 offset:6144
	ds_read_b128 v[228:231], v194 offset:7168
	s_waitcnt lgkmcnt(8)
	ds_read_b128 v[232:235], v192 offset:16384
	ds_read_b128 v[236:239], v192 offset:17408
	ds_read_b128 v[240:243], v192 offset:18432
	ds_read_b128 v[244:247], v192 offset:19456
	global_load_lds_dwordx4 v156, s[0:1]
	s_add_i32 m0, s77, 0xe000
	s_nop 0
	global_load_lds_dwordx4 v158, s[0:1]
	s_waitcnt lgkmcnt(0)
	s_waitcnt vmcnt(8)
	s_barrier
	v_mfma_f32_16x16x32_bf16 v[124:127], v[128:131], v[162:165], 0
	v_mfma_f32_16x16x32_bf16 v[120:123], v[136:139], v[162:165], 0
	v_mfma_f32_16x16x32_bf16 v[116:119], v[128:131], v[196:199], 0
	v_mfma_f32_16x16x32_bf16 v[112:115], v[136:139], v[196:199], 0
	v_mfma_f32_16x16x32_bf16 v[108:111], v[128:131], v[204:207], 0
	v_mfma_f32_16x16x32_bf16 v[104:107], v[136:139], v[204:207], 0
	v_mfma_f32_16x16x32_bf16 v[100:103], v[128:131], v[220:223], 0
	v_mfma_f32_16x16x32_bf16 v[96:99], v[136:139], v[220:223], 0
	v_mfma_f32_16x16x32_bf16 v[124:127], v[132:135], v[166:169], v[124:127]
	v_mfma_f32_16x16x32_bf16 v[120:123], v[140:143], v[166:169], v[120:123]
	v_mfma_f32_16x16x32_bf16 v[116:119], v[132:135], v[200:203], v[116:119]
	v_mfma_f32_16x16x32_bf16 v[112:115], v[140:143], v[200:203], v[112:115]
	v_mfma_f32_16x16x32_bf16 v[108:111], v[132:135], v[216:219], v[108:111]
	v_mfma_f32_16x16x32_bf16 v[104:107], v[140:143], v[216:219], v[104:107]
	v_mfma_f32_16x16x32_bf16 v[100:103], v[132:135], v[228:231], v[100:103]
	v_mfma_f32_16x16x32_bf16 v[96:99], v[140:143], v[228:231], v[96:99]
	v_mfma_f32_16x16x32_bf16 v[92:95], v[232:235], v[162:165], 0
	v_mfma_f32_16x16x32_bf16 v[88:91], v[240:243], v[162:165], 0
	v_mfma_f32_16x16x32_bf16 v[84:87], v[232:235], v[196:199], 0
	v_mfma_f32_16x16x32_bf16 v[80:83], v[240:243], v[196:199], 0
	v_mfma_f32_16x16x32_bf16 v[76:79], v[232:235], v[204:207], 0
	v_mfma_f32_16x16x32_bf16 v[72:75], v[240:243], v[204:207], 0
	v_mfma_f32_16x16x32_bf16 v[68:71], v[232:235], v[220:223], 0
	v_mfma_f32_16x16x32_bf16 v[64:67], v[240:243], v[220:223], 0
	v_mfma_f32_16x16x32_bf16 v[92:95], v[236:239], v[166:169], v[92:95]
	v_mfma_f32_16x16x32_bf16 v[88:91], v[244:247], v[166:169], v[88:91]
	v_mfma_f32_16x16x32_bf16 v[84:87], v[236:239], v[200:203], v[84:87]
	v_mfma_f32_16x16x32_bf16 v[80:83], v[244:247], v[200:203], v[80:83]
	v_mfma_f32_16x16x32_bf16 v[76:79], v[236:239], v[216:219], v[76:79]
	v_mfma_f32_16x16x32_bf16 v[72:75], v[244:247], v[216:219], v[72:75]
	v_mfma_f32_16x16x32_bf16 v[68:71], v[236:239], v[228:231], v[68:71]
	v_mfma_f32_16x16x32_bf16 v[64:67], v[244:247], v[228:231], v[64:67]
	s_barrier
	s_add_i32 s27, 0, 0x14000
	s_add_i32 s37, s47, s76
	s_mov_b32 m0, s37
	s_nop 0
	global_load_lds_dwordx4 v148, s[50:51]
	s_add_i32 m0, s37, 0x2000
	s_nop 0
	global_load_lds_dwordx4 v152, s[50:51]
	s_mov_b32 m0, s77
	v_lshl_add_u64 v[224:225], s[52:53], 0, v[146:147]
	ds_read_b128 v[162:165], v194 offset:16384
	ds_read_b128 v[166:169], v194 offset:17408
	ds_read_b128 v[196:199], v194 offset:18432
	ds_read_b128 v[200:203], v194 offset:19456
	ds_read_b128 v[204:207], v194 offset:20480
	ds_read_b128 v[216:219], v194 offset:21504
	ds_read_b128 v[220:223], v194 offset:22528
	ds_read_b128 v[228:231], v194 offset:23552
	global_load_lds_dwordx4 v[224:225], off
	v_lshl_add_u64 v[248:249], s[52:53], 0, v[150:151]
	s_mov_b32 m0, s78
	s_nop 0
	global_load_lds_dwordx4 v[248:249], off
	s_add_u32 s56, s50, 0x40000
	s_addc_u32 s57, s51, 0
	s_add_i32 s27, s27, s76
	s_mov_b32 m0, s27
	s_nop 0
	global_load_lds_dwordx4 v148, s[56:57]
	s_add_i32 m0, s27, 0x2000
	s_nop 0
	global_load_lds_dwordx4 v152, s[56:57]
	s_waitcnt lgkmcnt(0)
	s_waitcnt vmcnt(8)
	s_barrier
	v_mfma_f32_16x16x32_bf16 v[60:63], v[128:131], v[162:165], 0
	v_mfma_f32_16x16x32_bf16 v[56:59], v[136:139], v[162:165], 0
	v_mfma_f32_16x16x32_bf16 v[52:55], v[128:131], v[196:199], 0
	v_mfma_f32_16x16x32_bf16 v[48:51], v[136:139], v[196:199], 0
	v_mfma_f32_16x16x32_bf16 v[44:47], v[128:131], v[204:207], 0
	v_mfma_f32_16x16x32_bf16 v[40:43], v[136:139], v[204:207], 0
	v_mfma_f32_16x16x32_bf16 v[36:39], v[128:131], v[220:223], 0
	v_mfma_f32_16x16x32_bf16 v[32:35], v[136:139], v[220:223], 0
	v_mfma_f32_16x16x32_bf16 v[60:63], v[132:135], v[166:169], v[60:63]
	v_mfma_f32_16x16x32_bf16 v[56:59], v[140:143], v[166:169], v[56:59]
	v_mfma_f32_16x16x32_bf16 v[52:55], v[132:135], v[200:203], v[52:55]
	v_mfma_f32_16x16x32_bf16 v[48:51], v[140:143], v[200:203], v[48:51]
	v_mfma_f32_16x16x32_bf16 v[44:47], v[132:135], v[216:219], v[44:47]
	v_mfma_f32_16x16x32_bf16 v[40:43], v[140:143], v[216:219], v[40:43]
	v_mfma_f32_16x16x32_bf16 v[36:39], v[132:135], v[228:231], v[36:39]
	v_mfma_f32_16x16x32_bf16 v[32:35], v[140:143], v[228:231], v[32:35]
	v_mfma_f32_16x16x32_bf16 v[28:31], v[232:235], v[162:165], 0
	v_mfma_f32_16x16x32_bf16 v[24:27], v[240:243], v[162:165], 0
	v_mfma_f32_16x16x32_bf16 v[20:23], v[232:235], v[196:199], 0
	v_mfma_f32_16x16x32_bf16 v[16:19], v[240:243], v[196:199], 0
	v_mfma_f32_16x16x32_bf16 v[12:15], v[232:235], v[204:207], 0
	v_mfma_f32_16x16x32_bf16 v[8:11], v[240:243], v[204:207], 0
	v_mfma_f32_16x16x32_bf16 v[4:7], v[232:235], v[220:223], 0
	v_mfma_f32_16x16x32_bf16 v[0:3], v[240:243], v[220:223], 0
	v_mfma_f32_16x16x32_bf16 v[28:31], v[236:239], v[166:169], v[28:31]
	v_mfma_f32_16x16x32_bf16 v[24:27], v[244:247], v[166:169], v[24:27]
	v_mfma_f32_16x16x32_bf16 v[20:23], v[236:239], v[200:203], v[20:23]
	v_mfma_f32_16x16x32_bf16 v[16:19], v[244:247], v[200:203], v[16:19]
	v_mfma_f32_16x16x32_bf16 v[12:15], v[236:239], v[216:219], v[12:15]
	v_mfma_f32_16x16x32_bf16 v[8:11], v[244:247], v[216:219], v[8:11]
	v_mfma_f32_16x16x32_bf16 v[4:7], v[236:239], v[228:231], v[4:7]
	v_mfma_f32_16x16x32_bf16 v[0:3], v[244:247], v[228:231], v[0:3]
	s_barrier
	s_add_i32 s27, 0, 0x18000
	ds_read_b128 v[128:131], v192 offset:32768
	ds_read_b128 v[132:135], v192 offset:33792
	ds_read_b128 v[136:139], v192 offset:34816
	ds_read_b128 v[140:143], v192 offset:35840
	s_add_u32 s52, s52, 0x40000
	s_addc_u32 s53, s53, 0
	s_mov_b32 m0, s81
	ds_read_b128 v[162:165], v194 offset:32768
	ds_read_b128 v[166:169], v194 offset:33792
	ds_read_b128 v[196:199], v194 offset:34816
	ds_read_b128 v[200:203], v194 offset:35840
	ds_read_b128 v[204:207], v194 offset:36864
	ds_read_b128 v[216:219], v194 offset:37888
	ds_read_b128 v[220:223], v194 offset:38912
	ds_read_b128 v[228:231], v194 offset:39936
	s_waitcnt lgkmcnt(8)
	ds_read_b128 v[232:235], v192 offset:49152
	ds_read_b128 v[236:239], v192 offset:50176
	ds_read_b128 v[240:243], v192 offset:51200
	ds_read_b128 v[244:247], v192 offset:52224
	global_load_lds_dwordx4 v146, s[52:53]
	s_mov_b32 m0, s82
	s_nop 0
	global_load_lds_dwordx4 v150, s[52:53]
	s_waitcnt lgkmcnt(0)
	s_waitcnt vmcnt(8)
	s_barrier
	v_mfma_f32_16x16x32_bf16 v[124:127], v[128:131], v[162:165], v[124:127]
	v_mfma_f32_16x16x32_bf16 v[120:123], v[136:139], v[162:165], v[120:123]
	v_mfma_f32_16x16x32_bf16 v[116:119], v[128:131], v[196:199], v[116:119]
	v_mfma_f32_16x16x32_bf16 v[112:115], v[136:139], v[196:199], v[112:115]
	v_mfma_f32_16x16x32_bf16 v[108:111], v[128:131], v[204:207], v[108:111]
	v_mfma_f32_16x16x32_bf16 v[104:107], v[136:139], v[204:207], v[104:107]
	v_mfma_f32_16x16x32_bf16 v[100:103], v[128:131], v[220:223], v[100:103]
	v_mfma_f32_16x16x32_bf16 v[96:99], v[136:139], v[220:223], v[96:99]
	v_mfma_f32_16x16x32_bf16 v[124:127], v[132:135], v[166:169], v[124:127]
	v_mfma_f32_16x16x32_bf16 v[120:123], v[140:143], v[166:169], v[120:123]
	v_mfma_f32_16x16x32_bf16 v[116:119], v[132:135], v[200:203], v[116:119]
	v_mfma_f32_16x16x32_bf16 v[112:115], v[140:143], v[200:203], v[112:115]
	v_mfma_f32_16x16x32_bf16 v[108:111], v[132:135], v[216:219], v[108:111]
	v_mfma_f32_16x16x32_bf16 v[104:107], v[140:143], v[216:219], v[104:107]
	v_mfma_f32_16x16x32_bf16 v[100:103], v[132:135], v[228:231], v[100:103]
	v_mfma_f32_16x16x32_bf16 v[96:99], v[140:143], v[228:231], v[96:99]
	v_mfma_f32_16x16x32_bf16 v[92:95], v[232:235], v[162:165], v[92:95]
	v_mfma_f32_16x16x32_bf16 v[88:91], v[240:243], v[162:165], v[88:91]
	v_mfma_f32_16x16x32_bf16 v[84:87], v[232:235], v[196:199], v[84:87]
	v_mfma_f32_16x16x32_bf16 v[80:83], v[240:243], v[196:199], v[80:83]
	v_mfma_f32_16x16x32_bf16 v[76:79], v[232:235], v[204:207], v[76:79]
	v_mfma_f32_16x16x32_bf16 v[72:75], v[240:243], v[204:207], v[72:75]
	v_mfma_f32_16x16x32_bf16 v[68:71], v[232:235], v[220:223], v[68:71]
	v_mfma_f32_16x16x32_bf16 v[64:67], v[240:243], v[220:223], v[64:67]
	v_mfma_f32_16x16x32_bf16 v[92:95], v[236:239], v[166:169], v[92:95]
	v_mfma_f32_16x16x32_bf16 v[88:91], v[244:247], v[166:169], v[88:91]
	v_mfma_f32_16x16x32_bf16 v[84:87], v[236:239], v[200:203], v[84:87]
	v_mfma_f32_16x16x32_bf16 v[80:83], v[244:247], v[200:203], v[80:83]
	v_mfma_f32_16x16x32_bf16 v[76:79], v[236:239], v[216:219], v[76:79]
	v_mfma_f32_16x16x32_bf16 v[72:75], v[244:247], v[216:219], v[72:75]
	v_mfma_f32_16x16x32_bf16 v[68:71], v[236:239], v[228:231], v[68:71]
	v_mfma_f32_16x16x32_bf16 v[64:67], v[244:247], v[228:231], v[64:67]
	s_barrier
	s_add_i32 s37, 0, 0x1c000
	s_add_i32 s27, s27, s76
	s_add_u32 s56, s50, s18
	s_addc_u32 s57, s51, s19
	s_mov_b32 m0, s27
	s_nop 0
	global_load_lds_dwordx4 v148, s[56:57]
	s_add_u32 s56, s50, s18
	s_addc_u32 s57, s51, s19
	s_add_i32 m0, s27, 0x2000
	s_nop 0
	global_load_lds_dwordx4 v152, s[56:57]
	s_mov_b32 m0, s80
	v_lshl_add_u64 v[176:177], v[224:225], 0, s[18:19]
	ds_read_b128 v[162:165], v194 offset:49152
	ds_read_b128 v[166:169], v194 offset:50176
	ds_read_b128 v[196:199], v194 offset:51200
	ds_read_b128 v[200:203], v194 offset:52224
	ds_read_b128 v[204:207], v194 offset:53248
	ds_read_b128 v[216:219], v194 offset:54272
	ds_read_b128 v[220:223], v194 offset:55296
	ds_read_b128 v[228:231], v194 offset:56320
	global_load_lds_dwordx4 v[176:177], off
	v_lshl_add_u64 v[176:177], v[248:249], 0, s[18:19]
	s_mov_b32 m0, s83
	s_nop 0
	global_load_lds_dwordx4 v[176:177], off
	s_add_u32 s50, s50, 0x40080
	s_addc_u32 s51, s51, 0
	s_add_i32 s27, s37, s76
	s_mov_b32 m0, s27
	s_nop 0
	global_load_lds_dwordx4 v148, s[50:51]
	s_add_i32 m0, s27, 0x2000
	s_nop 0
	global_load_lds_dwordx4 v152, s[50:51]
	s_waitcnt lgkmcnt(0)
	s_waitcnt vmcnt(8)
	s_barrier
	v_mfma_f32_16x16x32_bf16 v[60:63], v[128:131], v[162:165], v[60:63]
	v_mfma_f32_16x16x32_bf16 v[56:59], v[136:139], v[162:165], v[56:59]
	v_mfma_f32_16x16x32_bf16 v[52:55], v[128:131], v[196:199], v[52:55]
	v_mfma_f32_16x16x32_bf16 v[48:51], v[136:139], v[196:199], v[48:51]
	v_mfma_f32_16x16x32_bf16 v[44:47], v[128:131], v[204:207], v[44:47]
	v_mfma_f32_16x16x32_bf16 v[40:43], v[136:139], v[204:207], v[40:43]
	v_mfma_f32_16x16x32_bf16 v[36:39], v[128:131], v[220:223], v[36:39]
	v_mfma_f32_16x16x32_bf16 v[32:35], v[136:139], v[220:223], v[32:35]
	v_mfma_f32_16x16x32_bf16 v[60:63], v[132:135], v[166:169], v[60:63]
	v_mfma_f32_16x16x32_bf16 v[56:59], v[140:143], v[166:169], v[56:59]
	v_mfma_f32_16x16x32_bf16 v[52:55], v[132:135], v[200:203], v[52:55]
	v_mfma_f32_16x16x32_bf16 v[48:51], v[140:143], v[200:203], v[48:51]
	v_mfma_f32_16x16x32_bf16 v[44:47], v[132:135], v[216:219], v[44:47]
	v_mfma_f32_16x16x32_bf16 v[40:43], v[140:143], v[216:219], v[40:43]
	v_mfma_f32_16x16x32_bf16 v[36:39], v[132:135], v[228:231], v[36:39]
	v_mfma_f32_16x16x32_bf16 v[32:35], v[140:143], v[228:231], v[32:35]
	v_mfma_f32_16x16x32_bf16 v[28:31], v[232:235], v[162:165], v[28:31]
	v_mfma_f32_16x16x32_bf16 v[24:27], v[240:243], v[162:165], v[24:27]
	v_mfma_f32_16x16x32_bf16 v[20:23], v[232:235], v[196:199], v[20:23]
	v_mfma_f32_16x16x32_bf16 v[16:19], v[240:243], v[196:199], v[16:19]
	v_mfma_f32_16x16x32_bf16 v[12:15], v[232:235], v[204:207], v[12:15]
	v_mfma_f32_16x16x32_bf16 v[8:11], v[240:243], v[204:207], v[8:11]
	v_mfma_f32_16x16x32_bf16 v[4:7], v[232:235], v[220:223], v[4:7]
	v_mfma_f32_16x16x32_bf16 v[0:3], v[240:243], v[220:223], v[0:3]
	v_mfma_f32_16x16x32_bf16 v[28:31], v[236:239], v[166:169], v[28:31]
	v_mfma_f32_16x16x32_bf16 v[24:27], v[244:247], v[166:169], v[24:27]
	v_mfma_f32_16x16x32_bf16 v[20:23], v[236:239], v[200:203], v[20:23]
	v_mfma_f32_16x16x32_bf16 v[16:19], v[244:247], v[200:203], v[16:19]
	v_mfma_f32_16x16x32_bf16 v[12:15], v[236:239], v[216:219], v[12:15]
	v_mfma_f32_16x16x32_bf16 v[8:11], v[244:247], v[216:219], v[8:11]
	v_mfma_f32_16x16x32_bf16 v[4:7], v[236:239], v[228:231], v[4:7]
	v_mfma_f32_16x16x32_bf16 v[0:3], v[244:247], v[228:231], v[0:3]
	s_barrier
	s_add_i32 s36, s36, 2
	s_add_u32 s0, s0, 0x100
	s_addc_u32 s1, s1, 0
	s_add_u32 s34, s34, 0x100
	s_addc_u32 s35, s35, 0
	s_cmp_gt_u32 s36, 13
.LBB0_351:
	s_nop 0
	s_add_u32 s27, s0, 0xfffc0080
	s_addc_u32 s37, s1, -1
	s_add_i32 s47, 0, 0x10000
	ds_read_b128 v[128:131], v192
	ds_read_b128 v[132:135], v192 offset:1024
	ds_read_b128 v[136:139], v192 offset:2048
	ds_read_b128 v[140:143], v192 offset:3072
	s_cmp_eq_u32 s36, 12
	s_cselect_b32 s53, s25, s37
	s_cselect_b32 s52, s30, s27
	s_cselect_b32 s51, s31, s35
	s_cselect_b32 s50, s33, s34
	s_add_i32 m0, s77, 0xc000
	ds_read_b128 v[162:165], v194
	ds_read_b128 v[166:169], v194 offset:1024
	ds_read_b128 v[196:199], v194 offset:2048
	ds_read_b128 v[200:203], v194 offset:3072
	ds_read_b128 v[204:207], v194 offset:4096
	ds_read_b128 v[216:219], v194 offset:5120
	ds_read_b128 v[220:223], v194 offset:6144
	ds_read_b128 v[228:231], v194 offset:7168
	s_waitcnt lgkmcnt(8)
	ds_read_b128 v[232:235], v192 offset:16384
	ds_read_b128 v[236:239], v192 offset:17408
	ds_read_b128 v[240:243], v192 offset:18432
	ds_read_b128 v[244:247], v192 offset:19456
	global_load_lds_dwordx4 v156, s[0:1]
	s_add_i32 m0, s77, 0xe000
	s_nop 0
	global_load_lds_dwordx4 v158, s[0:1]
	s_waitcnt lgkmcnt(0)
	s_waitcnt vmcnt(8)
	s_barrier
	v_mfma_f32_16x16x32_bf16 v[124:127], v[128:131], v[162:165], v[124:127]
	v_mfma_f32_16x16x32_bf16 v[120:123], v[136:139], v[162:165], v[120:123]
	v_mfma_f32_16x16x32_bf16 v[116:119], v[128:131], v[196:199], v[116:119]
	v_mfma_f32_16x16x32_bf16 v[112:115], v[136:139], v[196:199], v[112:115]
	v_mfma_f32_16x16x32_bf16 v[108:111], v[128:131], v[204:207], v[108:111]
	v_mfma_f32_16x16x32_bf16 v[104:107], v[136:139], v[204:207], v[104:107]
	v_mfma_f32_16x16x32_bf16 v[100:103], v[128:131], v[220:223], v[100:103]
	v_mfma_f32_16x16x32_bf16 v[96:99], v[136:139], v[220:223], v[96:99]
	v_mfma_f32_16x16x32_bf16 v[124:127], v[132:135], v[166:169], v[124:127]
	v_mfma_f32_16x16x32_bf16 v[120:123], v[140:143], v[166:169], v[120:123]
	v_mfma_f32_16x16x32_bf16 v[116:119], v[132:135], v[200:203], v[116:119]
	v_mfma_f32_16x16x32_bf16 v[112:115], v[140:143], v[200:203], v[112:115]
	v_mfma_f32_16x16x32_bf16 v[108:111], v[132:135], v[216:219], v[108:111]
	v_mfma_f32_16x16x32_bf16 v[104:107], v[140:143], v[216:219], v[104:107]
	v_mfma_f32_16x16x32_bf16 v[100:103], v[132:135], v[228:231], v[100:103]
	v_mfma_f32_16x16x32_bf16 v[96:99], v[140:143], v[228:231], v[96:99]
	v_mfma_f32_16x16x32_bf16 v[92:95], v[232:235], v[162:165], v[92:95]
	v_mfma_f32_16x16x32_bf16 v[88:91], v[240:243], v[162:165], v[88:91]
	v_mfma_f32_16x16x32_bf16 v[84:87], v[232:235], v[196:199], v[84:87]
	v_mfma_f32_16x16x32_bf16 v[80:83], v[240:243], v[196:199], v[80:83]
	v_mfma_f32_16x16x32_bf16 v[76:79], v[232:235], v[204:207], v[76:79]
	v_mfma_f32_16x16x32_bf16 v[72:75], v[240:243], v[204:207], v[72:75]
	v_mfma_f32_16x16x32_bf16 v[68:71], v[232:235], v[220:223], v[68:71]
	v_mfma_f32_16x16x32_bf16 v[64:67], v[240:243], v[220:223], v[64:67]
	v_mfma_f32_16x16x32_bf16 v[92:95], v[236:239], v[166:169], v[92:95]
	v_mfma_f32_16x16x32_bf16 v[88:91], v[244:247], v[166:169], v[88:91]
	v_mfma_f32_16x16x32_bf16 v[84:87], v[236:239], v[200:203], v[84:87]
	v_mfma_f32_16x16x32_bf16 v[80:83], v[244:247], v[200:203], v[80:83]
	v_mfma_f32_16x16x32_bf16 v[76:79], v[236:239], v[216:219], v[76:79]
	v_mfma_f32_16x16x32_bf16 v[72:75], v[244:247], v[216:219], v[72:75]
	v_mfma_f32_16x16x32_bf16 v[68:71], v[236:239], v[228:231], v[68:71]
	v_mfma_f32_16x16x32_bf16 v[64:67], v[244:247], v[228:231], v[64:67]
	s_barrier
	s_add_i32 s27, 0, 0x14000
	s_add_i32 s37, s47, s76
	s_mov_b32 m0, s37
	s_nop 0
	global_load_lds_dwordx4 v148, s[50:51]
	s_add_i32 m0, s37, 0x2000
	s_nop 0
	global_load_lds_dwordx4 v152, s[50:51]
	s_mov_b32 m0, s77
	v_lshl_add_u64 v[224:225], s[52:53], 0, v[146:147]
	ds_read_b128 v[162:165], v194 offset:16384
	ds_read_b128 v[166:169], v194 offset:17408
	ds_read_b128 v[196:199], v194 offset:18432
	ds_read_b128 v[200:203], v194 offset:19456
	ds_read_b128 v[204:207], v194 offset:20480
	ds_read_b128 v[216:219], v194 offset:21504
	ds_read_b128 v[220:223], v194 offset:22528
	ds_read_b128 v[228:231], v194 offset:23552
	global_load_lds_dwordx4 v[224:225], off
	v_lshl_add_u64 v[248:249], s[52:53], 0, v[150:151]
	s_mov_b32 m0, s78
	s_nop 0
	global_load_lds_dwordx4 v[248:249], off
	s_add_u32 s56, s50, 0x40000
	s_addc_u32 s57, s51, 0
	s_add_i32 s27, s27, s76
	s_mov_b32 m0, s27
	s_nop 0
	global_load_lds_dwordx4 v148, s[56:57]
	s_add_i32 m0, s27, 0x2000
	s_nop 0
	global_load_lds_dwordx4 v152, s[56:57]
	s_waitcnt lgkmcnt(0)
	s_waitcnt vmcnt(8)
	s_barrier
	v_mfma_f32_16x16x32_bf16 v[60:63], v[128:131], v[162:165], v[60:63]
	v_mfma_f32_16x16x32_bf16 v[56:59], v[136:139], v[162:165], v[56:59]
	v_mfma_f32_16x16x32_bf16 v[52:55], v[128:131], v[196:199], v[52:55]
	v_mfma_f32_16x16x32_bf16 v[48:51], v[136:139], v[196:199], v[48:51]
	v_mfma_f32_16x16x32_bf16 v[44:47], v[128:131], v[204:207], v[44:47]
	v_mfma_f32_16x16x32_bf16 v[40:43], v[136:139], v[204:207], v[40:43]
	v_mfma_f32_16x16x32_bf16 v[36:39], v[128:131], v[220:223], v[36:39]
	v_mfma_f32_16x16x32_bf16 v[32:35], v[136:139], v[220:223], v[32:35]
	v_mfma_f32_16x16x32_bf16 v[60:63], v[132:135], v[166:169], v[60:63]
	v_mfma_f32_16x16x32_bf16 v[56:59], v[140:143], v[166:169], v[56:59]
	v_mfma_f32_16x16x32_bf16 v[52:55], v[132:135], v[200:203], v[52:55]
	v_mfma_f32_16x16x32_bf16 v[48:51], v[140:143], v[200:203], v[48:51]
	v_mfma_f32_16x16x32_bf16 v[44:47], v[132:135], v[216:219], v[44:47]
	v_mfma_f32_16x16x32_bf16 v[40:43], v[140:143], v[216:219], v[40:43]
	v_mfma_f32_16x16x32_bf16 v[36:39], v[132:135], v[228:231], v[36:39]
	v_mfma_f32_16x16x32_bf16 v[32:35], v[140:143], v[228:231], v[32:35]
	v_mfma_f32_16x16x32_bf16 v[28:31], v[232:235], v[162:165], v[28:31]
	v_mfma_f32_16x16x32_bf16 v[24:27], v[240:243], v[162:165], v[24:27]
	v_mfma_f32_16x16x32_bf16 v[20:23], v[232:235], v[196:199], v[20:23]
	v_mfma_f32_16x16x32_bf16 v[16:19], v[240:243], v[196:199], v[16:19]
	v_mfma_f32_16x16x32_bf16 v[12:15], v[232:235], v[204:207], v[12:15]
	v_mfma_f32_16x16x32_bf16 v[8:11], v[240:243], v[204:207], v[8:11]
	v_mfma_f32_16x16x32_bf16 v[4:7], v[232:235], v[220:223], v[4:7]
	v_mfma_f32_16x16x32_bf16 v[0:3], v[240:243], v[220:223], v[0:3]
	v_mfma_f32_16x16x32_bf16 v[28:31], v[236:239], v[166:169], v[28:31]
	v_mfma_f32_16x16x32_bf16 v[24:27], v[244:247], v[166:169], v[24:27]
	v_mfma_f32_16x16x32_bf16 v[20:23], v[236:239], v[200:203], v[20:23]
	v_mfma_f32_16x16x32_bf16 v[16:19], v[244:247], v[200:203], v[16:19]
	v_mfma_f32_16x16x32_bf16 v[12:15], v[236:239], v[216:219], v[12:15]
	v_mfma_f32_16x16x32_bf16 v[8:11], v[244:247], v[216:219], v[8:11]
	v_mfma_f32_16x16x32_bf16 v[4:7], v[236:239], v[228:231], v[4:7]
	v_mfma_f32_16x16x32_bf16 v[0:3], v[244:247], v[228:231], v[0:3]
	s_barrier
	s_add_i32 s27, 0, 0x18000
	ds_read_b128 v[128:131], v192 offset:32768
	ds_read_b128 v[132:135], v192 offset:33792
	ds_read_b128 v[136:139], v192 offset:34816
	ds_read_b128 v[140:143], v192 offset:35840
	s_add_u32 s52, s52, 0x40000
	s_addc_u32 s53, s53, 0
	s_mov_b32 m0, s81
	ds_read_b128 v[162:165], v194 offset:32768
	ds_read_b128 v[166:169], v194 offset:33792
	ds_read_b128 v[196:199], v194 offset:34816
	ds_read_b128 v[200:203], v194 offset:35840
	ds_read_b128 v[204:207], v194 offset:36864
	ds_read_b128 v[216:219], v194 offset:37888
	ds_read_b128 v[220:223], v194 offset:38912
	ds_read_b128 v[228:231], v194 offset:39936
	s_waitcnt lgkmcnt(8)
	ds_read_b128 v[232:235], v192 offset:49152
	ds_read_b128 v[236:239], v192 offset:50176
	ds_read_b128 v[240:243], v192 offset:51200
	ds_read_b128 v[244:247], v192 offset:52224
	global_load_lds_dwordx4 v146, s[52:53]
	s_mov_b32 m0, s82
	s_nop 0
	global_load_lds_dwordx4 v150, s[52:53]
	s_waitcnt lgkmcnt(0)
	s_waitcnt vmcnt(8)
	s_barrier
	v_mfma_f32_16x16x32_bf16 v[124:127], v[128:131], v[162:165], v[124:127]
	v_mfma_f32_16x16x32_bf16 v[120:123], v[136:139], v[162:165], v[120:123]
	v_mfma_f32_16x16x32_bf16 v[116:119], v[128:131], v[196:199], v[116:119]
	v_mfma_f32_16x16x32_bf16 v[112:115], v[136:139], v[196:199], v[112:115]
	v_mfma_f32_16x16x32_bf16 v[108:111], v[128:131], v[204:207], v[108:111]
	v_mfma_f32_16x16x32_bf16 v[104:107], v[136:139], v[204:207], v[104:107]
	v_mfma_f32_16x16x32_bf16 v[100:103], v[128:131], v[220:223], v[100:103]
	v_mfma_f32_16x16x32_bf16 v[96:99], v[136:139], v[220:223], v[96:99]
	v_mfma_f32_16x16x32_bf16 v[124:127], v[132:135], v[166:169], v[124:127]
	v_mfma_f32_16x16x32_bf16 v[120:123], v[140:143], v[166:169], v[120:123]
	v_mfma_f32_16x16x32_bf16 v[116:119], v[132:135], v[200:203], v[116:119]
	v_mfma_f32_16x16x32_bf16 v[112:115], v[140:143], v[200:203], v[112:115]
	v_mfma_f32_16x16x32_bf16 v[108:111], v[132:135], v[216:219], v[108:111]
	v_mfma_f32_16x16x32_bf16 v[104:107], v[140:143], v[216:219], v[104:107]
	v_mfma_f32_16x16x32_bf16 v[100:103], v[132:135], v[228:231], v[100:103]
	v_mfma_f32_16x16x32_bf16 v[96:99], v[140:143], v[228:231], v[96:99]
	v_mfma_f32_16x16x32_bf16 v[92:95], v[232:235], v[162:165], v[92:95]
	v_mfma_f32_16x16x32_bf16 v[88:91], v[240:243], v[162:165], v[88:91]
	v_mfma_f32_16x16x32_bf16 v[84:87], v[232:235], v[196:199], v[84:87]
	v_mfma_f32_16x16x32_bf16 v[80:83], v[240:243], v[196:199], v[80:83]
	v_mfma_f32_16x16x32_bf16 v[76:79], v[232:235], v[204:207], v[76:79]
	v_mfma_f32_16x16x32_bf16 v[72:75], v[240:243], v[204:207], v[72:75]
	v_mfma_f32_16x16x32_bf16 v[68:71], v[232:235], v[220:223], v[68:71]
	v_mfma_f32_16x16x32_bf16 v[64:67], v[240:243], v[220:223], v[64:67]
	v_mfma_f32_16x16x32_bf16 v[92:95], v[236:239], v[166:169], v[92:95]
	v_mfma_f32_16x16x32_bf16 v[88:91], v[244:247], v[166:169], v[88:91]
	v_mfma_f32_16x16x32_bf16 v[84:87], v[236:239], v[200:203], v[84:87]
	v_mfma_f32_16x16x32_bf16 v[80:83], v[244:247], v[200:203], v[80:83]
	v_mfma_f32_16x16x32_bf16 v[76:79], v[236:239], v[216:219], v[76:79]
	v_mfma_f32_16x16x32_bf16 v[72:75], v[244:247], v[216:219], v[72:75]
	v_mfma_f32_16x16x32_bf16 v[68:71], v[236:239], v[228:231], v[68:71]
	v_mfma_f32_16x16x32_bf16 v[64:67], v[244:247], v[228:231], v[64:67]
	s_barrier
	s_add_i32 s37, 0, 0x1c000
	s_add_i32 s27, s27, s76
	s_add_u32 s56, s50, s18
	s_addc_u32 s57, s51, s19
	s_mov_b32 m0, s27
	s_nop 0
	global_load_lds_dwordx4 v148, s[56:57]
	s_add_u32 s56, s50, s18
	s_addc_u32 s57, s51, s19
	s_add_i32 m0, s27, 0x2000
	s_nop 0
	global_load_lds_dwordx4 v152, s[56:57]
	s_mov_b32 m0, s80
	v_lshl_add_u64 v[176:177], v[224:225], 0, s[18:19]
	ds_read_b128 v[162:165], v194 offset:49152
	ds_read_b128 v[166:169], v194 offset:50176
	ds_read_b128 v[196:199], v194 offset:51200
	ds_read_b128 v[200:203], v194 offset:52224
	ds_read_b128 v[204:207], v194 offset:53248
	ds_read_b128 v[216:219], v194 offset:54272
	ds_read_b128 v[220:223], v194 offset:55296
	ds_read_b128 v[228:231], v194 offset:56320
	global_load_lds_dwordx4 v[176:177], off
	v_lshl_add_u64 v[176:177], v[248:249], 0, s[18:19]
	s_mov_b32 m0, s83
	s_nop 0
	global_load_lds_dwordx4 v[176:177], off
	s_add_u32 s50, s50, 0x40080
	s_addc_u32 s51, s51, 0
	s_add_i32 s27, s37, s76
	s_mov_b32 m0, s27
	s_nop 0
	global_load_lds_dwordx4 v148, s[50:51]
	s_add_i32 m0, s27, 0x2000
	s_nop 0
	global_load_lds_dwordx4 v152, s[50:51]
	s_waitcnt lgkmcnt(0)
	s_waitcnt vmcnt(8)
	s_barrier
	v_mfma_f32_16x16x32_bf16 v[60:63], v[128:131], v[162:165], v[60:63]
	v_mfma_f32_16x16x32_bf16 v[56:59], v[136:139], v[162:165], v[56:59]
	v_mfma_f32_16x16x32_bf16 v[52:55], v[128:131], v[196:199], v[52:55]
	v_mfma_f32_16x16x32_bf16 v[48:51], v[136:139], v[196:199], v[48:51]
	v_mfma_f32_16x16x32_bf16 v[44:47], v[128:131], v[204:207], v[44:47]
	v_mfma_f32_16x16x32_bf16 v[40:43], v[136:139], v[204:207], v[40:43]
	v_mfma_f32_16x16x32_bf16 v[36:39], v[128:131], v[220:223], v[36:39]
	v_mfma_f32_16x16x32_bf16 v[32:35], v[136:139], v[220:223], v[32:35]
	v_mfma_f32_16x16x32_bf16 v[60:63], v[132:135], v[166:169], v[60:63]
	v_mfma_f32_16x16x32_bf16 v[56:59], v[140:143], v[166:169], v[56:59]
	v_mfma_f32_16x16x32_bf16 v[52:55], v[132:135], v[200:203], v[52:55]
	v_mfma_f32_16x16x32_bf16 v[48:51], v[140:143], v[200:203], v[48:51]
	v_mfma_f32_16x16x32_bf16 v[44:47], v[132:135], v[216:219], v[44:47]
	v_mfma_f32_16x16x32_bf16 v[40:43], v[140:143], v[216:219], v[40:43]
	v_mfma_f32_16x16x32_bf16 v[36:39], v[132:135], v[228:231], v[36:39]
	v_mfma_f32_16x16x32_bf16 v[32:35], v[140:143], v[228:231], v[32:35]
	v_mfma_f32_16x16x32_bf16 v[28:31], v[232:235], v[162:165], v[28:31]
	v_mfma_f32_16x16x32_bf16 v[24:27], v[240:243], v[162:165], v[24:27]
	v_mfma_f32_16x16x32_bf16 v[20:23], v[232:235], v[196:199], v[20:23]
	v_mfma_f32_16x16x32_bf16 v[16:19], v[240:243], v[196:199], v[16:19]
	v_mfma_f32_16x16x32_bf16 v[12:15], v[232:235], v[204:207], v[12:15]
	v_mfma_f32_16x16x32_bf16 v[8:11], v[240:243], v[204:207], v[8:11]
	v_mfma_f32_16x16x32_bf16 v[4:7], v[232:235], v[220:223], v[4:7]
	v_mfma_f32_16x16x32_bf16 v[0:3], v[240:243], v[220:223], v[0:3]
	v_mfma_f32_16x16x32_bf16 v[28:31], v[236:239], v[166:169], v[28:31]
	v_mfma_f32_16x16x32_bf16 v[24:27], v[244:247], v[166:169], v[24:27]
	v_mfma_f32_16x16x32_bf16 v[20:23], v[236:239], v[200:203], v[20:23]
	v_mfma_f32_16x16x32_bf16 v[16:19], v[244:247], v[200:203], v[16:19]
	v_mfma_f32_16x16x32_bf16 v[12:15], v[236:239], v[216:219], v[12:15]
	v_mfma_f32_16x16x32_bf16 v[8:11], v[244:247], v[216:219], v[8:11]
	v_mfma_f32_16x16x32_bf16 v[4:7], v[236:239], v[228:231], v[4:7]
	v_mfma_f32_16x16x32_bf16 v[0:3], v[244:247], v[228:231], v[0:3]
	s_barrier
	s_add_i32 s36, s36, 2
	s_add_u32 s0, s0, 0x100
	s_addc_u32 s1, s1, 0
	s_add_u32 s34, s34, 0x100
	s_addc_u32 s35, s35, 0
	s_cmp_gt_u32 s36, 13
	s_cbranch_scc0 .LBB0_351
	s_lshl_b32 s0, s11, 8
	s_or_b32 s50, s0, s79
	s_ashr_i32 s51, s50, 31
	v_lshl_add_u64 v[140:141], s[50:51], 3, v[154:155]
	global_load_dwordx4 v[128:131], v[140:141], off offset:48
	global_load_dwordx4 v[132:135], v[140:141], off offset:32
	global_load_dwordx4 v[136:139], v[140:141], off offset:16
	global_load_dwordx4 v[162:165], v[140:141], off
	s_mov_b32 s34, 0x35800000
	s_mov_b32 s0, 0x358637bd
	v_mov_b64_e32 v[168:169], s[0:1]
	s_mov_b32 s30, 0x45800000
	s_cmp_lt_u32 s10, 2
	s_waitcnt vmcnt(0)
	v_ffbh_u32_e32 v142, v165
	v_min_u32_e32 v161, 32, v142
	v_lshlrev_b64 v[142:143], v161, v[164:165]
	v_min_u32_e32 v142, 1, v142
	v_or_b32_e32 v142, v143, v142
	v_cvt_f32_u32_e32 v142, v142
	v_sub_u32_e32 v143, 32, v161
	v_ldexp_f32 v143, v142, v143
	v_ffbh_u32_e32 v142, v163
	v_min_u32_e32 v142, 32, v142
	v_lshlrev_b64 v[162:163], v142, v[162:163]
	v_min_u32_e32 v161, 1, v162
	v_or_b32_e32 v161, v163, v161
	v_cvt_f32_u32_e32 v161, v161
	v_sub_u32_e32 v142, 32, v142
	v_ldexp_f32 v142, v161, v142
	v_pk_mul_f32 v[142:143], v[142:143], s[34:35] op_sel_hi:[1,0]
	s_nop 0
	v_pk_fma_f32 v[142:143], v[142:143], s[2:3], v[168:169] op_sel_hi:[1,0,0]
	s_nop 0
	v_mul_f32_e32 v161, 0x4b800000, v142
	v_cmp_gt_f32_e64 s[0:1], s89, v142
	v_cmp_gt_f32_e32 vcc, s89, v143
	s_nop 0
	v_cndmask_b32_e64 v142, v142, v161, s[0:1]
	v_mul_f32_e32 v161, 0x4b800000, v143
	v_cndmask_b32_e32 v143, v143, v161, vcc
	v_rsq_f32_e32 v142, v142
	v_rsq_f32_e32 v143, v143
	s_nop 0
	v_pk_mul_f32 v[162:163], v[142:143], s[30:31] op_sel_hi:[1,0]
	s_nop 0
	v_cndmask_b32_e64 v166, v142, v162, s[0:1]
	v_ffbh_u32_e32 v142, v139
	v_min_u32_e32 v142, 32, v142
	v_lshlrev_b64 v[138:139], v142, v[138:139]
	v_min_u32_e32 v138, 1, v138
	v_or_b32_e32 v138, v139, v138
	v_cvt_f32_u32_e32 v138, v138
	v_sub_u32_e32 v139, 32, v142
	v_cndmask_b32_e32 v167, v143, v163, vcc
	v_pk_mul_f32 v[60:61], v[60:61], v[166:167]
	v_ldexp_f32 v139, v138, v139
	v_ffbh_u32_e32 v138, v137
	v_min_u32_e32 v138, 32, v138
	v_lshlrev_b64 v[136:137], v138, v[136:137]
	v_min_u32_e32 v136, 1, v136
	v_or_b32_e32 v136, v137, v136
	v_cvt_f32_u32_e32 v136, v136
	v_sub_u32_e32 v137, 32, v138
	v_pk_mul_f32 v[52:53], v[52:53], v[166:167]
	v_pk_mul_f32 v[44:45], v[44:45], v[166:167]
	v_ldexp_f32 v138, v136, v137
	v_pk_mul_f32 v[136:137], v[138:139], s[34:35] op_sel_hi:[1,0]
	v_pk_mul_f32 v[36:37], v[36:37], v[166:167]
	v_pk_fma_f32 v[136:137], v[136:137], s[2:3], v[168:169] op_sel_hi:[1,0,0]
	s_nop 0
	v_mul_f32_e32 v138, 0x4b800000, v136
	v_cmp_gt_f32_e64 s[0:1], s89, v136
	v_cmp_gt_f32_e32 vcc, s89, v137
	s_nop 0
	v_cndmask_b32_e64 v136, v136, v138, s[0:1]
	v_mul_f32_e32 v138, 0x4b800000, v137
	v_cndmask_b32_e32 v137, v137, v138, vcc
	v_rsq_f32_e32 v136, v136
	v_rsq_f32_e32 v137, v137
	s_nop 0
	v_pk_mul_f32 v[138:139], v[136:137], s[30:31] op_sel_hi:[1,0]
	s_nop 0
	v_cndmask_b32_e64 v162, v136, v138, s[0:1]
	v_ffbh_u32_e32 v136, v135
	v_min_u32_e32 v136, 32, v136
	v_lshlrev_b64 v[134:135], v136, v[134:135]
	v_min_u32_e32 v134, 1, v134
	v_or_b32_e32 v134, v135, v134
	v_cvt_f32_u32_e32 v134, v134
	v_sub_u32_e32 v135, 32, v136
	v_cndmask_b32_e32 v163, v137, v139, vcc
	v_ldexp_f32 v135, v134, v135
	v_ffbh_u32_e32 v134, v133
	v_min_u32_e32 v134, 32, v134
	v_lshlrev_b64 v[132:133], v134, v[132:133]
	v_min_u32_e32 v132, 1, v132
	v_or_b32_e32 v132, v133, v132
	v_cvt_f32_u32_e32 v132, v132
	v_sub_u32_e32 v133, 32, v134
	v_ldexp_f32 v134, v132, v133
	v_pk_mul_f32 v[132:133], v[134:135], s[34:35] op_sel_hi:[1,0]
	s_nop 0
	v_pk_fma_f32 v[132:133], v[132:133], s[2:3], v[168:169] op_sel_hi:[1,0,0]
	s_nop 0
	v_mul_f32_e32 v134, 0x4b800000, v132
	v_cmp_gt_f32_e64 s[0:1], s89, v132
	v_cmp_gt_f32_e32 vcc, s89, v133
	s_nop 0
	v_cndmask_b32_e64 v132, v132, v134, s[0:1]
	v_mul_f32_e32 v134, 0x4b800000, v133
	v_cndmask_b32_e32 v133, v133, v134, vcc
	v_rsq_f32_e32 v132, v132
	v_rsq_f32_e32 v133, v133
	s_nop 0
	v_pk_mul_f32 v[134:135], v[132:133], s[30:31] op_sel_hi:[1,0]
	s_nop 0
	v_cndmask_b32_e64 v188, v132, v134, s[0:1]
	v_ffbh_u32_e32 v132, v131
	v_min_u32_e32 v132, 32, v132
	v_lshlrev_b64 v[130:131], v132, v[130:131]
	v_min_u32_e32 v130, 1, v130
	v_or_b32_e32 v130, v131, v130
	v_cvt_f32_u32_e32 v130, v130
	v_sub_u32_e32 v131, 32, v132
	v_cndmask_b32_e32 v189, v133, v135, vcc
	v_pk_mul_f32 v[56:57], v[56:57], v[188:189]
	v_ldexp_f32 v131, v130, v131
	v_ffbh_u32_e32 v130, v129
	v_min_u32_e32 v130, 32, v130
	v_lshlrev_b64 v[128:129], v130, v[128:129]
	v_min_u32_e32 v128, 1, v128
	v_or_b32_e32 v128, v129, v128
	v_cvt_f32_u32_e32 v128, v128
	v_sub_u32_e32 v129, 32, v130
	v_pk_mul_f32 v[48:49], v[48:49], v[188:189]
	v_pk_mul_f32 v[40:41], v[40:41], v[188:189]
	v_ldexp_f32 v130, v128, v129
	v_pk_mul_f32 v[128:129], v[130:131], s[34:35] op_sel_hi:[1,0]
	v_pk_mul_f32 v[32:33], v[32:33], v[188:189]
	v_pk_fma_f32 v[128:129], v[128:129], s[2:3], v[168:169] op_sel_hi:[1,0,0]
	s_nop 0
	v_mul_f32_e32 v130, 0x4b800000, v128
	v_cmp_gt_f32_e64 s[0:1], s89, v128
	v_cmp_gt_f32_e32 vcc, s89, v129
	s_nop 0
	v_cndmask_b32_e64 v128, v128, v130, s[0:1]
	v_mul_f32_e32 v130, 0x4b800000, v129
	v_cndmask_b32_e32 v129, v129, v130, vcc
	v_rsq_f32_e32 v128, v128
	v_rsq_f32_e32 v129, v129
	s_nop 0
	v_pk_mul_f32 v[130:131], v[128:129], s[30:31] op_sel_hi:[1,0]
	s_nop 0
	v_cndmask_b32_e32 v165, v129, v131, vcc
	v_cndmask_b32_e64 v164, v128, v130, s[0:1]
	global_load_dwordx4 v[128:131], v[140:141], off offset:1072
	global_load_dwordx4 v[132:135], v[140:141], off offset:1056
	global_load_dwordx4 v[136:139], v[140:141], off offset:1040
	s_nop 0
	global_load_dwordx4 v[140:143], v[140:141], off offset:1024
	s_waitcnt vmcnt(0)
	v_ffbh_u32_e32 v161, v143
	v_min_u32_e32 v161, 32, v161
	v_lshlrev_b64 v[142:143], v161, v[142:143]
	v_min_u32_e32 v142, 1, v142
	v_or_b32_e32 v142, v143, v142
	v_cvt_f32_u32_e32 v142, v142
	v_sub_u32_e32 v143, 32, v161
	v_ldexp_f32 v143, v142, v143
	v_ffbh_u32_e32 v142, v141
	v_min_u32_e32 v142, 32, v142
	v_lshlrev_b64 v[140:141], v142, v[140:141]
	v_min_u32_e32 v140, 1, v140
	v_or_b32_e32 v140, v141, v140
	v_cvt_f32_u32_e32 v140, v140
	v_sub_u32_e32 v141, 32, v142
	v_ldexp_f32 v142, v140, v141
	v_pk_mul_f32 v[140:141], v[142:143], s[34:35] op_sel_hi:[1,0]
	s_nop 0
	v_pk_fma_f32 v[140:141], v[140:141], s[2:3], v[168:169] op_sel_hi:[1,0,0]
	s_nop 0
	v_mul_f32_e32 v142, 0x4b800000, v140
	v_cmp_gt_f32_e64 s[0:1], s89, v140
	v_cmp_gt_f32_e32 vcc, s89, v141
	s_nop 0
	v_cndmask_b32_e64 v140, v140, v142, s[0:1]
	v_mul_f32_e32 v142, 0x4b800000, v141
	v_cndmask_b32_e32 v141, v141, v142, vcc
	v_rsq_f32_e32 v140, v140
	v_rsq_f32_e32 v141, v141
	s_nop 0
	v_pk_mul_f32 v[142:143], v[140:141], s[30:31] op_sel_hi:[1,0]
	s_nop 0
	v_cndmask_b32_e64 v142, v140, v142, s[0:1]
	v_ffbh_u32_e32 v140, v139
	v_min_u32_e32 v140, 32, v140
	v_lshlrev_b64 v[138:139], v140, v[138:139]
	v_min_u32_e32 v138, 1, v138
	v_or_b32_e32 v138, v139, v138
	v_cvt_f32_u32_e32 v138, v138
	v_sub_u32_e32 v139, 32, v140
	v_cndmask_b32_e32 v143, v141, v143, vcc
	v_pk_mul_f32 v[140:141], v[124:125], v[166:167]
	v_ldexp_f32 v139, v138, v139
	v_ffbh_u32_e32 v138, v137
	v_min_u32_e32 v138, 32, v138
	v_lshlrev_b64 v[136:137], v138, v[136:137]
	v_min_u32_e32 v136, 1, v136
	v_or_b32_e32 v136, v137, v136
	v_cvt_f32_u32_e32 v136, v136
	v_sub_u32_e32 v137, 32, v138
	v_pk_mul_f32 v[28:29], v[28:29], v[142:143]
	v_pk_mul_f32 v[20:21], v[20:21], v[142:143]
	v_ldexp_f32 v138, v136, v137
	v_pk_mul_f32 v[136:137], v[138:139], s[34:35] op_sel_hi:[1,0]
	v_pk_mul_f32 v[12:13], v[12:13], v[142:143]
	v_pk_fma_f32 v[136:137], v[136:137], s[2:3], v[168:169] op_sel_hi:[1,0,0]
	v_pk_mul_f32 v[4:5], v[4:5], v[142:143]
	v_mul_f32_e32 v138, 0x4b800000, v136
	v_cmp_gt_f32_e64 s[0:1], s89, v136
	v_cmp_gt_f32_e32 vcc, s89, v137
	s_nop 0
	v_cndmask_b32_e64 v136, v136, v138, s[0:1]
	v_mul_f32_e32 v138, 0x4b800000, v137
	v_cndmask_b32_e32 v137, v137, v138, vcc
	v_rsq_f32_e32 v136, v136
	v_rsq_f32_e32 v137, v137
	s_nop 0
	v_pk_mul_f32 v[138:139], v[136:137], s[30:31] op_sel_hi:[1,0]
	s_nop 0
	v_cndmask_b32_e64 v136, v136, v138, s[0:1]
	v_ffbh_u32_e32 v138, v135
	v_min_u32_e32 v138, 32, v138
	v_lshlrev_b64 v[134:135], v138, v[134:135]
	v_min_u32_e32 v134, 1, v134
	v_or_b32_e32 v134, v135, v134
	v_cvt_f32_u32_e32 v134, v134
	v_sub_u32_e32 v135, 32, v138
	v_cndmask_b32_e32 v137, v137, v139, vcc
	v_pk_mul_f32 v[138:139], v[120:121], v[188:189]
	v_ldexp_f32 v135, v134, v135
	v_ffbh_u32_e32 v134, v133
	v_min_u32_e32 v134, 32, v134
	v_lshlrev_b64 v[132:133], v134, v[132:133]
	v_min_u32_e32 v132, 1, v132
	v_or_b32_e32 v132, v133, v132
	v_cvt_f32_u32_e32 v132, v132
	v_sub_u32_e32 v133, 32, v134
	v_pk_mul_f32 v[120:121], v[84:85], v[142:143]
	v_ldexp_f32 v134, v132, v133
	v_pk_mul_f32 v[132:133], v[134:135], s[34:35] op_sel_hi:[1,0]
	s_nop 0
	v_pk_fma_f32 v[132:133], v[132:133], s[2:3], v[168:169] op_sel_hi:[1,0,0]
	s_nop 0
	v_mul_f32_e32 v134, 0x4b800000, v132
	v_cmp_gt_f32_e64 s[0:1], s89, v132
	v_cmp_gt_f32_e32 vcc, s89, v133
	s_nop 0
	v_cndmask_b32_e64 v132, v132, v134, s[0:1]
	v_mul_f32_e32 v134, 0x4b800000, v133
	v_cndmask_b32_e32 v133, v133, v134, vcc
	v_rsq_f32_e32 v132, v132
	v_rsq_f32_e32 v133, v133
	s_nop 0
	v_pk_mul_f32 v[134:135], v[132:133], s[30:31] op_sel_hi:[1,0]
	s_nop 0
	v_cndmask_b32_e64 v176, v132, v134, s[0:1]
	v_ffbh_u32_e32 v132, v131
	v_min_u32_e32 v132, 32, v132
	v_lshlrev_b64 v[130:131], v132, v[130:131]
	v_min_u32_e32 v130, 1, v130
	v_or_b32_e32 v130, v131, v130
	v_cvt_f32_u32_e32 v130, v130
	v_sub_u32_e32 v131, 32, v132
	v_cndmask_b32_e32 v177, v133, v135, vcc
	v_pk_mul_f32 v[124:125], v[88:89], v[176:177]
	v_ldexp_f32 v131, v130, v131
	v_ffbh_u32_e32 v130, v129
	v_min_u32_e32 v130, 32, v130
	v_lshlrev_b64 v[128:129], v130, v[128:129]
	v_min_u32_e32 v128, 1, v128
	v_or_b32_e32 v128, v129, v128
	v_cvt_f32_u32_e32 v128, v128
	v_sub_u32_e32 v129, 32, v130
	v_pk_mul_f32 v[134:135], v[116:117], v[166:167]
	v_pk_mul_f32 v[132:133], v[112:113], v[188:189]
	v_ldexp_f32 v130, v128, v129
	v_pk_mul_f32 v[128:129], v[130:131], s[34:35] op_sel_hi:[1,0]
	v_pk_mul_f32 v[116:117], v[80:81], v[176:177]
	v_pk_fma_f32 v[128:129], v[128:129], s[2:3], v[168:169] op_sel_hi:[1,0,0]
	v_pk_mul_f32 v[88:89], v[104:105], v[188:189]
	v_mul_f32_e32 v130, 0x4b800000, v128
	v_cmp_gt_f32_e64 s[0:1], s89, v128
	v_cmp_gt_f32_e32 vcc, s89, v129
	v_pk_mul_f32 v[112:113], v[76:77], v[142:143]
	v_cndmask_b32_e64 v128, v128, v130, s[0:1]
	v_mul_f32_e32 v130, 0x4b800000, v129
	v_cndmask_b32_e32 v129, v129, v130, vcc
	v_rsq_f32_e32 v128, v128
	v_rsq_f32_e32 v129, v129
	v_pk_mul_f32 v[76:77], v[100:101], v[166:167]
	v_pk_mul_f32 v[104:105], v[68:69], v[142:143]
	v_pk_mul_f32 v[24:25], v[24:25], v[176:177]
	v_pk_mul_f32 v[130:131], v[128:129], s[30:31] op_sel_hi:[1,0]
	v_pk_mul_f32 v[16:17], v[16:17], v[176:177]
	v_cndmask_b32_e32 v129, v129, v131, vcc
	v_cndmask_b32_e64 v128, v128, v130, s[0:1]
	s_mov_b64 s[0:1], -1
	v_pk_mul_f32 v[130:131], v[92:93], v[142:143]
	v_pk_mul_f32 v[92:93], v[108:109], v[166:167]
	v_pk_mul_f32 v[108:109], v[72:73], v[176:177]
	v_pk_mul_f32 v[72:73], v[96:97], v[188:189]
	v_pk_mul_f32 v[96:97], v[64:65], v[176:177]
	v_pk_mul_f32 v[8:9], v[8:9], v[176:177]
	v_pk_mul_f32 v[0:1], v[0:1], v[176:177]
	s_cbranch_scc1 .LBB0_354
	v_lshl_add_u32 v68, s10, 8, v193
	v_ashrrev_i32_e32 v69, 31, v68
	v_pk_mul_f32 v[64:65], v[126:127], v[162:163]
	v_cvt_pk_bf16_f32 v80, v140, v141
	s_lshl_b64 s[0:1], s[50:51], 1
	v_cvt_pk_bf16_f32 v81, v64, v65
	v_lshlrev_b64 v[64:65], 13, v[68:69]
	v_lshl_add_u64 v[64:65], s[44:45], 0, v[64:65]
	v_lshl_add_u64 v[64:65], v[64:65], 0, s[0:1]
	v_lshl_add_u64 v[64:65], v[64:65], 0, v[144:145]
	v_mov_b32_e32 v161, v145
	v_lshl_add_u64 v[64:65], v[64:65], 0, v[160:161]
	global_store_dwordx2 v[64:65], v[80:81], off
	v_pk_mul_f32 v[80:81], v[122:123], v[164:165]
	v_cvt_pk_bf16_f32 v84, v138, v139
	s_nop 0
	v_cvt_pk_bf16_f32 v85, v80, v81
	v_pk_mul_f32 v[80:81], v[94:95], v[136:137]
	global_store_dwordx2 v[64:65], v[84:85], off offset:16
	v_cvt_pk_bf16_f32 v84, v130, v131
	v_cvt_pk_bf16_f32 v85, v80, v81
	v_pk_mul_f32 v[80:81], v[90:91], v[128:129]
	global_store_dwordx2 v[64:65], v[84:85], off offset:256
	v_cvt_pk_bf16_f32 v84, v124, v125
	v_cvt_pk_bf16_f32 v85, v80, v81
	v_or_b32_e32 v80, 16, v68
	v_ashrrev_i32_e32 v81, 31, v80
	v_lshlrev_b64 v[80:81], 13, v[80:81]
	v_lshl_add_u64 v[80:81], s[44:45], 0, v[80:81]
	v_lshl_add_u64 v[80:81], v[80:81], 0, s[0:1]
	v_lshl_add_u64 v[80:81], v[80:81], 0, v[144:145]
	global_store_dwordx2 v[64:65], v[84:85], off offset:272
	v_pk_mul_f32 v[84:85], v[118:119], v[162:163]
	v_cvt_pk_bf16_f32 v100, v134, v135
	v_lshl_add_u64 v[80:81], v[80:81], 0, v[160:161]
	v_cvt_pk_bf16_f32 v101, v84, v85
	global_store_dwordx2 v[80:81], v[100:101], off
	v_pk_mul_f32 v[84:85], v[114:115], v[164:165]
	v_cvt_pk_bf16_f32 v100, v132, v133
	s_nop 0
	v_cvt_pk_bf16_f32 v101, v84, v85
	global_store_dwordx2 v[80:81], v[100:101], off offset:16
	v_pk_mul_f32 v[84:85], v[86:87], v[136:137]
	v_cvt_pk_bf16_f32 v100, v120, v121
	s_nop 0
	v_cvt_pk_bf16_f32 v101, v84, v85
	global_store_dwordx2 v[80:81], v[100:101], off offset:256
	v_pk_mul_f32 v[84:85], v[82:83], v[128:129]
	v_cvt_pk_bf16_f32 v100, v116, v117
	s_nop 0
	v_cvt_pk_bf16_f32 v101, v84, v85
	global_store_dwordx2 v[80:81], v[100:101], off offset:272
	v_or_b32_e32 v80, 32, v68
	v_ashrrev_i32_e32 v81, 31, v80
	v_lshlrev_b64 v[80:81], 13, v[80:81]
	v_lshl_add_u64 v[80:81], s[44:45], 0, v[80:81]
	v_or_b32_e32 v68, 48, v68
	v_lshl_add_u64 v[80:81], v[80:81], 0, s[0:1]
	v_ashrrev_i32_e32 v69, 31, v68
	v_pk_mul_f32 v[84:85], v[110:111], v[162:163]
	v_lshl_add_u64 v[80:81], v[80:81], 0, v[144:145]
	v_lshlrev_b64 v[68:69], 13, v[68:69]
	v_cvt_pk_bf16_f32 v100, v92, v93
	v_cvt_pk_bf16_f32 v101, v84, v85
	v_lshl_add_u64 v[80:81], v[80:81], 0, v[160:161]
	v_pk_mul_f32 v[84:85], v[106:107], v[164:165]
	v_lshl_add_u64 v[68:69], s[44:45], 0, v[68:69]
	global_store_dwordx2 v[80:81], v[100:101], off
	v_cvt_pk_bf16_f32 v100, v88, v89
	v_cvt_pk_bf16_f32 v101, v84, v85
	v_pk_mul_f32 v[84:85], v[78:79], v[136:137]
	v_lshl_add_u64 v[68:69], v[68:69], 0, s[0:1]
	global_store_dwordx2 v[80:81], v[100:101], off offset:16
	v_cvt_pk_bf16_f32 v100, v112, v113
	v_cvt_pk_bf16_f32 v101, v84, v85
	v_pk_mul_f32 v[84:85], v[74:75], v[128:129]
	v_lshl_add_u64 v[68:69], v[68:69], 0, v[144:145]
	global_store_dwordx2 v[80:81], v[100:101], off offset:256
	v_cvt_pk_bf16_f32 v100, v108, v109
	v_cvt_pk_bf16_f32 v101, v84, v85
	global_store_dwordx2 v[80:81], v[100:101], off offset:272
	v_cvt_pk_bf16_f32 v84, v76, v77
	v_lshl_add_u64 v[68:69], v[68:69], 0, v[160:161]
	v_pk_mul_f32 v[80:81], v[102:103], v[162:163]
	s_mov_b64 s[0:1], 0x100000
	v_cvt_pk_bf16_f32 v85, v80, v81
	global_store_dwordx2 v[68:69], v[84:85], off
	v_cvt_pk_bf16_f32 v84, v72, v73
	v_pk_mul_f32 v[80:81], v[98:99], v[164:165]
	s_nop 0
	v_cvt_pk_bf16_f32 v85, v80, v81
	global_store_dwordx2 v[68:69], v[84:85], off offset:16
	v_cvt_pk_bf16_f32 v84, v104, v105
	v_pk_mul_f32 v[80:81], v[70:71], v[136:137]
	s_nop 0
	v_cvt_pk_bf16_f32 v85, v80, v81
	global_store_dwordx2 v[68:69], v[84:85], off offset:256
	v_cvt_pk_bf16_f32 v84, v96, v97
	v_pk_mul_f32 v[80:81], v[66:67], v[128:129]
	s_nop 0
	v_cvt_pk_bf16_f32 v85, v80, v81
	global_store_dwordx2 v[68:69], v[84:85], off offset:272
	v_add_co_u32_e32 v84, vcc, s29, v64
	v_pk_mul_f32 v[68:69], v[62:63], v[162:163]
	s_nop 0
	v_addc_co_u32_e32 v85, vcc, 0, v65, vcc
	v_cvt_pk_bf16_f32 v80, v60, v61
	v_cvt_pk_bf16_f32 v81, v68, v69
	v_lshl_add_u64 v[68:69], v[64:65], 0, s[0:1]
	global_store_dwordx2 v[84:85], v[80:81], off
	v_cvt_pk_bf16_f32 v84, v56, v57
	v_pk_mul_f32 v[80:81], v[58:59], v[164:165]
	s_mov_b64 s[0:1], 0x120000
	v_cvt_pk_bf16_f32 v85, v80, v81
	global_store_dwordx2 v[68:69], v[84:85], off offset:16
	v_cvt_pk_bf16_f32 v84, v28, v29
	v_pk_mul_f32 v[80:81], v[30:31], v[136:137]
	s_nop 0
	v_cvt_pk_bf16_f32 v85, v80, v81
	global_store_dwordx2 v[68:69], v[84:85], off offset:256
	v_cvt_pk_bf16_f32 v84, v24, v25
	v_pk_mul_f32 v[80:81], v[26:27], v[128:129]
	s_nop 0
	v_cvt_pk_bf16_f32 v85, v80, v81
	global_store_dwordx2 v[68:69], v[84:85], off offset:272
	v_add_co_u32_e32 v84, vcc, s49, v64
	v_pk_mul_f32 v[68:69], v[54:55], v[162:163]
	v_cvt_pk_bf16_f32 v80, v52, v53
	s_nop 0
	v_addc_co_u32_e32 v85, vcc, 0, v65, vcc
	v_cvt_pk_bf16_f32 v81, v68, v69
	v_lshl_add_u64 v[68:69], v[64:65], 0, s[0:1]
	global_store_dwordx2 v[84:85], v[80:81], off
	v_pk_mul_f32 v[80:81], v[50:51], v[164:165]
	v_cvt_pk_bf16_f32 v84, v48, v49
	s_mov_b64 s[0:1], 0x140000
	v_cvt_pk_bf16_f32 v85, v80, v81
	global_store_dwordx2 v[68:69], v[84:85], off offset:16
	v_pk_mul_f32 v[80:81], v[22:23], v[136:137]
	v_cvt_pk_bf16_f32 v84, v20, v21
	s_nop 0
	v_cvt_pk_bf16_f32 v85, v80, v81
	global_store_dwordx2 v[68:69], v[84:85], off offset:256
	v_pk_mul_f32 v[80:81], v[18:19], v[128:129]
	v_cvt_pk_bf16_f32 v84, v16, v17
	s_nop 0
	v_cvt_pk_bf16_f32 v85, v80, v81
	global_store_dwordx2 v[68:69], v[84:85], off offset:272
	v_pk_mul_f32 v[68:69], v[46:47], v[162:163]
	v_cvt_pk_bf16_f32 v80, v44, v45
	s_nop 0
	v_cvt_pk_bf16_f32 v81, v68, v69
	v_lshl_add_u64 v[68:69], v[64:65], 0, s[0:1]
	s_mov_b32 s0, 0x140000
	v_add_co_u32_e32 v84, vcc, s0, v64
	s_mov_b64 s[0:1], 0x160000
	s_nop 0
	v_addc_co_u32_e32 v85, vcc, 0, v65, vcc
	global_store_dwordx2 v[84:85], v[80:81], off
	v_pk_mul_f32 v[80:81], v[42:43], v[164:165]
	v_cvt_pk_bf16_f32 v84, v40, v41
	s_nop 0
	v_cvt_pk_bf16_f32 v85, v80, v81
	global_store_dwordx2 v[68:69], v[84:85], off offset:16
	v_pk_mul_f32 v[80:81], v[14:15], v[136:137]
	v_cvt_pk_bf16_f32 v84, v12, v13
	s_nop 0
	v_cvt_pk_bf16_f32 v85, v80, v81
	global_store_dwordx2 v[68:69], v[84:85], off offset:256
	v_pk_mul_f32 v[80:81], v[10:11], v[128:129]
	v_cvt_pk_bf16_f32 v84, v8, v9
	s_nop 0
	v_cvt_pk_bf16_f32 v85, v80, v81
	global_store_dwordx2 v[68:69], v[84:85], off offset:272
	v_pk_mul_f32 v[68:69], v[38:39], v[162:163]
	v_cvt_pk_bf16_f32 v80, v36, v37
	s_nop 0
	v_cvt_pk_bf16_f32 v81, v68, v69
	v_lshl_add_u64 v[68:69], v[64:65], 0, s[0:1]
	s_mov_b32 s0, 0x160000
	v_add_co_u32_e32 v64, vcc, s0, v64
	s_mov_b64 s[0:1], 0
	s_nop 0
	v_addc_co_u32_e32 v65, vcc, 0, v65, vcc
	global_store_dwordx2 v[64:65], v[80:81], off
	v_pk_mul_f32 v[64:65], v[34:35], v[164:165]
	v_cvt_pk_bf16_f32 v80, v32, v33
	s_nop 0
	v_cvt_pk_bf16_f32 v81, v64, v65
	global_store_dwordx2 v[68:69], v[80:81], off offset:16
	v_pk_mul_f32 v[64:65], v[6:7], v[136:137]
	v_cvt_pk_bf16_f32 v80, v4, v5
	s_nop 0
	v_cvt_pk_bf16_f32 v81, v64, v65
	global_store_dwordx2 v[68:69], v[80:81], off offset:256
	v_pk_mul_f32 v[64:65], v[2:3], v[128:129]
	v_cvt_pk_bf16_f32 v80, v0, v1
	s_nop 0
	v_cvt_pk_bf16_f32 v81, v64, v65
	s_nop 1
	global_store_dwordx2 v[68:69], v[80:81], off offset:272
